# remaining provably redundant s_waitcnt lgkmcnt(0) deleted (14 sites; one per differential-attention tile-loop iteration and one per GDN scan chunk among them)
# speedup vs baseline: 1.0000x; 1.0000x over previous
; template <bool MAPW = false>
; __device__ __forceinline__ void transpose_item(const float* W, int K, int N, bf16* WT, int k0, int n0, int drow0, LAS float* scr, int lane) {
; #pragma unroll 8
;     for (int i = 0; i < 32; ++i) { const int kk = 2 * i + (lane >> 5); scr[kk * 33 + (lane & 31)] = W[(size_t)(k0 + kk) * N + n0 + (lane & 31)]; }
.LBB0_13:
	s_lshl_b32 s35, s15, 1
	s_lshl_b32 s36, s30, 1
	v_or_b32_e32 v11, s36, v2
	s_add_i32 s37, s35, 4
	s_add_i32 s38, s36, 4
	s_add_i32 s44, s36, 8
	v_add_u32_e32 v4, s12, v11
	v_or_b32_e32 v19, s37, v1
	v_or_b32_e32 v42, s38, v2
	v_mov_b32_e32 v23, v5
	v_or_b32_e32 v9, s35, v1
	s_add_i32 s46, s36, 12
	v_or_b32_e32 v44, s44, v2
	v_lshlrev_b64 v[36:37], 13, v[4:5]
	v_add_u32_e32 v22, s13, v19
	v_add_u32_e32 v4, s12, v42
	v_mov_b32_e32 v21, v5
	s_add_i32 s39, s35, 8
	s_add_i32 s45, s35, 12
	s_add_i32 s48, s36, 16
	v_add_u32_e32 v20, s13, v9
	v_or_b32_e32 v46, s46, v2
	v_lshlrev_b64 v[22:23], 13, v[22:23]
	v_lshlrev_b64 v[38:39], 13, v[4:5]
	v_add_u32_e32 v4, s12, v44
	s_add_i32 s50, s36, 20
	v_or_b32_e32 v43, s39, v1
	v_or_b32_e32 v45, s45, v1
	v_or_b32_e32 v48, s48, v2
	v_lshlrev_b64 v[20:21], 13, v[20:21]
	v_lshl_add_u64 v[36:37], v[12:13], 0, v[36:37]
	v_lshl_add_u64 v[22:23], v[12:13], 0, v[22:23]
	v_lshlrev_b64 v[40:41], 13, v[4:5]
	v_add_u32_e32 v4, s12, v46
	v_mov_b32_e32 v25, v5
	v_mov_b32_e32 v27, v5
	s_add_i32 s47, s35, 16
	s_add_i32 s49, s35, 20
	s_add_i32 s52, s36, 24
	v_or_b32_e32 v50, s50, v2
	v_add_u32_e32 v24, s13, v43
	v_add_u32_e32 v26, s13, v45
	v_lshl_add_u64 v[20:21], v[12:13], 0, v[20:21]
	v_lshl_add_u64 v[38:39], v[12:13], 0, v[38:39]
	global_load_dword v55, v[36:37], off
	global_load_dword v56, v[20:21], off
	global_load_dword v57, v[38:39], off
	global_load_dword v58, v[22:23], off
	v_lshlrev_b64 v[22:23], 13, v[4:5]
	v_add_u32_e32 v4, s12, v48
	s_add_i32 s51, s35, 24
	s_add_i32 s35, s35, 28
	s_add_i32 s36, s36, 28
	v_or_b32_e32 v47, s47, v1
	v_or_b32_e32 v49, s49, v1
	v_or_b32_e32 v52, s52, v2
	v_lshlrev_b64 v[24:25], 13, v[24:25]
	v_lshlrev_b64 v[26:27], 13, v[26:27]
	v_lshl_add_u64 v[20:21], v[12:13], 0, v[40:41]
	v_lshl_add_u64 v[22:23], v[12:13], 0, v[22:23]
	v_lshlrev_b64 v[36:37], 13, v[4:5]
	v_add_u32_e32 v4, s12, v50
	v_mov_b32_e32 v29, v5
	v_mov_b32_e32 v31, v5
	v_or_b32_e32 v51, s51, v1
	v_or_b32_e32 v53, s35, v1
	v_or_b32_e32 v54, s36, v2
	v_add_u32_e32 v28, s13, v47
	v_add_u32_e32 v30, s13, v49
	v_lshl_add_u64 v[24:25], v[12:13], 0, v[24:25]
	v_lshl_add_u64 v[26:27], v[12:13], 0, v[26:27]
	global_load_dword v59, v[20:21], off
	global_load_dword v60, v[24:25], off
	global_load_dword v61, v[22:23], off
	global_load_dword v62, v[26:27], off
	v_lshlrev_b64 v[22:23], 13, v[4:5]
	v_add_u32_e32 v4, s12, v52
	v_mov_b32_e32 v33, v5
	v_mov_b32_e32 v35, v5
	v_add_u32_e32 v32, s13, v51
	v_add_u32_e32 v34, s13, v53
	v_lshlrev_b64 v[28:29], 13, v[28:29]
	v_lshlrev_b64 v[30:31], 13, v[30:31]
	v_lshl_add_u64 v[20:21], v[12:13], 0, v[36:37]
	v_lshl_add_u64 v[22:23], v[12:13], 0, v[22:23]
	v_lshlrev_b64 v[24:25], 13, v[4:5]
	v_add_u32_e32 v4, s12, v54
	v_lshlrev_b64 v[32:33], 13, v[32:33]
	v_lshlrev_b64 v[34:35], 13, v[34:35]
	v_lshl_add_u64 v[28:29], v[12:13], 0, v[28:29]
	v_lshl_add_u64 v[30:31], v[12:13], 0, v[30:31]
	global_load_dword v63, v[20:21], off
	global_load_dword v64, v[28:29], off
	global_load_dword v65, v[22:23], off
	global_load_dword v66, v[30:31], off
	v_lshl_add_u64 v[20:21], v[12:13], 0, v[24:25]
	v_lshlrev_b64 v[22:23], 13, v[4:5]
	v_lshl_add_u64 v[32:33], v[12:13], 0, v[32:33]
	v_lshl_add_u64 v[34:35], v[12:13], 0, v[34:35]
	v_lshl_add_u64 v[22:23], v[12:13], 0, v[22:23]
	global_load_dword v4, v[20:21], off
	global_load_dword v67, v[32:33], off
	global_load_dword v68, v[22:23], off
	global_load_dword v69, v[34:35], off
	s_add_i32 s30, s30, 16
	s_add_i32 s15, s15, 16
	s_add_i32 s31, s31, -16
	v_mad_u64_u32 v[20:21], s[36:37], v11, s23, v[6:7]
	s_cmp_lg_u32 s31, 0
	v_mad_u64_u32 v[22:23], s[36:37], v9, s23, v[6:7]
	v_mad_u64_u32 v[24:25], s[36:37], v42, s23, v[6:7]
	v_mad_u64_u32 v[26:27], s[36:37], v19, s23, v[6:7]
	v_mad_u64_u32 v[28:29], s[36:37], v44, s23, v[6:7]
	v_mad_u64_u32 v[30:31], s[36:37], v43, s23, v[6:7]
	v_mad_u64_u32 v[32:33], s[36:37], v46, s23, v[6:7]
	v_mad_u64_u32 v[34:35], s[36:37], v45, s23, v[6:7]
	v_mad_u64_u32 v[36:37], s[36:37], v48, s23, v[6:7]
	v_mad_u64_u32 v[38:39], s[36:37], v47, s23, v[6:7]
	v_mad_u64_u32 v[40:41], s[36:37], v50, s23, v[6:7]
	v_mad_u64_u32 v[42:43], s[36:37], v49, s23, v[6:7]
	v_mad_u64_u32 v[44:45], s[36:37], v52, s23, v[6:7]
	v_mad_u64_u32 v[46:47], s[36:37], v51, s23, v[6:7]
	v_mad_u64_u32 v[48:49], s[36:37], v54, s23, v[6:7]
	v_mad_u64_u32 v[50:51], s[36:37], v53, s23, v[6:7]
	s_waitcnt vmcnt(15)
	ds_write_b32 v20, v55
	s_waitcnt vmcnt(14)
	ds_write_b32 v22, v56
	s_waitcnt vmcnt(13)
	ds_write_b32 v24, v57
	s_waitcnt vmcnt(12)
	ds_write_b32 v26, v58
	s_waitcnt vmcnt(11)
	ds_write_b32 v28, v59
	s_waitcnt vmcnt(10)
	ds_write_b32 v30, v60
	s_waitcnt vmcnt(9)
	ds_write_b32 v32, v61
	s_waitcnt vmcnt(8)
	ds_write_b32 v34, v62
	s_waitcnt vmcnt(7)
	ds_write_b32 v36, v63
	s_waitcnt vmcnt(6)
	ds_write_b32 v38, v64
	s_waitcnt vmcnt(5)
	ds_write_b32 v40, v65
	s_waitcnt vmcnt(4)
	ds_write_b32 v42, v66
	s_waitcnt vmcnt(3)
	ds_write_b32 v44, v4
	s_waitcnt vmcnt(2)
	ds_write_b32 v46, v67
	s_waitcnt vmcnt(1)
	ds_write_b32 v48, v68
	s_waitcnt vmcnt(0)
	ds_write_b32 v50, v69
	s_cbranch_scc1 .LBB0_13
; #define LAS __attribute__((address_space(3)))
; #define LDS_WAIT() asm volatile("s_waitcnt lgkmcnt(0)" ::: "memory")
; __device__ __forceinline__ unsigned cvtpk(float lo, float hi) { const f32x2_t v = {lo, hi}; const bf16x2_t b = __builtin_convertvector(v, bf16x2_t); return __builtin_bit_cast(unsigned, b); }
; template <bool MAPW = false>
; __device__ __forceinline__ void transpose_item(const float* W, int K, int N, bf16* WT, int k0, int n0, int drow0, LAS float* scr, int lane) {
;     ...
;     LDS_WAIT(); asm volatile("" ::: "memory");
;     const int c = lane & 7;
; #pragma unroll
;     for (int j = 0; j < 4; ++j) { const int n = (lane >> 3) + 8 * j; const LAS float* s = scr + (8 * c) * 33 + n;
;         v4u o; o.x = cvtpk(s[0 * 33], s[1 * 33]); o.y = cvtpk(s[2 * 33], s[3 * 33]); o.z = cvtpk(s[4 * 33], s[5 * 33]); o.w = cvtpk(s[6 * 33], s[7 * 33]);
;         *(v4u*)(WT + (size_t)(MAPW ? win_row(drow0 + n) : drow0 + n) * K + k0 + 8 * c) = o; }
;     LDS_WAIT(); asm volatile("" ::: "memory");
; __device__ __forceinline__ void phase_prologue(LAS unsigned char* lds, const float* w_in, const float* w_branch, const float* w_out, unsigned char* ws, int gw, int ngw, int wave, int lane) {
;     ...
;         if (r < 12 * I_BR) { const int m = r / I_BR; r -= m * I_BR; const int kb = r / 64, nb = r % 64;
;             transpose_item(w_branch + (size_t)m * 1024 * 2048, 1024, 2048, (bf16*)(ws + WS_WBR + (size_t)m * SZ_WBR_1), kb * 64, nb * 32, nb * 32, scr, lane); continue; }
	s_waitcnt lgkmcnt(0)
	s_lshl_b64 s[30:31], s[10:11], 23
	s_add_u32 s10, s17, s30
	ds_read2_b32 v[12:13], v14 offset0:33 offset1:41
	ds_read2_b32 v[24:25], v14 offset1:8
	ds_read2_b32 v[26:27], v14 offset0:66 offset1:74
	ds_read2_b32 v[28:29], v14 offset0:99 offset1:107
	ds_read2_b32 v[30:31], v14 offset0:132 offset1:140
	ds_read2_b32 v[32:33], v14 offset0:165 offset1:173
	ds_read2_b32 v[34:35], v14 offset0:198 offset1:206
	ds_read2_b32 v[36:37], v14 offset0:231 offset1:239
	s_addc_u32 s13, s18, s31
	s_lshl_b32 s12, s12, 1
	s_add_u32 s12, s10, s12
	s_addc_u32 s13, s13, 0
	v_mov_b32_e32 v11, v5
	v_or_b32_e32 v4, s14, v7
	v_lshl_add_u64 v[38:39], s[12:13], 0, v[10:11]
	v_lshlrev_b32_e32 v4, 12, v4
	s_waitcnt lgkmcnt(6)
	v_cvt_pk_bf16_f32 v20, v24, v12
	s_waitcnt lgkmcnt(4)
	v_cvt_pk_bf16_f32 v21, v26, v28
	s_waitcnt lgkmcnt(2)
	v_cvt_pk_bf16_f32 v22, v30, v32
	s_waitcnt lgkmcnt(0)
	v_cvt_pk_bf16_f32 v23, v34, v36
	v_lshl_add_u64 v[40:41], v[38:39], 0, v[4:5]
	global_store_dwordx4 v[40:41], v[20:23], off
	v_or_b32_e32 v4, s14, v15
	v_lshlrev_b32_e32 v4, 12, v4
	v_cvt_pk_bf16_f32 v20, v25, v13
	v_cvt_pk_bf16_f32 v21, v27, v29
	v_cvt_pk_bf16_f32 v22, v31, v33
	v_cvt_pk_bf16_f32 v23, v35, v37
	ds_read2_b32 v[24:25], v14 offset0:49 offset1:57
	ds_read2_b32 v[26:27], v14 offset0:16 offset1:24
	ds_read2_b32 v[28:29], v14 offset0:82 offset1:90
	ds_read2_b32 v[30:31], v14 offset0:115 offset1:123
	ds_read2_b32 v[32:33], v14 offset0:148 offset1:156
	ds_read2_b32 v[34:35], v14 offset0:181 offset1:189
	ds_read2_b32 v[36:37], v14 offset0:214 offset1:222
	ds_read2_b32 v[40:41], v14 offset0:247 offset1:255
	v_lshl_add_u64 v[12:13], v[38:39], 0, v[4:5]
	v_or_b32_e32 v4, s14, v16
	v_lshlrev_b32_e32 v4, 12, v4
	global_store_dwordx4 v[12:13], v[20:23], off
	v_lshl_add_u64 v[12:13], v[38:39], 0, v[4:5]
	v_or_b32_e32 v4, s14, v17
	s_waitcnt lgkmcnt(6)
	v_cvt_pk_bf16_f32 v20, v26, v24
	s_waitcnt lgkmcnt(4)
	v_cvt_pk_bf16_f32 v21, v28, v30
	s_waitcnt lgkmcnt(2)
	v_cvt_pk_bf16_f32 v22, v32, v34
	s_waitcnt lgkmcnt(0)
	v_cvt_pk_bf16_f32 v23, v36, v40
	v_lshlrev_b32_e32 v4, 12, v4
	global_store_dwordx4 v[12:13], v[20:23], off
	v_lshl_add_u64 v[12:13], v[38:39], 0, v[4:5]
	s_mov_b64 s[12:13], 0
	v_cvt_pk_bf16_f32 v20, v27, v25
	v_cvt_pk_bf16_f32 v21, v29, v31
	v_cvt_pk_bf16_f32 v22, v33, v35
	v_cvt_pk_bf16_f32 v23, v37, v41
	global_store_dwordx4 v[12:13], v[20:23], off
.LBB0_15:
	s_and_b64 vcc, exec, s[12:13]
	s_cbranch_vccz .LBB0_19
	s_add_i32 s12, s29, 0xfffef780
	s_lshr_b32 s10, s12, 10
	s_and_b32 s12, s12, 0x3c0
	s_lshl_b64 s[30:31], s[10:11], 23
	s_waitcnt lgkmcnt(0)
	s_add_u32 s13, s6, s30
	s_addc_u32 s15, s7, s31
	s_lshl_b32 s30, s14, 2
	s_add_u32 s30, s13, s30
	s_addc_u32 s31, s15, 0
	v_mov_b32_e32 v9, v5
	v_lshl_add_u64 v[12:13], s[30:31], 0, v[8:9]
	s_mov_b32 s13, s12
	s_mov_b32 s15, 1
	s_mov_b32 s30, 0
	s_mov_b32 s31, 32
.LBB0_17:
	s_lshl_b32 s35, s15, 1
	s_lshl_b32 s36, s30, 1
	v_or_b32_e32 v11, s36, v2
	s_add_i32 s37, s35, 4
	s_add_i32 s38, s36, 4
	s_add_i32 s44, s36, 8
	v_add_u32_e32 v4, s12, v11
	v_or_b32_e32 v19, s37, v1
	v_or_b32_e32 v42, s38, v2
	v_mov_b32_e32 v23, v5
	v_or_b32_e32 v9, s35, v1
	s_add_i32 s46, s36, 12
	v_or_b32_e32 v44, s44, v2
	v_lshlrev_b64 v[36:37], 13, v[4:5]
	v_add_u32_e32 v22, s13, v19
	v_add_u32_e32 v4, s12, v42
	v_mov_b32_e32 v21, v5
	s_add_i32 s39, s35, 8
	s_add_i32 s45, s35, 12
	s_add_i32 s48, s36, 16
	v_add_u32_e32 v20, s13, v9
	v_or_b32_e32 v46, s46, v2
	v_lshlrev_b64 v[22:23], 13, v[22:23]
	v_lshlrev_b64 v[38:39], 13, v[4:5]
	v_add_u32_e32 v4, s12, v44
	s_add_i32 s50, s36, 20
	v_or_b32_e32 v43, s39, v1
	v_or_b32_e32 v45, s45, v1
	v_or_b32_e32 v48, s48, v2
	v_lshlrev_b64 v[20:21], 13, v[20:21]
	v_lshl_add_u64 v[36:37], v[12:13], 0, v[36:37]
	v_lshl_add_u64 v[22:23], v[12:13], 0, v[22:23]
	v_lshlrev_b64 v[40:41], 13, v[4:5]
	v_add_u32_e32 v4, s12, v46
	v_mov_b32_e32 v25, v5
	v_mov_b32_e32 v27, v5
	s_add_i32 s47, s35, 16
	s_add_i32 s49, s35, 20
	s_add_i32 s52, s36, 24
	v_or_b32_e32 v50, s50, v2
	v_add_u32_e32 v24, s13, v43
	v_add_u32_e32 v26, s13, v45
	v_lshl_add_u64 v[20:21], v[12:13], 0, v[20:21]
	v_lshl_add_u64 v[38:39], v[12:13], 0, v[38:39]
	global_load_dword v55, v[36:37], off
	global_load_dword v56, v[20:21], off
	global_load_dword v57, v[38:39], off
	global_load_dword v58, v[22:23], off
	v_lshlrev_b64 v[22:23], 13, v[4:5]
	v_add_u32_e32 v4, s12, v48
	s_add_i32 s51, s35, 24
	s_add_i32 s35, s35, 28
	s_add_i32 s36, s36, 28
	v_or_b32_e32 v47, s47, v1
	v_or_b32_e32 v49, s49, v1
	v_or_b32_e32 v52, s52, v2
	v_lshlrev_b64 v[24:25], 13, v[24:25]
	v_lshlrev_b64 v[26:27], 13, v[26:27]
	v_lshl_add_u64 v[20:21], v[12:13], 0, v[40:41]
	v_lshl_add_u64 v[22:23], v[12:13], 0, v[22:23]
	v_lshlrev_b64 v[36:37], 13, v[4:5]
	v_add_u32_e32 v4, s12, v50
	v_mov_b32_e32 v29, v5
	v_mov_b32_e32 v31, v5
	v_or_b32_e32 v51, s51, v1
	v_or_b32_e32 v53, s35, v1
	v_or_b32_e32 v54, s36, v2
	v_add_u32_e32 v28, s13, v47
	v_add_u32_e32 v30, s13, v49
	v_lshl_add_u64 v[24:25], v[12:13], 0, v[24:25]
	v_lshl_add_u64 v[26:27], v[12:13], 0, v[26:27]
	global_load_dword v59, v[20:21], off
	global_load_dword v60, v[24:25], off
	global_load_dword v61, v[22:23], off
	global_load_dword v62, v[26:27], off
; #define LAS __attribute__((address_space(3)))
; #define LDS_WAIT() asm volatile("s_waitcnt lgkmcnt(0)" ::: "memory")
; __device__ __forceinline__ unsigned cvtpk(float lo, float hi) { const f32x2_t v = {lo, hi}; const bf16x2_t b = __builtin_convertvector(v, bf16x2_t); return __builtin_bit_cast(unsigned, b); }
; template <bool MAPW = false>
; __device__ __forceinline__ void transpose_item(const float* W, int K, int N, bf16* WT, int k0, int n0, int drow0, LAS float* scr, int lane) {
;     ...
;     for (int i = 0; i < 32; ++i) { const int kk = 2 * i + (lane >> 5); scr[kk * 33 + (lane & 31)] = W[(size_t)(k0 + kk) * N + n0 + (lane & 31)]; }
;     LDS_WAIT(); asm volatile("" ::: "memory");
;     const int c = lane & 7;
; #pragma unroll
;     for (int j = 0; j < 4; ++j) { const int n = (lane >> 3) + 8 * j; const LAS float* s = scr + (8 * c) * 33 + n;
;         v4u o; o.x = cvtpk(s[0 * 33], s[1 * 33]); o.y = cvtpk(s[2 * 33], s[3 * 33]); o.z = cvtpk(s[4 * 33], s[5 * 33]); o.w = cvtpk(s[6 * 33], s[7 * 33]);
;         *(v4u*)(WT + (size_t)(MAPW ? win_row(drow0 + n) : drow0 + n) * K + k0 + 8 * c) = o; }
;     LDS_WAIT(); asm volatile("" ::: "memory");
; __device__ __forceinline__ void phase_prologue(LAS unsigned char* lds, const float* w_in, const float* w_branch, const float* w_out, unsigned char* ws, int gw, int ngw, int wave, int lane) {
;     ...
;         if (r < 12 * I_BR) { const int m = r / I_BR; r -= m * I_BR; const int kb = r / 64, nb = r % 64;
;             transpose_item(w_branch + (size_t)m * 1024 * 2048, 1024, 2048, (bf16*)(ws + WS_WBR + (size_t)m * SZ_WBR_1), kb * 64, nb * 32, nb * 32, scr, lane); continue; }
	v_lshlrev_b64 v[22:23], 13, v[4:5]
	v_add_u32_e32 v4, s12, v52
	v_mov_b32_e32 v33, v5
	v_mov_b32_e32 v35, v5
	v_add_u32_e32 v32, s13, v51
	v_add_u32_e32 v34, s13, v53
	v_lshlrev_b64 v[28:29], 13, v[28:29]
	v_lshlrev_b64 v[30:31], 13, v[30:31]
	v_lshl_add_u64 v[20:21], v[12:13], 0, v[36:37]
	v_lshl_add_u64 v[22:23], v[12:13], 0, v[22:23]
	v_lshlrev_b64 v[24:25], 13, v[4:5]
	v_add_u32_e32 v4, s12, v54
	v_lshlrev_b64 v[32:33], 13, v[32:33]
	v_lshlrev_b64 v[34:35], 13, v[34:35]
	v_lshl_add_u64 v[28:29], v[12:13], 0, v[28:29]
	v_lshl_add_u64 v[30:31], v[12:13], 0, v[30:31]
	global_load_dword v63, v[20:21], off
	global_load_dword v64, v[28:29], off
	global_load_dword v65, v[22:23], off
	global_load_dword v66, v[30:31], off
	v_lshl_add_u64 v[20:21], v[12:13], 0, v[24:25]
	v_lshlrev_b64 v[22:23], 13, v[4:5]
	v_lshl_add_u64 v[32:33], v[12:13], 0, v[32:33]
	v_lshl_add_u64 v[34:35], v[12:13], 0, v[34:35]
	v_lshl_add_u64 v[22:23], v[12:13], 0, v[22:23]
	global_load_dword v4, v[20:21], off
	global_load_dword v67, v[32:33], off
	global_load_dword v68, v[22:23], off
	global_load_dword v69, v[34:35], off
	s_add_i32 s30, s30, 16
	s_add_i32 s15, s15, 16
	s_add_i32 s31, s31, -16
	v_mad_u64_u32 v[20:21], s[36:37], v11, s23, v[6:7]
	s_cmp_lg_u32 s31, 0
	v_mad_u64_u32 v[22:23], s[36:37], v9, s23, v[6:7]
	v_mad_u64_u32 v[24:25], s[36:37], v42, s23, v[6:7]
	v_mad_u64_u32 v[26:27], s[36:37], v19, s23, v[6:7]
	v_mad_u64_u32 v[28:29], s[36:37], v44, s23, v[6:7]
	v_mad_u64_u32 v[30:31], s[36:37], v43, s23, v[6:7]
	v_mad_u64_u32 v[32:33], s[36:37], v46, s23, v[6:7]
	v_mad_u64_u32 v[34:35], s[36:37], v45, s23, v[6:7]
	v_mad_u64_u32 v[36:37], s[36:37], v48, s23, v[6:7]
	v_mad_u64_u32 v[38:39], s[36:37], v47, s23, v[6:7]
	v_mad_u64_u32 v[40:41], s[36:37], v50, s23, v[6:7]
	v_mad_u64_u32 v[42:43], s[36:37], v49, s23, v[6:7]
	v_mad_u64_u32 v[44:45], s[36:37], v52, s23, v[6:7]
	v_mad_u64_u32 v[46:47], s[36:37], v51, s23, v[6:7]
	v_mad_u64_u32 v[48:49], s[36:37], v54, s23, v[6:7]
	v_mad_u64_u32 v[50:51], s[36:37], v53, s23, v[6:7]
	s_waitcnt vmcnt(15)
	ds_write_b32 v20, v55
	s_waitcnt vmcnt(14)
	ds_write_b32 v22, v56
	s_waitcnt vmcnt(13)
	ds_write_b32 v24, v57
	s_waitcnt vmcnt(12)
	ds_write_b32 v26, v58
	s_waitcnt vmcnt(11)
	ds_write_b32 v28, v59
	s_waitcnt vmcnt(10)
	ds_write_b32 v30, v60
	s_waitcnt vmcnt(9)
	ds_write_b32 v32, v61
	s_waitcnt vmcnt(8)
	ds_write_b32 v34, v62
	s_waitcnt vmcnt(7)
	ds_write_b32 v36, v63
	s_waitcnt vmcnt(6)
	ds_write_b32 v38, v64
	s_waitcnt vmcnt(5)
	ds_write_b32 v40, v65
	s_waitcnt vmcnt(4)
	ds_write_b32 v42, v66
	s_waitcnt vmcnt(3)
	ds_write_b32 v44, v4
	s_waitcnt vmcnt(2)
	ds_write_b32 v46, v67
	s_waitcnt vmcnt(1)
	ds_write_b32 v48, v68
	s_waitcnt vmcnt(0)
	ds_write_b32 v50, v69
	s_cbranch_scc1 .LBB0_17
	s_waitcnt lgkmcnt(0)
	s_lshl_b64 s[30:31], s[10:11], 22
	s_add_u32 s10, s19, s30
	ds_read2_b32 v[12:13], v14 offset0:33 offset1:41
	ds_read2_b32 v[24:25], v14 offset1:8
	ds_read2_b32 v[26:27], v14 offset0:66 offset1:74
	ds_read2_b32 v[28:29], v14 offset0:99 offset1:107
	ds_read2_b32 v[30:31], v14 offset0:132 offset1:140
	ds_read2_b32 v[32:33], v14 offset0:165 offset1:173
	ds_read2_b32 v[34:35], v14 offset0:198 offset1:206
	ds_read2_b32 v[36:37], v14 offset0:231 offset1:239
	s_addc_u32 s13, s20, s31
	s_lshl_b32 s12, s12, 1
	s_add_u32 s12, s10, s12
	s_addc_u32 s13, s13, 0
	v_mov_b32_e32 v11, v5
	v_or_b32_e32 v4, s14, v7
	v_lshl_add_u64 v[38:39], s[12:13], 0, v[10:11]
	v_lshlrev_b32_e32 v4, 11, v4
	s_waitcnt lgkmcnt(6)
	v_cvt_pk_bf16_f32 v20, v24, v12
	s_waitcnt lgkmcnt(4)
	v_cvt_pk_bf16_f32 v21, v26, v28
	s_waitcnt lgkmcnt(2)
	v_cvt_pk_bf16_f32 v22, v30, v32
	s_waitcnt lgkmcnt(0)
	v_cvt_pk_bf16_f32 v23, v34, v36
	v_lshl_add_u64 v[40:41], v[38:39], 0, v[4:5]
	global_store_dwordx4 v[40:41], v[20:23], off
	v_or_b32_e32 v4, s14, v15
	v_lshlrev_b32_e32 v4, 11, v4
	v_cvt_pk_bf16_f32 v20, v25, v13
	v_cvt_pk_bf16_f32 v21, v27, v29
	v_cvt_pk_bf16_f32 v22, v31, v33
	v_cvt_pk_bf16_f32 v23, v35, v37
	ds_read2_b32 v[24:25], v14 offset0:49 offset1:57
	ds_read2_b32 v[26:27], v14 offset0:16 offset1:24
	ds_read2_b32 v[28:29], v14 offset0:82 offset1:90
	ds_read2_b32 v[30:31], v14 offset0:115 offset1:123
	ds_read2_b32 v[32:33], v14 offset0:148 offset1:156
	ds_read2_b32 v[34:35], v14 offset0:181 offset1:189
	ds_read2_b32 v[36:37], v14 offset0:214 offset1:222
	ds_read2_b32 v[40:41], v14 offset0:247 offset1:255
	v_lshl_add_u64 v[12:13], v[38:39], 0, v[4:5]
	v_or_b32_e32 v4, s14, v16
	v_lshlrev_b32_e32 v4, 11, v4
	global_store_dwordx4 v[12:13], v[20:23], off
	v_lshl_add_u64 v[12:13], v[38:39], 0, v[4:5]
	v_or_b32_e32 v4, s14, v17
	s_waitcnt lgkmcnt(6)
	v_cvt_pk_bf16_f32 v20, v26, v24
	s_waitcnt lgkmcnt(4)
	v_cvt_pk_bf16_f32 v21, v28, v30
	s_waitcnt lgkmcnt(2)
	v_cvt_pk_bf16_f32 v22, v32, v34
	s_waitcnt lgkmcnt(0)
	v_cvt_pk_bf16_f32 v23, v36, v40
	v_lshlrev_b32_e32 v4, 11, v4
	global_store_dwordx4 v[12:13], v[20:23], off
	v_lshl_add_u64 v[12:13], v[38:39], 0, v[4:5]
	s_nop 0
	v_cvt_pk_bf16_f32 v20, v27, v25
	v_cvt_pk_bf16_f32 v21, v29, v31
	v_cvt_pk_bf16_f32 v22, v33, v35
	v_cvt_pk_bf16_f32 v23, v37, v41
	global_store_dwordx4 v[12:13], v[20:23], off
.LBB0_19:
	s_cbranch_execnz .LBB0_8

; #define w_in INP(3)
; template <bool MAPW = false>
; __device__ __forceinline__ void transpose_item(const float* W, int K, int N, bf16* WT, int k0, int n0, int drow0, LAS float* scr, int lane) {
;     ...
;     for (int i = 0; i < 32; ++i) { const int kk = 2 * i + (lane >> 5); scr[kk * 33 + (lane & 31)] = W[(size_t)(k0 + kk) * N + n0 + (lane & 31)]; }
; __device__ __forceinline__ void phase_prologue(LAS unsigned char* lds, const float* w_in, const float* w_branch, const float* w_out, unsigned char* ws, int gw, int ngw, int wave, int lane) {
;     ...
;         if (r < 4 * I_IN) { const int l = r / I_IN; r -= l * I_IN; const int kb = r / NB_IN, nb = r % NB_IN, n0 = nb * 32;
;             const int drow = (n0 < 4096) ? n0 : ((n0 < 4128) ? (C_BA + (n0 - 4096)) : (n0 - 32));
;             transpose_item<true>(w_in + (size_t)l * DM * IN_REAL, DM, IN_REAL, (bf16*)(ws + WS_WIN + (size_t)l * SZ_WIN_L), kb * 64, n0, drow, scr, lane); continue; }
.LBB0_21:
	s_lshl_b32 s36, s30, 1
	s_lshl_b32 s37, s31, 1
	v_or_b32_e32 v4, s36, v1
	v_or_b32_e32 v9, s37, v2
	s_add_i32 s38, s36, 4
	s_add_i32 s39, s37, 4
	s_add_i32 s44, s36, 8
	s_add_i32 s45, s37, 8
	s_add_i32 s46, s36, 12
	s_add_i32 s47, s37, 12
	s_add_i32 s48, s36, 16
	s_add_i32 s49, s37, 16
	s_add_i32 s50, s36, 20
	s_add_i32 s51, s37, 20
	s_add_i32 s52, s36, 24
	s_add_i32 s53, s37, 24
	s_add_i32 s36, s36, 28
	s_add_i32 s37, s37, 28
	v_add_u32_e32 v11, s15, v4
	v_add_u32_e32 v19, s12, v9
	v_or_b32_e32 v52, s38, v1
	v_or_b32_e32 v53, s39, v2
	v_or_b32_e32 v54, s44, v1
	v_or_b32_e32 v55, s45, v2
	v_or_b32_e32 v56, s46, v1
	v_or_b32_e32 v57, s47, v2
	v_or_b32_e32 v58, s48, v1
	v_or_b32_e32 v59, s49, v2
	v_or_b32_e32 v60, s50, v1
	v_or_b32_e32 v61, s51, v2
	v_or_b32_e32 v62, s52, v1
	v_or_b32_e32 v63, s53, v2
	v_or_b32_e32 v64, s36, v1
	v_or_b32_e32 v65, s37, v2
	v_mad_i64_i32 v[20:21], s[36:37], v19, s24, v[12:13]
	v_mad_i64_i32 v[22:23], s[36:37], v11, s24, v[12:13]
	v_add_u32_e32 v11, s15, v52
	v_add_u32_e32 v19, s12, v53
	v_add_u32_e32 v30, s15, v54
	v_add_u32_e32 v28, s12, v55
	v_add_u32_e32 v34, s15, v56
	v_add_u32_e32 v32, s12, v57
	v_add_u32_e32 v38, s15, v58
	v_add_u32_e32 v36, s12, v59
	v_add_u32_e32 v42, s15, v60
	v_add_u32_e32 v40, s12, v61
	v_add_u32_e32 v46, s15, v62
	v_add_u32_e32 v44, s12, v63
	v_add_u32_e32 v50, s15, v64
	v_add_u32_e32 v48, s12, v65
	v_mad_i64_i32 v[24:25], s[36:37], v19, s24, v[12:13]
	v_mad_i64_i32 v[26:27], s[36:37], v11, s24, v[12:13]
	v_mad_i64_i32 v[28:29], s[36:37], v28, s24, v[12:13]
	v_mad_i64_i32 v[30:31], s[36:37], v30, s24, v[12:13]
	v_mad_i64_i32 v[32:33], s[36:37], v32, s24, v[12:13]
	v_mad_i64_i32 v[34:35], s[36:37], v34, s24, v[12:13]
	v_mad_i64_i32 v[36:37], s[36:37], v36, s24, v[12:13]
	v_mad_i64_i32 v[38:39], s[36:37], v38, s24, v[12:13]
	v_mad_i64_i32 v[40:41], s[36:37], v40, s24, v[12:13]
	v_mad_i64_i32 v[42:43], s[36:37], v42, s24, v[12:13]
	v_mad_i64_i32 v[44:45], s[36:37], v44, s24, v[12:13]
	v_mad_i64_i32 v[46:47], s[36:37], v46, s24, v[12:13]
	v_mad_i64_i32 v[48:49], s[36:37], v48, s24, v[12:13]
	v_mad_i64_i32 v[50:51], s[36:37], v50, s24, v[12:13]
	global_load_dword v11, v[20:21], off
	global_load_dword v19, v[22:23], off
	global_load_dword v66, v[24:25], off
	global_load_dword v67, v[26:27], off
	global_load_dword v68, v[28:29], off
	global_load_dword v69, v[30:31], off
	global_load_dword v70, v[32:33], off
	global_load_dword v71, v[34:35], off
	global_load_dword v72, v[36:37], off
	global_load_dword v73, v[38:39], off
	global_load_dword v74, v[40:41], off
	global_load_dword v75, v[42:43], off
	global_load_dword v76, v[44:45], off
	global_load_dword v77, v[46:47], off
	global_load_dword v78, v[48:49], off
	global_load_dword v79, v[50:51], off
	s_add_i32 s31, s31, 16
	s_add_i32 s30, s30, 16
	s_add_i32 s35, s35, -16
	v_mad_u64_u32 v[20:21], s[36:37], v9, s23, v[6:7]
	s_cmp_lg_u32 s35, 0
	v_mad_u64_u32 v[22:23], s[36:37], v4, s23, v[6:7]
	v_mad_u64_u32 v[24:25], s[36:37], v53, s23, v[6:7]
	v_mad_u64_u32 v[26:27], s[36:37], v52, s23, v[6:7]
	v_mad_u64_u32 v[28:29], s[36:37], v55, s23, v[6:7]
	v_mad_u64_u32 v[30:31], s[36:37], v54, s23, v[6:7]
	v_mad_u64_u32 v[32:33], s[36:37], v57, s23, v[6:7]
	v_mad_u64_u32 v[34:35], s[36:37], v56, s23, v[6:7]
	v_mad_u64_u32 v[36:37], s[36:37], v59, s23, v[6:7]
	v_mad_u64_u32 v[38:39], s[36:37], v58, s23, v[6:7]
	v_mad_u64_u32 v[40:41], s[36:37], v61, s23, v[6:7]
	v_mad_u64_u32 v[42:43], s[36:37], v60, s23, v[6:7]
	v_mad_u64_u32 v[44:45], s[36:37], v63, s23, v[6:7]
	v_mad_u64_u32 v[46:47], s[36:37], v62, s23, v[6:7]
	v_mad_u64_u32 v[48:49], s[36:37], v65, s23, v[6:7]
	v_mad_u64_u32 v[50:51], s[36:37], v64, s23, v[6:7]
	s_waitcnt vmcnt(15)
	ds_write_b32 v20, v11
	s_waitcnt vmcnt(14)
	ds_write_b32 v22, v19
	s_waitcnt vmcnt(13)
	ds_write_b32 v24, v66
	s_waitcnt vmcnt(12)
	ds_write_b32 v26, v67
	s_waitcnt vmcnt(11)
	ds_write_b32 v28, v68
	s_waitcnt vmcnt(10)
	ds_write_b32 v30, v69
	s_waitcnt vmcnt(9)
	ds_write_b32 v32, v70
	s_waitcnt vmcnt(8)
	ds_write_b32 v34, v71
	s_waitcnt vmcnt(7)
	ds_write_b32 v36, v72
	s_waitcnt vmcnt(6)
	ds_write_b32 v38, v73
	s_waitcnt vmcnt(5)
	ds_write_b32 v40, v74
	s_waitcnt vmcnt(4)
	ds_write_b32 v42, v75
	s_waitcnt vmcnt(3)
	ds_write_b32 v44, v76
	s_waitcnt vmcnt(2)
	ds_write_b32 v46, v77
	s_waitcnt vmcnt(1)
	ds_write_b32 v48, v78
	s_waitcnt vmcnt(0)
	ds_write_b32 v50, v79
	s_cbranch_scc1 .LBB0_21
; #define LAS __attribute__((address_space(3)))
; #define LDS_WAIT() asm volatile("s_waitcnt lgkmcnt(0)" ::: "memory")
; __device__ __forceinline__ unsigned cvtpk(float lo, float hi) { const f32x2_t v = {lo, hi}; const bf16x2_t b = __builtin_convertvector(v, bf16x2_t); return __builtin_bit_cast(unsigned, b); }
; __device__ __forceinline__ int win_row(int dl) {
;     const int L = dl & 255;
;     const int p = (dl >= C_GATE && dl < C_GATE + 6144) ? (((L >> 3) & 1) * 128 + (L >> 6) * 32 + ((L >> 4) & 3) * 8 + (L & 7)) : (((L >> 5) & 1) * 128 + (L >> 6) * 32 + (L & 31));
;     return (dl & ~255) + p;
; template <bool MAPW = false>
; __device__ __forceinline__ void transpose_item(const float* W, int K, int N, bf16* WT, int k0, int n0, int drow0, LAS float* scr, int lane) {
;     ...
;     LDS_WAIT(); asm volatile("" ::: "memory");
;     const int c = lane & 7;
; #pragma unroll
;     for (int j = 0; j < 4; ++j) { const int n = (lane >> 3) + 8 * j; const LAS float* s = scr + (8 * c) * 33 + n;
;         v4u o; o.x = cvtpk(s[0 * 33], s[1 * 33]); o.y = cvtpk(s[2 * 33], s[3 * 33]); o.z = cvtpk(s[4 * 33], s[5 * 33]); o.w = cvtpk(s[6 * 33], s[7 * 33]);
;         *(v4u*)(WT + (size_t)(MAPW ? win_row(drow0 + n) : drow0 + n) * K + k0 + 8 * c) = o; }
;     LDS_WAIT(); asm volatile("" ::: "memory");
	s_sub_i32 s15, s14, 32
	s_cmpk_lg_i32 s13, 0x80
	s_cselect_b32 s15, s15, 0x4200
	s_mul_hi_i32 s30, s10, 0x4300000
	s_mul_i32 s10, s10, 0x4300000
	s_cmpk_lt_i32 s13, 0x80
	s_cselect_b32 s14, s14, s15
	s_add_u32 s10, s21, s10
	s_addc_u32 s15, s22, s30
	s_ashr_i32 s13, s12, 31
	s_lshl_b64 s[12:13], s[12:13], 1
	s_add_u32 s12, s10, s12
	s_addc_u32 s13, s15, s13
	s_add_i32 s10, s14, 0xffffd600
	s_waitcnt lgkmcnt(0)
	s_cmpk_lt_u32 s10, 0x1800
	v_mov_b32_e32 v11, v5
	v_or_b32_e32 v4, s14, v7
	s_cselect_b32 s10, 4, 2
	ds_read2_b32 v[12:13], v14 offset0:33 offset1:41
	ds_read2_b32 v[24:25], v14 offset1:8
	ds_read2_b32 v[26:27], v14 offset0:66 offset1:74
	ds_read2_b32 v[28:29], v14 offset0:99 offset1:107
	ds_read2_b32 v[30:31], v14 offset0:132 offset1:140
	ds_read2_b32 v[32:33], v14 offset0:165 offset1:173
	ds_read2_b32 v[34:35], v14 offset0:198 offset1:206
	ds_read2_b32 v[36:37], v14 offset0:231 offset1:239
	v_lshl_add_u64 v[38:39], s[12:13], 0, v[10:11]
	v_lshrrev_b32_e32 v9, 1, v4
	s_cselect_b32 s12, s25, 0x60
	v_lshlrev_b32_e32 v4, s10, v4
	v_and_b32_e32 v4, 0x80, v4
	v_and_b32_e32 v9, s12, v9
	v_bitop3_b32 v11, s14, v18, v7 bitop3:0xc8
	v_or3_b32 v40, v9, v11, v4
	v_or_b32_e32 v4, s14, v15
	v_ashrrev_i32_e32 v41, 31, v40
	v_lshrrev_b32_e32 v9, 1, v4
	v_lshlrev_b32_e32 v4, s10, v4
	s_cselect_b32 s13, 0xffffff07, s26
	v_mov_b32_e32 v11, s14
	s_waitcnt lgkmcnt(6)
	v_cvt_pk_bf16_f32 v20, v24, v12
	v_lshlrev_b64 v[40:41], 12, v[40:41]
	v_and_b32_e32 v4, 0x80, v4
	v_and_b32_e32 v9, s12, v9
	v_bitop3_b32 v12, s13, v11, v15 bitop3:0xe0
	s_waitcnt lgkmcnt(4)
	v_cvt_pk_bf16_f32 v21, v26, v28
	s_waitcnt lgkmcnt(2)
	v_cvt_pk_bf16_f32 v22, v30, v32
	s_waitcnt lgkmcnt(0)
	v_cvt_pk_bf16_f32 v23, v34, v36
	v_lshl_add_u64 v[40:41], v[38:39], 0, v[40:41]
	v_or3_b32 v12, v12, v9, v4
	global_store_dwordx4 v[40:41], v[20:23], off
	v_or_b32_e32 v4, s14, v16
	v_lshrrev_b32_e32 v9, 1, v4
	v_cvt_pk_bf16_f32 v20, v25, v13
	v_ashrrev_i32_e32 v13, 31, v12
	v_lshlrev_b64 v[12:13], 12, v[12:13]
	v_cvt_pk_bf16_f32 v21, v27, v29
	v_cvt_pk_bf16_f32 v22, v31, v33
	v_cvt_pk_bf16_f32 v23, v35, v37
	v_lshl_add_u64 v[12:13], v[38:39], 0, v[12:13]
	ds_read2_b32 v[24:25], v14 offset0:16 offset1:24
	ds_read2_b32 v[26:27], v14 offset0:49 offset1:57
	ds_read2_b32 v[28:29], v14 offset0:82 offset1:90
	ds_read2_b32 v[30:31], v14 offset0:115 offset1:123
	ds_read2_b32 v[32:33], v14 offset0:148 offset1:156
	ds_read2_b32 v[34:35], v14 offset0:181 offset1:189
	ds_read2_b32 v[36:37], v14 offset0:214 offset1:222
	ds_read2_b32 v[40:41], v14 offset0:247 offset1:255
	v_lshlrev_b32_e32 v4, s10, v4
	s_cselect_b32 s13, 0xffffff07, s27
	global_store_dwordx4 v[12:13], v[20:23], off
	v_and_b32_e32 v4, 0x80, v4
	v_and_b32_e32 v9, s12, v9
	v_bitop3_b32 v12, s13, v11, v16 bitop3:0xe0
	v_or3_b32 v12, v12, v9, v4
	v_ashrrev_i32_e32 v13, 31, v12
	v_or_b32_e32 v4, s14, v17
	v_lshlrev_b64 v[12:13], 12, v[12:13]
	v_lshrrev_b32_e32 v9, 1, v4
	v_lshlrev_b32_e32 v4, s10, v4
	s_cselect_b32 s10, 0xffffff07, s28
	s_waitcnt lgkmcnt(6)
	v_cvt_pk_bf16_f32 v20, v24, v26
	s_waitcnt lgkmcnt(4)
	v_cvt_pk_bf16_f32 v21, v28, v30
	s_waitcnt lgkmcnt(2)
	v_cvt_pk_bf16_f32 v22, v32, v34
	s_waitcnt lgkmcnt(0)
	v_cvt_pk_bf16_f32 v23, v36, v40
	v_lshl_add_u64 v[12:13], v[38:39], 0, v[12:13]
	v_and_b32_e32 v4, 0x80, v4
	v_and_b32_e32 v9, s12, v9
	v_bitop3_b32 v11, s10, v11, v17 bitop3:0xe0
	global_store_dwordx4 v[12:13], v[20:23], off
	v_or3_b32 v12, v11, v9, v4
	v_ashrrev_i32_e32 v13, 31, v12
	v_lshlrev_b64 v[12:13], 12, v[12:13]
	v_cvt_pk_bf16_f32 v20, v25, v27
	v_cvt_pk_bf16_f32 v21, v29, v31
	v_cvt_pk_bf16_f32 v22, v33, v35
	v_cvt_pk_bf16_f32 v23, v37, v41
	v_lshl_add_u64 v[12:13], v[38:39], 0, v[12:13]
	global_store_dwordx4 v[12:13], v[20:23], off
	s_branch .LBB0_8

; #define LAUNDER_TID() int tid = tid0; asm volatile("" : "+v"(tid)); const int lane = tid & 63, wave = __builtin_amdgcn_readfirstlane(tid >> 6), gw = bx * NWAVES + wave; (void)lane; (void)gw
; #define norm_gain INP(2)
; __device__ __forceinline__ void rms_row(const float* xrow, const float* gain, bf16* orow, float* rowss, int lane) {
;     const f32x4* xr = (const f32x4*)xrow + lane; const f32x4* gr = (const f32x4*)gain + lane;
;     f32x4 v[8]; float s = 0.f;
; #pragma unroll
;     for (int j = 0; j < 8; ++j) { v[j] = xr[64 * j]; s += (v[j].x * v[j].x + v[j].y * v[j].y) + (v[j].z * v[j].z + v[j].w * v[j].w); }
; __global__ void __launch_bounds__(NTHREADS, 2) fwd_kernel(Args args) {
;     ...
;         if (PH_ON(1) && IN(pb + 0) && l == 0) { LAUNDER_TID(); const float* xin = XIN(); const float* ng = norm_gain; for (int m = gw; m < PASS_ROWS; m += ngw) rms_row(xin + (size_t)m * DM, ng, HNp + (size_t)m * DM, RSp + m, lane); }
.LBB0_90:
	s_ashr_i32 s4, s8, 6
	v_readlane_b32 s3, v252, 28
	s_add_i32 s8, s4, s3
	v_readlane_b32 s4, v251, 0
	v_readlane_b32 s5, v251, 1
	s_cmpk_gt_i32 s8, 0x3fff
	s_cbranch_scc1 .LBB0_95
	s_load_dwordx2 s[16:17], s[4:5], 0x10
	v_readlane_b32 s10, v254, 7
	v_readlane_b32 s11, v254, 8
	v_and_b32_e32 v5, 63, v2
	s_lshl_b64 s[10:11], s[10:11], 16
	v_readlane_b32 s3, v254, 4
	s_and_b32 s9, s10, 0xfffc0000
	s_and_b32 s10, s3, 3
	s_waitcnt vmcnt(0)
	v_lshlrev_b32_e32 v6, 4, v5
	s_waitcnt lgkmcnt(0)
	v_mov_b32_e32 v7, v4
	s_lshl_b32 s15, s10, 16
	v_lshl_add_u64 v[2:3], s[16:17], 0, v[6:7]
	s_mov_b64 s[16:17], 0x1000
	s_lshl_b32 s18, s10, 26
	v_lshl_add_u64 v[38:39], v[2:3], 0, s[16:17]
	s_mov_b64 s[16:17], 0x1400
	s_or_b32 s10, s9, s15
	s_ashr_i32 s9, s8, 31
	v_lshl_add_u64 v[40:41], v[2:3], 0, s[16:17]
	s_lshl_b64 s[16:17], s[8:9], 2
	s_add_u32 s10, s10, s16
	s_addc_u32 s11, s11, s17
	v_readlane_b32 s3, v251, 8
	s_add_u32 s10, s3, s10
	v_readlane_b32 s3, v251, 9
	s_addc_u32 s11, s3, s11
	s_lshl_b64 s[16:17], s[8:9], 13
	s_add_u32 s12, s12, s16
	s_addc_u32 s13, s13, s17
	v_lshl_add_u64 v[6:7], s[12:13], 0, v[6:7]
	s_lshl_b64 s[12:13], s[8:9], 12
	s_add_u32 s9, s18, s12
	s_addc_u32 s13, 0, s13
	v_readlane_b32 s3, v253, 25
	v_lshl_add_u64 v[42:43], v[2:3], 0, s[22:23]
	s_mov_b64 s[22:23], 0x1c00
	s_add_u32 s12, s3, s9
	v_readlane_b32 s3, v253, 26
	v_lshl_add_u64 v[46:47], v[6:7], 0, s[22:23]
	v_lshlrev_b32_e32 v6, 3, v5
	v_mov_b32_e32 v7, v4
	s_addc_u32 s13, s3, s13
	v_cmp_eq_u32_e64 s[4:5], 0, v5
	v_lshl_add_u64 v[44:45], v[2:3], 0, s[22:23]
	v_lshl_add_u64 v[48:49], s[12:13], 0, v[6:7]
	s_branch .LBB0_93

; __device__ __forceinline__ float bflo(unsigned w) { return __uint_as_float(w << 16); }
; __device__ __forceinline__ float bfhi(unsigned w) { return __uint_as_float(w & 0xffff0000u); }
; #define LAS __attribute__((address_space(3)))
; #define conv_w INP(4)
; #define a_log INP(5)
; __device__ __forceinline__ void gdn_prep_unit(LAS unsigned char* lds, unsigned char* ws, const float* conv_w, const float* a_log, const float* dt_bias,
;                                               int l, int Tp, int ci, int h, int nci, int nh, unsigned& pre_ba, int tid, int wave, int lane) {
;     ...
;     const int row0 = ci * 64, tin = row0 % Tp; const bool first = (tin == 0), last = (tin + 64 == Tp);
;     LAS float* BETA = (LAS float*)(lds + D1_BETA); LAS float* GC = (LAS float*)(lds + D1_GC);
;     if (tid < 128) {
;         const int d = tid >> 6, r = tid & 63, c = d ? 63 - r : r;
;         const float braw = bflo(pre_ba), araw = bfhi(pre_ba);
;         if (nci >= 0) { const bf16* pn = PROJ + (size_t)(nci * 64 + c) * LDP + C_BA; pre_ba = (unsigned)pn[d * 8 + nh] | ((unsigned)pn[16 + d * 8 + nh] << 16); }
;         const float beta = __builtin_amdgcn_rcpf(1.0f + __expf(-braw));
;         const float x = araw + dt_bias[(l * 2 + d) * 8 + h];
;         const float sp = fmaxf(x, 0.f) + log1pf(__expf(-fabsf(x)));
;         float gcv = -__expf(a_log[(l * 2 + d) * 8 + h]) * sp;
; #pragma unroll
;         for (int off = 1; off < 64; off <<= 1) { const float t = __shfl_up(gcv, off); if (r >= off) gcv += t; }
;         BETA[d * 64 + r] = beta; GC[d * 64 + r] = gcv;
;         if (r == 63) *(float*)(gdn_rec(ws, d, ci, h) + REC_GAM) = __expf(gcv);
; __global__ void __launch_bounds__(NTHREADS, 2) fwd_kernel(Args args) {
;     ...
;             { const float* cw = conv_w; const float* al = a_log; const float* db = dt_bias;
;               for (int rep = 0; rep < NREP(3); ++rep) {
;                   unsigned pre_ba = 0u;
;                   if (tid < 128 && bx < 2048) { const int d = tid >> 6, r = tid & 63, c = d ? 63 - r : r; const bf16* pn = PROJ + (size_t)((bx >> 3) * 64 + c) * LDP + C_BA;
;                       pre_ba = (unsigned)pn[d * 8 + (bx & 7)] | ((unsigned)pn[16 + d * 8 + (bx & 7)] << 16); }
;                   for (int u = bx; u < 2048; u += G) { const int un = u + G; gdn_prep_unit(lds, ws, cw, al, db, l, Tp, u >> 3, u & 7, un < 2048 ? (un >> 3) : -1, un & 7, pre_ba, tid, wave, lane); } } }
.LBB0_316:
	s_or_b64 exec, exec, s[10:11]
	v_readlane_b32 s10, v252, 26
	v_readlane_b32 s11, v252, 27
	v_and_b32_e32 v106, 31, v6
	s_andn2_b64 vcc, exec, s[10:11]
	s_cbranch_vccnz .LBB0_510
	s_load_dwordx2 s[4:5], s[4:5], 0x20
	s_nop 0
	s_load_dwordx2 s[6:7], s[6:7], 0x28
	s_waitcnt lgkmcnt(0)
	v_lshlrev_b32_e32 v7, 3, v6
	v_ashrrev_i32_e32 v9, 4, v6
	v_and_b32_e32 v8, 0x78, v7
	v_and_b32_e32 v111, 63, v9
	v_writelane_b32 v254, s6, 36
	v_bfe_u32 v11, v7, 5, 2
	v_and_b32_e32 v38, 8, v7
	v_writelane_b32 v254, s7, 37
	s_load_dwordx2 s[6:7], s[8:9], 0x30
	v_ashrrev_i32_e32 v7, 10, v6
	v_lshlrev_b32_e32 v10, 4, v6
	v_and_b32_e32 v10, 0x70, v10
	v_lshlrev_b32_e32 v12, 9, v6
	s_waitcnt lgkmcnt(0)
	v_writelane_b32 v254, s6, 38
	v_lshrrev_b32_e32 v13, 3, v9
	v_and_b32_e32 v12, 0x400, v12
	v_writelane_b32 v254, s7, 39
	v_cmp_eq_u32_e64 s[6:7], 0, v5
	v_and_or_b32 v13, v13, 4, v11
	v_lshl_or_b32 v40, v13, 11, v12
	v_writelane_b32 v254, s6, 40
	v_lshl_add_u32 v110, v8, 1, 0
	v_mul_u32_u24_e32 v114, 0x90, v8
	v_writelane_b32 v254, s7, 41
	v_cmp_gt_u32_e64 s[6:7], 2, v5
	v_readlane_b32 s9, v253, 39
	v_readlane_b32 s3, v253, 36
	v_writelane_b32 v254, s6, 42
	v_readlane_b32 s8, v253, 37
	v_lshlrev_b32_e32 v3, 2, v6
	v_writelane_b32 v254, s7, 43
	v_cmp_gt_u32_e64 s[6:7], 4, v5
	v_and_b32_e32 v42, 0xfffffdf0, v6
	v_and_b32_e32 v44, 0x1f0, v6
	v_writelane_b32 v254, s6, 44
	v_add_u32_e32 v108, s3, v3
	v_add_u32_e32 v109, s8, v3
	v_writelane_b32 v254, s7, 45
	v_cmp_gt_u32_e64 s[6:7], 8, v5
	v_ashrrev_i32_e32 v3, 31, v2
	v_lshlrev_b32_e32 v145, 4, v5
	v_writelane_b32 v254, s6, 46
	v_add_u32_e32 v107, 16, v104
	v_lshlrev_b64 v[2:3], 11, v[2:3]
	v_writelane_b32 v254, s7, 47
	v_cmp_gt_u32_e64 s[6:7], 16, v5
	v_mov_b32_e32 v39, v4
	v_mul_u32_u24_e32 v115, 0x110, v111
	v_writelane_b32 v254, s6, 48
	v_lshl_add_u32 v116, v111, 2, s8
	v_mov_b32_e32 v41, v4
	v_writelane_b32 v254, s7, 49
	v_cmp_gt_u32_e64 s[6:7], 32, v5
	v_mov_b32_e32 v45, v4
	v_ashrrev_i32_e32 v43, 31, v42
	v_writelane_b32 v254, s6, 50
	v_mov_b32_e32 v47, v4
	v_mov_b32_e32 v49, v4
	v_writelane_b32 v254, s7, 51
	v_cmp_lt_u32_e64 s[6:7], 31, v5
	v_mov_b32_e32 v51, v4
	v_mov_b32_e32 v53, v4
	v_writelane_b32 v254, s6, 52
	v_mov_b32_e32 v55, v4
	v_mov_b32_e32 v57, v4
	v_writelane_b32 v254, s7, 53
	v_cmp_eq_u32_e64 s[6:7], 63, v5
	v_mov_b32_e32 v59, v4
	v_mov_b32_e32 v61, v4
	v_writelane_b32 v254, s6, 54
	v_mov_b32_e32 v63, v4
	v_mov_b32_e32 v65, v4
	v_writelane_b32 v254, s7, 55
	v_mov_b32_e32 v67, v4
	v_readlane_b32 s16, v254, 26
	s_mul_i32 s6, s16, 0x9000
	s_add_u32 s44, s4, s6
	s_movk_i32 s4, 0xfc00
	s_addc_u32 s45, s5, 0
	v_and_or_b32 v112, v6, s4, v8
	v_cmp_eq_u32_e64 s[4:5], 0, v111
	v_readlane_b32 s17, v254, 27
	s_cmp_lt_i32 s14, 12
	v_writelane_b32 v254, s4, 30
	v_mov_b32_e32 v69, v4
	v_mov_b32_e32 v71, v4
	v_writelane_b32 v254, s5, 31
	v_cmp_eq_u32_e64 s[4:5], 63, v111
	v_mov_b32_e32 v73, v4
	v_mov_b32_e32 v75, v4
	v_writelane_b32 v254, s4, 32
	v_mov_b32_e32 v77, v4
	v_mov_b32_e32 v79, v4
	v_writelane_b32 v254, s5, 33
	v_cmp_gt_i32_e64 s[4:5], 2, v7
	v_mov_b32_e32 v81, v4
	v_mov_b32_e32 v83, v4
	v_writelane_b32 v254, s4, 34
	v_mov_b32_e32 v85, v4
	v_mov_b32_e32 v87, v4
	v_writelane_b32 v254, s5, 35
	v_cmp_gt_u32_e64 s[4:5], 64, v9
	v_mov_b32_e32 v89, v4
	v_mov_b32_e32 v91, v4
	v_writelane_b32 v254, s4, 56
	v_mov_b32_e32 v93, v4
	v_mov_b32_e32 v95, v4
	v_writelane_b32 v254, s5, 57
	v_cmp_lt_u32_e64 s[4:5], 63, v9
	v_mov_b32_e32 v97, v4
	v_mov_b32_e32 v99, v4
	v_writelane_b32 v254, s4, 58
	v_mov_b32_e32 v101, v4
	v_mov_b32_e32 v103, v4
	v_writelane_b32 v254, s5, 59
	v_cmp_ne_u32_e64 s[4:5], 1, v7
	v_lshlrev_b32_e32 v7, 1, v111
	v_xad_u32 v113, v7, v10, 0
	v_xor_b32_e32 v7, 63, v9
	v_lshrrev_b32_e32 v13, 3, v7
	v_and_or_b32 v13, v13, 4, v11
	v_lshl_or_b32 v46, v13, 11, v12
	v_add_u32_e32 v13, 32, v9
	v_writelane_b32 v254, s4, 60
	v_and_b32_e32 v118, 63, v13
	v_cmp_eq_u32_e64 s[6:7], 0, v118
	v_writelane_b32 v254, s5, 61
	v_readlane_b32 s5, v253, 38
	v_writelane_b32 v254, s6, 62
	v_xor_b32_e32 v14, 63, v13
	v_lshl_add_u32 v117, v7, 2, s5
	v_lshlrev_b32_e32 v7, 4, v7
	v_writelane_b32 v254, s7, 63
	v_cmp_eq_u32_e64 s[6:7], 63, v118
	v_and_b32_e32 v48, 0x1f0, v7
	v_or_b32_e32 v50, 0x200, v7
	v_ashrrev_i32_e32 v7, 6, v13
	v_writelane_b32 v255, s6, 0
	v_lshrrev_b32_e32 v15, 3, v13
	v_lshl_add_u32 v122, v14, 2, s5
	v_writelane_b32 v255, s7, 1
	v_cmp_gt_i32_e64 s[6:7], 2, v7
	s_movk_i32 s4, 0xffbf
	v_and_or_b32 v15, v15, 4, v11
	v_writelane_b32 v255, s6, 2
	v_lshl_or_b32 v52, v15, 11, v12
	v_lshl_or_b32 v119, v7, 10, v8
	v_writelane_b32 v255, s7, 3
	v_cmp_gt_u32_e64 s[6:7], 64, v13
	v_mul_u32_u24_e32 v120, 0x110, v118
	v_lshl_add_u32 v121, v118, 2, s8
	v_writelane_b32 v255, s6, 4
	v_lshlrev_b32_e32 v191, 5, v5
	v_lshl_add_u32 v202, s16, 4, v104
	v_writelane_b32 v255, s7, 5
	v_cmp_lt_u32_e64 s[6:7], 63, v13
	v_lshlrev_b32_e32 v13, 4, v13
	v_and_b32_e32 v54, 0x1f0, v13
	v_or_b32_e32 v56, 0x200, v13
	v_lshrrev_b32_e32 v13, 3, v14
	v_and_or_b32 v13, v13, 4, v11
	v_writelane_b32 v255, s6, 6
	v_lshl_or_b32 v58, v13, 11, v12
	v_lshlrev_b32_e32 v13, 4, v14
	v_writelane_b32 v255, s7, 7
	v_cmp_ne_u32_e64 s[6:7], 1, v7
	v_and_b32_e32 v60, 0x1f0, v13
	v_or_b32_e32 v62, 0x200, v13
	v_add_u32_e32 v13, 64, v9
	v_writelane_b32 v255, s6, 8
	v_ashrrev_i32_e32 v14, 6, v13
	v_lshl_or_b32 v123, v14, 10, v8
	v_writelane_b32 v255, s7, 9
	v_cmp_gt_i32_e64 s[6:7], 2, v14
	v_xor_b32_e32 v13, 63, v13
	v_lshl_add_u32 v124, v13, 2, s5
	v_writelane_b32 v255, s6, 10
	v_lshlrev_b32_e32 v7, 1, v118
	v_xad_u32 v7, v7, v10, 0
	v_writelane_b32 v255, s7, 11
	v_cmp_lt_u32_e64 s[6:7], s4, v9
	s_movk_i32 s4, 0xffc0
	v_add_u32_e32 v207, v7, v114
; __device__ __forceinline__ void gdn_prep_unit(LAS unsigned char* lds, unsigned char* ws, const float* conv_w, const float* a_log, const float* dt_bias,
;                                               int l, int Tp, int ci, int h, int nci, int nh, unsigned& pre_ba, int tid, int wave, int lane) {
;     ...
;         const int sub = tid & 15, ch0 = sub * 8;
; #pragma unroll 6
;         for (int rnd = 0; rnd < 6; ++rnd) {
;             const int it = rnd * 32 + (tid >> 4), mat = it >> 6, c = it & 63;
;             const int chan = mat * 1024 + h * 128 + ch0;
;             const bf16* px = PROJ + (size_t)(row0 + c) * LDP + C_GQKV + chan;
;             const v4u zz = {0u, 0u, 0u, 0u};
;             const v4u x1 = *(const v4u*)px;
;             const v4u x0 = (c == 0 && first) ? zz : *(const v4u*)(px - LDP);
;             const v4u x2 = (c == 63 && last) ? zz : *(const v4u*)(px + LDP);
;             const float* cw = conv_w + (size_t)l * 3 * 3072 + chan;
;             const f32x4 w0a = *(const f32x4*)cw, w0b = *(const f32x4*)(cw + 4), w1a = *(const f32x4*)(cw + 3072), w1b = *(const f32x4*)(cw + 3072 + 4), w2a = *(const f32x4*)(cw + 6144), w2b = *(const f32x4*)(cw + 6144 + 4);
;             const float w0[8] = {w0a.x, w0a.y, w0a.z, w0a.w, w0b.x, w0b.y, w0b.z, w0b.w}, w1[8] = {w1a.x, w1a.y, w1a.z, w1a.w, w1b.x, w1b.y, w1b.z, w1b.w}, w2[8] = {w2a.x, w2a.y, w2a.z, w2a.w, w2b.x, w2b.y, w2b.z, w2b.w};
;             const float a0[8] = {bflo(x0.x), bfhi(x0.x), bflo(x0.y), bfhi(x0.y), bflo(x0.z), bfhi(x0.z), bflo(x0.w), bfhi(x0.w)};
;             const float a1[8] = {bflo(x1.x), bfhi(x1.x), bflo(x1.y), bfhi(x1.y), bflo(x1.z), bfhi(x1.z), bflo(x1.w), bfhi(x1.w)};
;             const float a2[8] = {bflo(x2.x), bfhi(x2.x), bflo(x2.y), bfhi(x2.y), bflo(x2.z), bfhi(x2.z), bflo(x2.w), bfhi(x2.w)};
;             float y[8]; float ss = 0.f;
; #pragma unroll
;             for (int e = 0; e < 8; ++e) { const float a = a0[e] * w0[e] + a1[e] * w1[e] + a2[e] * w2[e]; y[e] = a * __builtin_amdgcn_rcpf(1.0f + __expf(-a)); ss += y[e] * y[e]; }
;             if (mat < 2) {
;                 ss += xshfl<1>(ss); ss += xshfl<2>(ss); ss += xshfl<4>(ss); ss += xshfl<8>(ss);
;                 float rs = __builtin_amdgcn_rsqf(ss + NORM_EPS); if (mat == 0) rs *= 0.08838834764831845f;
; #pragma unroll
;                 for (int e = 0; e < 8; ++e) y[e] *= rs;
;             }
;             if (mat == 0) {
	v_writelane_b32 v255, s6, 12
	s_nop 1
	v_writelane_b32 v255, s7, 13
	v_cmp_gt_u32_e64 s[6:7], s4, v9
	s_nop 1
	v_writelane_b32 v255, s6, 14
	s_nop 1
	v_writelane_b32 v255, s7, 15
	v_cmp_ne_u32_e64 s[6:7], 1, v14
	v_lshlrev_b32_e32 v14, 4, v111
	v_and_b32_e32 v64, 0x1f0, v14
	v_or_b32_e32 v66, 0x200, v14
	v_lshrrev_b32_e32 v14, 3, v13
	v_lshlrev_b32_e32 v13, 4, v13
	v_and_b32_e32 v70, 0x1f0, v13
	v_or_b32_e32 v72, 0x200, v13
	v_add_u32_e32 v13, 0x60, v9
	v_writelane_b32 v255, s6, 16
	v_and_b32_e32 v125, 63, v13
	v_and_or_b32 v14, v14, 4, v11
	v_writelane_b32 v255, s7, 17
	v_cmp_eq_u32_e64 s[6:7], 0, v125
	v_lshl_or_b32 v68, v14, 11, v12
	v_ashrrev_i32_e32 v14, 6, v13
	v_writelane_b32 v255, s6, 18
	v_xor_b32_e32 v15, 63, v13
	v_lshrrev_b32_e32 v16, 3, v13
	v_writelane_b32 v255, s7, 19
	v_cmp_eq_u32_e64 s[6:7], 63, v125
	v_lshl_add_u32 v129, v15, 2, s5
	v_lshl_or_b32 v126, v14, 10, v8
	v_writelane_b32 v255, s6, 20
	v_and_or_b32 v16, v16, 4, v11
	v_lshl_or_b32 v74, v16, 11, v12
	v_writelane_b32 v255, s7, 21
	v_cmp_gt_i32_e64 s[6:7], 2, v14
	v_mul_u32_u24_e32 v127, 0x110, v125
	v_lshl_add_u32 v128, v125, 2, s8
	v_writelane_b32 v255, s6, 22
	s_nop 1
	v_writelane_b32 v255, s7, 23
	v_cmp_gt_u32_e64 s[6:7], 64, v13
	s_nop 1
	v_writelane_b32 v255, s6, 24
	s_nop 1
	v_writelane_b32 v255, s7, 25
	v_cmp_lt_u32_e64 s[6:7], 63, v13
	v_lshlrev_b32_e32 v13, 4, v13
	v_and_b32_e32 v76, 0x1f0, v13
	v_or_b32_e32 v78, 0x200, v13
	v_lshrrev_b32_e32 v13, 3, v15
	v_and_or_b32 v13, v13, 4, v11
	v_writelane_b32 v255, s6, 26
	v_lshl_or_b32 v80, v13, 11, v12
	v_lshlrev_b32_e32 v13, 4, v15
	v_writelane_b32 v255, s7, 27
	v_cmp_ne_u32_e64 s[6:7], 1, v14
	v_and_b32_e32 v82, 0x1f0, v13
	v_or_b32_e32 v84, 0x200, v13
	v_add_u32_e32 v13, 0x80, v9
	v_writelane_b32 v255, s6, 28
	v_ashrrev_i32_e32 v15, 6, v13
	v_add_u32_e32 v9, 0xa0, v9
	v_writelane_b32 v255, s7, 29
	v_cmp_gt_i32_e64 s[6:7], 2, v15
	v_and_b32_e32 v132, 63, v9
	v_lshl_or_b32 v130, v15, 10, v8
	v_writelane_b32 v255, s6, 30
	v_lshlrev_b32_e32 v14, 1, v125
	v_xad_u32 v14, v14, v10, 0
	v_writelane_b32 v255, s7, 31
	v_cmp_gt_u32_e64 s[6:7], 64, v13
	v_mul_u32_u24_e32 v135, 0x110, v132
	v_lshl_add_u32 v136, v132, 2, s8
	v_writelane_b32 v255, s6, 32
	v_add_u32_e32 v208, v14, v114
	s_nop 0
	v_writelane_b32 v255, s7, 33
	v_cmp_lt_u32_e64 s[6:7], 63, v13
	v_xor_b32_e32 v13, 63, v13
	v_lshl_add_u32 v131, v13, 2, s5
	v_writelane_b32 v255, s6, 34
	s_nop 1
	v_writelane_b32 v255, s7, 35
	v_cmp_ne_u32_e64 s[6:7], 1, v15
	v_lshrrev_b32_e32 v15, 3, v13
	v_lshlrev_b32_e32 v13, 4, v13
	v_writelane_b32 v255, s6, 36
	v_and_b32_e32 v88, 0x1f0, v13
	v_or_b32_e32 v90, 0x200, v13
	v_writelane_b32 v255, s7, 37
	v_cmp_eq_u32_e64 s[6:7], 0, v132
	v_ashrrev_i32_e32 v13, 6, v9
	v_lshl_or_b32 v133, v13, 10, v8
	v_writelane_b32 v255, s6, 38
	v_lshlrev_b32_e32 v8, 1, v132
	v_xad_u32 v8, v8, v10, 0
	v_writelane_b32 v255, s7, 39
	v_cmp_eq_u32_e64 s[6:7], 63, v132
	v_xor_b32_e32 v10, 63, v9
	v_lshl_add_u32 v137, v10, 2, s5
	v_writelane_b32 v255, s6, 40
	s_cselect_b64 s[4:5], -1, 0
	s_cmp_gt_i32 s14, 3
	v_writelane_b32 v255, s7, 41
	v_cmp_gt_i32_e64 s[6:7], 2, v13
	v_and_or_b32 v15, v15, 4, v11
	v_lshl_or_b32 v86, v15, 11, v12
	v_writelane_b32 v255, s6, 42
	v_or_b32_e32 v15, 32, v5
	v_add_u32_e32 v209, v8, v114
	v_writelane_b32 v255, s7, 43
	v_cmp_gt_u32_e64 s[6:7], 64, v9
	s_nop 1
	v_writelane_b32 v255, s6, 44
	s_nop 1
	v_writelane_b32 v255, s7, 45
	v_cmp_lt_u32_e64 s[6:7], 63, v9
	s_nop 1
	v_writelane_b32 v255, s6, 46
	s_nop 1
	v_writelane_b32 v255, s7, 47
	v_cmp_ne_u32_e64 s[6:7], 1, v13
	v_lshrrev_b32_e32 v13, 3, v9
	v_lshlrev_b32_e32 v9, 4, v9
	v_writelane_b32 v255, s6, 48
	v_and_b32_e32 v94, 0x1f0, v9
	v_or_b32_e32 v96, 0x200, v9
	v_writelane_b32 v255, s7, 49
	v_writelane_b32 v255, s4, 50
	v_lshrrev_b32_e32 v9, 3, v10
	v_and_or_b32 v13, v13, 4, v11
	v_writelane_b32 v255, s5, 51
	s_cselect_b64 s[4:5], -1, 0
	v_writelane_b32 v255, s4, 52
	v_and_or_b32 v9, v9, 4, v11
	v_lshl_or_b32 v92, v13, 11, v12
	v_writelane_b32 v255, s5, 53
	s_ashr_i32 s4, s14, 1
	s_and_b32 s5, s14, 1
	s_mul_i32 s6, s4, 0x4400
	s_add_i32 s6, s9, s6
	s_mul_i32 s7, s5, 0x2200
	s_add_i32 s6, s6, s7
	s_lshl_b32 s7, s5, 7
	v_lshl_or_b32 v11, s5, 5, v106
	s_add_i32 s53, s6, s7
	v_lshl_or_b32 v98, v9, 11, v12
	s_cmp_lt_u32 s14, 2
	v_lshlrev_b32_e32 v12, 1, v11
	s_cselect_b64 vcc, -1, 0
	v_xor_b32_e32 v13, 0x7e, v12
	v_cndmask_b32_e32 v12, v13, v12, vcc
	v_xor_b32_e32 v13, 31, v106
	v_cndmask_b32_e32 v13, v13, v15, vcc
	v_cmp_eq_u32_e32 vcc, 0, v106
	s_mul_i32 s6, s4, 0x4800
	s_add_i32 s7, 0, 0x1a000
	v_cndmask_b32_e64 v155, 0, 1.0, vcc
	v_cmp_eq_u32_e32 vcc, 1, v106
	s_add_i32 s6, s7, s6
	s_mul_i32 s10, s5, 0x1200
	v_cndmask_b32_e64 v156, 0, 1.0, vcc
	v_cmp_eq_u32_e32 vcc, 2, v106
	s_add_i32 s10, s6, s10
	v_add_u32_e32 v146, s10, v12
; #define LAS __attribute__((address_space(3)))
; __device__ __forceinline__ bf16 f2bf1(float f) { return (bf16)(cvtpk(f, 0.f) & 0xffffu); }
; __device__ __forceinline__ void gdn_prep_unit(LAS unsigned char* lds, unsigned char* ws, const float* conv_w, const float* a_log, const float* dt_bias,
;                                               int l, int Tp, int ci, int h, int nci, int nh, unsigned& pre_ba, int tid, int wave, int lane) {
;     ...
;         const int d = wave >> 1, blk = wave & 1, j = lane & 31, jp = 32 * blk + j;
;         const LAS float* Lm = (const LAS float*)(lds + D1_LM + d * 17408) + (32 * blk) * (LMP / 4) + 32 * blk;
;         const float bj = BETA[d * 64 + jp], bgj = bj * __expf(GC[d * 64 + jp]);
;         const int col = d ? 63 - jp : jp;
;         LAS unsigned char* tb = lds + D1_TB + d * 18432 + (32 * blk) * TBP + col * 2;
;         LAS float* ts = (LAS float*)(lds + D1_TS + (d * 2 + blk) * 4352) + j;
;         if (lane < 32) {
;             float t[32];
; #pragma unroll
;             for (int r = 0; r < 32; ++r) {
;                 float a4[4] = {(r == j) ? 1.f : 0.f, 0.f, 0.f, 0.f};
; #pragma unroll
;                 for (int m4 = 0; m4 < (r + 3) / 4; ++m4) { const f32x4 lv = *(const LAS f32x4*)(Lm + r * (LMP / 4) + m4 * 4);
; #pragma unroll
;                     for (int e = 0; e < 4; ++e) if (m4 * 4 + e < r) a4[e] -= lv[e] * t[m4 * 4 + e]; }
;                 const float a = (a4[0] + a4[1]) + (a4[2] + a4[3]);
;                 t[r] = a; ts[r * 33] = a;
;                 *(LAS bf16*)(tb + r * TBP) = f2bf1(a * bj); *(LAS bf16*)(tb + 9216 + r * TBP) = f2bf1(a * bgj);
;             }
;         } else if (blk == 0) {
;             const int colz = d ? 63 - (32 + j) : 32 + j; LAS unsigned char* tz = lds + D1_TB + d * 18432 + colz * 2;
; #pragma unroll
;             for (int r = 0; r < 32; ++r) { *(LAS bf16*)(tz + r * TBP) = (bf16)0; *(LAS bf16*)(tz + 9216 + r * TBP) = (bf16)0; }
;         }
	v_cndmask_b32_e64 v157, 0, 1.0, vcc
	v_cmp_eq_u32_e32 vcc, 3, v106
	s_mul_i32 s10, s14, 0x1100
	s_add_i32 s10, s10, 0
	v_cndmask_b32_e64 v158, 0, 1.0, vcc
	v_cmp_eq_u32_e32 vcc, 4, v106
	v_lshlrev_b32_e32 v12, 2, v106
	s_cmp_eq_u32 s5, 0
	v_cndmask_b32_e64 v159, 0, 1.0, vcc
	v_cmp_eq_u32_e32 vcc, 5, v106
	v_add_u32_e32 v147, s10, v12
	s_cselect_b64 s[10:11], -1, 0
	v_cndmask_b32_e64 v160, 0, 1.0, vcc
	v_cmp_eq_u32_e32 vcc, 6, v106
	v_lshlrev_b32_e32 v9, 4, v10
	v_lshrrev_b32_e32 v10, 3, v6
	v_cndmask_b32_e64 v161, 0, 1.0, vcc
	v_cmp_eq_u32_e32 vcc, 7, v106
	v_writelane_b32 v255, s10, 54
	s_cmp_lt_u32 s14, 36
	v_cndmask_b32_e64 v162, 0, 1.0, vcc
	v_cmp_eq_u32_e32 vcc, 8, v106
	v_and_b32_e32 v10, 4, v10
	v_writelane_b32 v255, s11, 55
	v_cndmask_b32_e64 v163, 0, 1.0, vcc
	v_cmp_eq_u32_e32 vcc, 9, v106
	s_cselect_b64 s[10:11], -1, 0
	s_lshl_b32 s5, s14, 4
	v_cndmask_b32_e64 v164, 0, 1.0, vcc
	v_cmp_eq_u32_e32 vcc, 10, v106
	v_writelane_b32 v255, s10, 56
	v_and_or_b32 v149, s5, 48, v10
	v_cndmask_b32_e64 v165, 0, 1.0, vcc
	v_cmp_eq_u32_e32 vcc, 11, v106
	v_writelane_b32 v255, s11, 57
	v_lshlrev_b32_e32 v10, 1, v149
	v_cndmask_b32_e64 v166, 0, 1.0, vcc
	v_cmp_eq_u32_e32 vcc, 12, v106
	s_lshl_b32 s10, s14, 10
	v_lshl_add_u32 v148, v13, 1, s6
	v_cndmask_b32_e64 v167, 0, 1.0, vcc
	v_cmp_eq_u32_e32 vcc, 13, v106
	s_add_i32 s6, s14, -4
	v_xor_b32_e32 v150, 0x78, v10
	v_cndmask_b32_e64 v168, 0, 1.0, vcc
	v_cmp_eq_u32_e32 vcc, 14, v106
	v_xor_b32_e32 v151, 0x68, v10
	v_or_b32_e32 v152, 16, v10
	v_cndmask_b32_e64 v169, 0, 1.0, vcc
	v_cmp_eq_u32_e32 vcc, 15, v106
	s_and_b32 s10, s10, 0xc00
	v_lshlrev_b32_e32 v10, 2, v11
	v_cndmask_b32_e64 v170, 0, 1.0, vcc
	v_cmp_eq_u32_e32 vcc, 16, v106
	v_and_b32_e32 v100, 0x1f0, v9
	v_or_b32_e32 v102, 0x200, v9
	v_cndmask_b32_e64 v171, 0, 1.0, vcc
	v_cmp_eq_u32_e32 vcc, 17, v106
	v_lshrrev_b32_e32 v9, 5, v5
	v_lshl_or_b32 v10, s4, 8, v10
	v_cndmask_b32_e64 v172, 0, 1.0, vcc
	v_cmp_eq_u32_e32 vcc, 18, v106
	s_cmp_lt_i32 s14, 2
	s_mul_i32 s4, s14, 0x4400
	v_cndmask_b32_e64 v173, 0, 1.0, vcc
	v_cmp_eq_u32_e32 vcc, 19, v106
	s_mul_i32 s11, s14, 0x2200
	v_lshlrev_b32_e32 v144, 2, v9
	v_cndmask_b32_e64 v174, 0, 1.0, vcc
	v_cmp_eq_u32_e32 vcc, 20, v106
	v_add_u32_e32 v153, s3, v10
	v_add_u32_e32 v154, s8, v10
	v_cndmask_b32_e64 v175, 0, 1.0, vcc
	v_cmp_eq_u32_e32 vcc, 21, v106
	s_cselect_b64 s[12:13], -1, 0
	s_add_i32 s4, s9, s4
	v_cndmask_b32_e64 v176, 0, 1.0, vcc
	v_cmp_eq_u32_e32 vcc, 22, v106
	v_mul_u32_u24_e32 v10, 0x110, v15
	s_add_i32 s11, s11, 0
	v_cndmask_b32_e64 v177, 0, 1.0, vcc
	v_cmp_eq_u32_e32 vcc, 23, v106
	v_add_u32_e32 v11, s11, v12
	v_add3_u32 v187, s4, v10, v144
	v_cndmask_b32_e64 v178, 0, 1.0, vcc
	v_cmp_eq_u32_e32 vcc, 24, v106
	v_mov_b32_e32 v13, s11
	s_movk_i32 s4, 0x84
	v_cndmask_b32_e64 v179, 0, 1.0, vcc
	v_cmp_eq_u32_e32 vcc, 25, v106
	v_lshl_or_b32 v12, s14, 8, v12
	v_mad_u32_u24 v13, v106, s4, v13
	v_cndmask_b32_e64 v180, 0, 1.0, vcc
	v_cmp_eq_u32_e32 vcc, 26, v106
	v_add_u32_e32 v188, s3, v12
	v_add_u32_e32 v189, s8, v12
	v_cndmask_b32_e64 v181, 0, 1.0, vcc
	v_cmp_eq_u32_e32 vcc, 27, v106
	s_cmp_eq_u32 s14, 0
	s_mul_i32 s4, s14, 0x4800
	v_cndmask_b32_e64 v182, 0, 1.0, vcc
	v_cmp_eq_u32_e32 vcc, 28, v106
	v_lshlrev_b32_e32 v12, 1, v106
	v_xor_b32_e32 v15, 0x7e, v12
	v_cndmask_b32_e64 v183, 0, 1.0, vcc
	v_cmp_eq_u32_e32 vcc, 29, v106
	v_lshrrev_b32_e32 v6, 1, v6
	v_and_b32_e32 v190, 16, v6
	v_cndmask_b32_e64 v184, 0, 1.0, vcc
	v_cmp_eq_u32_e32 vcc, 30, v106
	s_movk_i32 s3, 0x90
	v_lshlrev_b32_e32 v142, 4, v9
	v_cndmask_b32_e64 v185, 0, 1.0, vcc
	v_cmp_eq_u32_e32 vcc, 31, v106
	v_mul_u32_u24_e32 v10, 0x84, v9
	v_mul_u32_u24_e32 v9, 0x240, v9
	v_cndmask_b32_e64 v186, 0, 1.0, vcc
	s_cselect_b64 vcc, -1, 0
	s_add_i32 s4, s7, s4
	v_cndmask_b32_e32 v12, v15, v12, vcc
	s_cmp_lt_i32 s14, 32
	v_add_u32_e32 v12, s4, v12
	s_cselect_b64 s[72:73], -1, 0
	s_and_b32 s4, s5, 0x60
	v_or_b32_e32 v6, s4, v106
	v_mad_u32_u24 v15, v6, s3, 0
	v_lshlrev_b32_e32 v6, 1, v6
	s_lshl_b32 s4, s14, 3
	v_add_u32_e32 v192, 0x8800, v15
	v_and_b32_e32 v193, 0x70, v6
	v_and_or_b32 v6, s4, 32, v106
	v_mov_b32_e32 v15, s7
	v_mad_u32_u24 v194, v6, s3, v15
	v_cvt_f32_u32_e32 v6, s35
	s_sub_i32 s4, 0, s35
	s_lshr_b32 s3, s6, 2
	v_add_u32_e32 v143, 0, v142
	v_rcp_iflag_f32_e32 v6, v6
	s_movk_i32 s8, 0x90
	v_or_b32_e32 v195, 32, v190
	v_or_b32_e32 v200, 64, v190
	v_mul_f32_e32 v6, 0x4f7ffffe, v6
	v_cvt_u32_f32_e32 v6, v6
	v_or_b32_e32 v201, 0x60, v190
	s_bfe_u32 s15, s14, 0x10002
	v_or_b32_e32 v203, s10, v145
	v_readfirstlane_b32 s5, v6
	s_mul_i32 s4, s4, s5
	s_mul_hi_u32 s4, s5, s4
	s_add_i32 s10, s5, s4
	s_add_i32 s9, s14, -8
	v_writelane_b32 v255, s3, 58
	s_lshl_b32 s11, s14, 5
	v_add_u32_e32 v204, v11, v10
	v_add_u32_e32 v205, v13, v142
	v_add_u32_e32 v206, v12, v9
	s_mov_b32 s6, s2
	s_branch .LBB0_320

; #define LAS __attribute__((address_space(3)))
; __device__ __forceinline__ int crow(int r, int hi) { return (r & 3) + 8 * (r >> 2) + 4 * hi; }
; template <int MODE, bool FIXED>
; __device__ __forceinline__ void attn_unit(LAS unsigned char* lds, unsigned char* ws, const AttnParams& P, int l, int Tp, int sq, int h, int qb, int part, int np, int pslot, int tid, int wave, int lane) {
;     ...
;     LAS float* ost = (LAS float*)(lds + AT_OST + wave * AT_OST_W);
;     {
;         if (hi == 0) li_l[r32] = l_reg;
;         asm volatile("s_waitcnt lgkmcnt(0)" ::: "memory");
; #pragma unroll
;         for (int r4 = 0; r4 < 4; ++r4) { float rl[4];
; #pragma unroll
;             for (int e = 0; e < 4; ++e) rl[e] = __builtin_amdgcn_rcpf(li_l[crow(4 * r4 + e, hi)]);
; #pragma unroll
;             for (int d = 0; d < 4; ++d) { f32x4 pk = {0.f, 0.f, 0.f, 0.f}; if (MODE == 1) pk = *(const f32x4*)(park + (d * 4 + r4) * 256);
; #pragma unroll
;                 for (int e = 0; e < 4; ++e) { float v = o[d][4 * r4 + e] * rl[e]; if (MODE == 1) v = pk[e] - lam * v;
;                     ost[crow(4 * r4 + e, hi) * 132 + d * 32 + r32] = v; } } }
;     }
;     asm volatile("s_waitcnt lgkmcnt(0)" ::: "memory");
.LBB0_858:
	s_waitcnt lgkmcnt(0)
	s_barrier
	v_readlane_b32 s6, v254, 26
	v_readlane_b32 s7, v254, 27
	s_and_saveexec_b64 s[6:7], s[4:5]
	ds_write_b32 v171, v209
	s_or_b64 exec, exec, s[6:7]
	s_waitcnt lgkmcnt(0)
	ds_read_b128 v[6:9], v174
	s_mul_i32 s4, s31, 0x4200
	s_add_i32 s4, s4, 0
	v_lshlrev_b32_e32 v2, 2, v195
	s_add_i32 s44, s44, s12
	s_waitcnt lgkmcnt(0)
	v_rcp_f32_e32 v3, v6
	v_rcp_f32_e32 v5, v7
	v_rcp_f32_e32 v6, v8
	v_rcp_f32_e32 v7, v9
	v_mul_u32_u24_e32 v9, 0x840, v194
	v_mul_f32_e32 v8, v66, v3
	v_add3_u32 v2, s4, v2, v9
	v_mul_f32_e32 v12, v50, v3
	v_mul_f32_e32 v9, v67, v5
	ds_write2_b32 v2, v8, v12 offset1:32
	v_mul_f32_e32 v8, v51, v5
	v_mul_f32_e32 v10, v68, v6
	ds_write2_b32 v2, v9, v8 offset0:132 offset1:164
	v_mul_f32_e32 v8, v52, v6
	v_add_u32_e32 v9, 0x400, v2
	v_mul_f32_e32 v11, v69, v7
	ds_write2_b32 v9, v10, v8 offset0:8 offset1:40
	v_mul_f32_e32 v8, v53, v7
	ds_write2_b32 v9, v11, v8 offset0:140 offset1:172
	v_mul_f32_e32 v8, v34, v3
	v_mul_f32_e32 v3, v18, v3
	v_mul_f32_e32 v10, v35, v5
	ds_write2_b32 v2, v8, v3 offset0:64 offset1:96
	v_mul_f32_e32 v3, v19, v5
	v_mul_f32_e32 v11, v36, v6
	ds_write2_b32 v2, v10, v3 offset0:196 offset1:228
	v_mul_f32_e32 v3, v20, v6
	v_mul_f32_e32 v12, v37, v7
	ds_write2_b32 v9, v11, v3 offset0:72 offset1:104
	v_mul_f32_e32 v3, v21, v7
	ds_write2_b32 v9, v12, v3 offset0:204 offset1:236
	ds_read_b128 v[6:9], v174 offset:32
	v_add_u32_e32 v13, 0x1000, v2
	v_mov_b64_e32 v[50:51], s[50:51]
	s_movk_i32 s3, 0x2000
	s_waitcnt lgkmcnt(0)
	v_rcp_f32_e32 v3, v6
	v_rcp_f32_e32 v5, v7
	v_rcp_f32_e32 v6, v8
	v_rcp_f32_e32 v7, v9
	v_mul_f32_e32 v8, v70, v3
	v_mul_f32_e32 v12, v54, v3
	v_mul_f32_e32 v9, v71, v5
	ds_write2_b32 v13, v8, v12 offset0:32 offset1:64
	v_mul_f32_e32 v8, v55, v5
	v_mul_f32_e32 v10, v72, v6
	ds_write2_b32 v13, v9, v8 offset0:164 offset1:196
	v_mul_f32_e32 v8, v56, v6
	v_add_u32_e32 v9, 0x1400, v2
	v_mul_f32_e32 v11, v73, v7
	ds_write2_b32 v9, v10, v8 offset0:40 offset1:72
	v_mul_f32_e32 v8, v57, v7
	ds_write2_b32 v9, v11, v8 offset0:172 offset1:204
	v_mul_f32_e32 v8, v38, v3
	v_mul_f32_e32 v3, v22, v3
	v_mul_f32_e32 v10, v39, v5
	ds_write2_b32 v13, v8, v3 offset0:96 offset1:128
	v_mul_f32_e32 v3, v23, v5
	v_add_u32_e32 v5, 0x1200, v2
	v_mul_f32_e32 v11, v40, v6
	ds_write2_b32 v5, v10, v3 offset0:100 offset1:132
	v_mul_f32_e32 v3, v24, v6
	v_mul_f32_e32 v12, v41, v7
	ds_write2_b32 v9, v11, v3 offset0:104 offset1:136
	v_mul_f32_e32 v3, v25, v7
	v_add_u32_e32 v5, 0x1600, v2
	ds_write2_b32 v5, v12, v3 offset0:108 offset1:140
	ds_read_b128 v[6:9], v174 offset:64
	v_add_u32_e32 v13, 0x2000, v2
	v_mov_b32_e32 v73, v4
	s_waitcnt lgkmcnt(0)
	v_rcp_f32_e32 v3, v6
	v_rcp_f32_e32 v5, v7
	v_rcp_f32_e32 v6, v8
	v_rcp_f32_e32 v7, v9
	v_mul_f32_e32 v8, v74, v3
	v_mul_f32_e32 v12, v58, v3
	v_mul_f32_e32 v9, v75, v5
	ds_write2_b32 v13, v8, v12 offset0:64 offset1:96
	v_mul_f32_e32 v8, v59, v5
	v_mul_f32_e32 v10, v76, v6
	ds_write2_b32 v13, v9, v8 offset0:196 offset1:228
	v_mul_f32_e32 v8, v60, v6
	v_add_u32_e32 v9, 0x2400, v2
	v_mul_f32_e32 v11, v77, v7
	ds_write2_b32 v9, v10, v8 offset0:72 offset1:104
	v_mul_f32_e32 v8, v61, v7
	ds_write2_b32 v9, v11, v8 offset0:204 offset1:236
	v_mul_f32_e32 v8, v42, v3
	v_mul_f32_e32 v3, v26, v3
	v_mul_f32_e32 v10, v43, v5
	ds_write2_b32 v13, v8, v3 offset0:128 offset1:160
	v_mul_f32_e32 v3, v27, v5
	v_mul_f32_e32 v11, v44, v6
	ds_write2_b32 v9, v10, v3 offset0:4 offset1:36
	v_mul_f32_e32 v3, v28, v6
	v_mul_f32_e32 v12, v45, v7
	ds_write2_b32 v9, v11, v3 offset0:136 offset1:168
	v_mul_f32_e32 v3, v29, v7
	v_add_u32_e32 v5, 0x2800, v2
	ds_write2_b32 v5, v12, v3 offset0:12 offset1:44
	ds_read_b128 v[6:9], v174 offset:96
	v_add_u32_e32 v13, 0x3000, v2
	s_waitcnt lgkmcnt(0)
	v_rcp_f32_e32 v3, v6
	v_rcp_f32_e32 v5, v7
	v_rcp_f32_e32 v6, v8
	v_rcp_f32_e32 v7, v9
	v_mul_f32_e32 v8, v78, v3
	v_mul_f32_e32 v12, v62, v3
	v_mul_f32_e32 v9, v79, v5
	ds_write2_b32 v13, v8, v12 offset0:96 offset1:128
	v_mul_f32_e32 v8, v63, v5
	v_add_u32_e32 v12, 0x3200, v2
	v_mul_f32_e32 v10, v80, v6
	ds_write2_b32 v12, v9, v8 offset0:100 offset1:132
	v_mul_f32_e32 v8, v64, v6
	v_add_u32_e32 v9, 0x3400, v2
	v_mul_f32_e32 v11, v81, v7
	ds_write2_b32 v9, v10, v8 offset0:104 offset1:136
	v_mul_f32_e32 v8, v65, v7
	v_add_u32_e32 v10, 0x3600, v2
	ds_write2_b32 v10, v11, v8 offset0:108 offset1:140
	v_mul_f32_e32 v8, v46, v3
	v_mul_f32_e32 v3, v30, v3
	v_mul_f32_e32 v10, v47, v5
	ds_write2_b32 v13, v8, v3 offset0:160 offset1:192
	v_mul_f32_e32 v3, v31, v5
	v_mul_f32_e32 v11, v48, v6
	ds_write2_b32 v9, v10, v3 offset0:36 offset1:68
	v_mul_f32_e32 v3, v32, v6
	v_mul_f32_e32 v12, v49, v7
	ds_write2_b32 v9, v11, v3 offset0:168 offset1:200
	v_mul_f32_e32 v3, v33, v7
	v_add_u32_e32 v2, 0x3800, v2
	v_lshlrev_b32_e32 v5, 6, v193
	ds_write2_b32 v2, v12, v3 offset0:44 offset1:76
	v_lshrrev_b32_e32 v2, 1, v193
	v_and_b32_e32 v5, 64, v5
	v_mul_u32_u24_e32 v3, 0x210, v2
	v_lshlrev_b32_e32 v6, 2, v5
	v_or_b32_e32 v2, s44, v2
	v_add3_u32 v3, s4, v3, v6
	v_mad_i64_i32 v[50:51], s[4:5], v2, s70, v[50:51]
	v_lshl_add_u64 v[50:51], v[50:51], 0, s[60:61]
	v_lshlrev_b32_e32 v72, 1, v5
	s_waitcnt lgkmcnt(0)
; __device__ __forceinline__ float bflo(unsigned w) { return __uint_as_float(w << 16); }
; __device__ __forceinline__ float bfhi(unsigned w) { return __uint_as_float(w & 0xffff0000u); }
; #define LAS __attribute__((address_space(3)))
; __device__ __forceinline__ float bflo(unsigned w) { return __uint_as_float(w << 16); }
; __device__ __forceinline__ float bfhi(unsigned w) { return __uint_as_float(w & 0xffff0000u); }
; __device__ __forceinline__ unsigned cvtpk(float lo, float hi) { const f32x2_t v = {lo, hi}; const bf16x2_t b = __builtin_convertvector(v, bf16x2_t); return __builtin_bit_cast(unsigned, b); }
; template <int MODE, bool FIXED>
; __device__ __forceinline__ void attn_unit(LAS unsigned char* lds, unsigned char* ws, const AttnParams& P, int l, int Tp, int sq, int h, int qb, int part, int np, int pslot, int tid, int wave, int lane) {
;     ...
;     {
;         const int row = lane >> 1, half = lane & 1;
;         const LAS f32x4* src = (const LAS f32x4*)(ost + row * 132 + half * 64);
;         float v[64];
; #pragma unroll
;         for (int k = 0; k < 16; ++k) { const f32x4 t = src[k]; v[4 * k] = t.x; v[4 * k + 1] = t.y; v[4 * k + 2] = t.z; v[4 * k + 3] = t.w; }
;         const size_t grow = (size_t)(seq0 + q0 + wave * 32 + row);
;         float rs = 1.f;
;         if (MODE == 1) { float ss = 0.f;
; #pragma unroll
;             for (int e = 0; e < 64; ++e) ss += v[e] * v[e];
;             ss += xshfl<1>(ss); rs = (1.0f / sqrtf(ss * (1.0f / 128.0f) + NORM_EPS)) * (1.0f - lin); }
;         const v4u* zp = (const v4u*)(PROJ + grow * LDP + zcol + half * 64);
;         bf16* yb = (bf16*)(ws + WS_Y + (MODE ? 2 : 1) * SZ_Y1) + grow * 1024 + h * 128 + half * 64;
; #pragma unroll
;         for (int k = 0; k < 8; ++k) { const v4u zw = zp[k];
;             const float z[8] = {bflo(zw.x), bfhi(zw.x), bflo(zw.y), bfhi(zw.y), bflo(zw.z), bfhi(zw.z), bflo(zw.w), bfhi(zw.w)};
;             float y[8];
; #pragma unroll
;             for (int e = 0; e < 8; ++e) { float g = 1.f; if (MODE == 1) g = P.norm_gain[half * 64 + 8 * k + e]; y[e] = v[8 * k + e] * rs * g * z[e]; }
;             v4u w; w.x = cvtpk(y[0], y[1]); w.y = cvtpk(y[2], y[3]); w.z = cvtpk(y[4], y[5]); w.w = cvtpk(y[6], y[7]);
;             *(v4u*)(yb + 8 * k) = w; }
;     }
;     asm volatile("s_waitcnt lgkmcnt(0)" ::: "memory"); __builtin_amdgcn_s_barrier(); asm volatile("" ::: "memory");
	v_lshl_add_u64 v[74:75], v[50:51], 0, v[72:73]
	s_mov_b64 s[4:5], 0x2c00
	ds_read_b128 v[38:41], v3
	ds_read_b128 v[42:45], v3 offset:16
	ds_read_b128 v[46:49], v3 offset:32
	ds_read_b128 v[52:55], v3 offset:48
	ds_read_b128 v[56:59], v3 offset:64
	ds_read_b128 v[60:63], v3 offset:80
	ds_read_b128 v[64:67], v3 offset:96
	ds_read_b128 v[68:71], v3 offset:112
	ds_read_b128 v[34:37], v3 offset:128
	ds_read_b128 v[30:33], v3 offset:144
	ds_read_b128 v[26:29], v3 offset:160
	ds_read_b128 v[22:25], v3 offset:176
	ds_read_b128 v[18:21], v3 offset:192
	ds_read_b128 v[14:17], v3 offset:208
	ds_read_b128 v[10:13], v3 offset:224
	ds_read_b128 v[6:9], v3 offset:240
	v_ashrrev_i32_e32 v3, 31, v2
	v_lshl_add_u64 v[50:51], v[74:75], 0, s[4:5]
	v_readlane_b32 s4, v252, 34
	v_lshlrev_b64 v[2:3], 11, v[2:3]
	v_readlane_b32 s5, v252, 35
	s_nop 1
	v_lshl_add_u64 v[2:3], s[4:5], 0, v[2:3]
	v_lshl_add_u64 v[2:3], v[2:3], 0, s[60:61]
	v_lshl_add_u64 v[2:3], v[2:3], 0, v[72:73]
	v_add_co_u32_e32 v72, vcc, s3, v74
	s_nop 1
	v_addc_co_u32_e32 v73, vcc, 0, v75, vcc
	global_load_dwordx4 v[72:75], v[72:73], off offset:3072
	s_nop 0
	global_load_dwordx4 v[76:79], v[50:51], off offset:48
	global_load_dwordx4 v[80:83], v[50:51], off offset:32
	global_load_dwordx4 v[84:87], v[50:51], off offset:16
	s_waitcnt vmcnt(3)
	v_lshlrev_b32_e32 v88, 16, v72
	v_and_b32_e32 v89, 0xffff0000, v72
	v_lshlrev_b32_e32 v72, 16, v73
	v_and_b32_e32 v73, 0xffff0000, v73
	s_waitcnt lgkmcnt(14)
	v_pk_mul_f32 v[40:41], v[40:41], v[72:73]
	v_lshlrev_b32_e32 v72, 16, v74
	v_and_b32_e32 v73, 0xffff0000, v74
	v_pk_mul_f32 v[42:43], v[42:43], v[72:73]
	v_lshlrev_b32_e32 v72, 16, v75
	v_and_b32_e32 v73, 0xffff0000, v75
	v_pk_mul_f32 v[38:39], v[38:39], v[88:89]
	v_pk_mul_f32 v[44:45], v[44:45], v[72:73]
	v_cvt_pk_bf16_f32 v38, v38, v39
	v_cvt_pk_bf16_f32 v39, v40, v41
	v_cvt_pk_bf16_f32 v40, v42, v43
	v_cvt_pk_bf16_f32 v41, v44, v45
	global_store_dwordx4 v[2:3], v[38:41], off
	s_waitcnt vmcnt(1)
	v_lshlrev_b32_e32 v42, 16, v86
	v_and_b32_e32 v43, 0xffff0000, v86
	v_lshlrev_b32_e32 v38, 16, v84
	v_and_b32_e32 v39, 0xffff0000, v84
	v_lshlrev_b32_e32 v40, 16, v85
	v_and_b32_e32 v41, 0xffff0000, v85
	v_lshlrev_b32_e32 v44, 16, v87
	v_and_b32_e32 v45, 0xffff0000, v87
	s_waitcnt lgkmcnt(13)
	v_pk_mul_f32 v[38:39], v[46:47], v[38:39]
	v_pk_mul_f32 v[40:41], v[48:49], v[40:41]
	s_waitcnt lgkmcnt(12)
	v_pk_mul_f32 v[42:43], v[52:53], v[42:43]
	v_pk_mul_f32 v[44:45], v[54:55], v[44:45]
	v_cvt_pk_bf16_f32 v38, v38, v39
	v_cvt_pk_bf16_f32 v39, v40, v41
	v_cvt_pk_bf16_f32 v40, v42, v43
	v_cvt_pk_bf16_f32 v41, v44, v45
	global_store_dwordx4 v[2:3], v[38:41], off offset:16
	v_lshlrev_b32_e32 v42, 16, v82
	v_and_b32_e32 v43, 0xffff0000, v82
	v_lshlrev_b32_e32 v38, 16, v80
	v_and_b32_e32 v39, 0xffff0000, v80
	v_lshlrev_b32_e32 v40, 16, v81
	v_and_b32_e32 v41, 0xffff0000, v81
	v_lshlrev_b32_e32 v44, 16, v83
	v_and_b32_e32 v45, 0xffff0000, v83
	s_waitcnt lgkmcnt(11)
	v_pk_mul_f32 v[38:39], v[56:57], v[38:39]
	v_pk_mul_f32 v[40:41], v[58:59], v[40:41]
	s_waitcnt lgkmcnt(10)
	v_pk_mul_f32 v[42:43], v[60:61], v[42:43]
	v_pk_mul_f32 v[44:45], v[62:63], v[44:45]
	v_cvt_pk_bf16_f32 v38, v38, v39
	v_cvt_pk_bf16_f32 v39, v40, v41
	v_cvt_pk_bf16_f32 v40, v42, v43
	v_cvt_pk_bf16_f32 v41, v44, v45
	global_store_dwordx4 v[2:3], v[38:41], off offset:32
	v_lshlrev_b32_e32 v42, 16, v78
	v_and_b32_e32 v43, 0xffff0000, v78
	v_lshlrev_b32_e32 v38, 16, v76
	v_and_b32_e32 v39, 0xffff0000, v76
	v_lshlrev_b32_e32 v40, 16, v77
	v_and_b32_e32 v41, 0xffff0000, v77
	v_lshlrev_b32_e32 v44, 16, v79
	v_and_b32_e32 v45, 0xffff0000, v79
	s_waitcnt lgkmcnt(9)
	v_pk_mul_f32 v[38:39], v[64:65], v[38:39]
	v_pk_mul_f32 v[40:41], v[66:67], v[40:41]
	s_waitcnt lgkmcnt(8)
	v_pk_mul_f32 v[42:43], v[68:69], v[42:43]
	v_pk_mul_f32 v[44:45], v[70:71], v[44:45]
	v_cvt_pk_bf16_f32 v38, v38, v39
	v_cvt_pk_bf16_f32 v39, v40, v41
	v_cvt_pk_bf16_f32 v40, v42, v43
	v_cvt_pk_bf16_f32 v41, v44, v45
	global_store_dwordx4 v[2:3], v[38:41], off offset:48
	global_load_dwordx4 v[38:41], v[50:51], off offset:112
	s_nop 0
	global_load_dwordx4 v[42:45], v[50:51], off offset:96
	global_load_dwordx4 v[46:49], v[50:51], off offset:80
	s_nop 0
	global_load_dwordx4 v[50:53], v[50:51], off offset:64
	s_waitcnt vmcnt(0)
	v_lshlrev_b32_e32 v54, 16, v50
	v_and_b32_e32 v55, 0xffff0000, v50
	v_lshlrev_b32_e32 v50, 16, v51
	v_and_b32_e32 v51, 0xffff0000, v51
	s_waitcnt lgkmcnt(7)
	v_pk_mul_f32 v[36:37], v[36:37], v[50:51]
	v_lshlrev_b32_e32 v50, 16, v52
	v_and_b32_e32 v51, 0xffff0000, v52
	s_waitcnt lgkmcnt(6)
	v_pk_mul_f32 v[50:51], v[30:31], v[50:51]
	v_lshlrev_b32_e32 v30, 16, v53
	v_and_b32_e32 v31, 0xffff0000, v53
	v_pk_mul_f32 v[34:35], v[34:35], v[54:55]
	v_pk_mul_f32 v[52:53], v[32:33], v[30:31]
	v_cvt_pk_bf16_f32 v30, v34, v35
	v_cvt_pk_bf16_f32 v31, v36, v37
	v_cvt_pk_bf16_f32 v32, v50, v51
	v_cvt_pk_bf16_f32 v33, v52, v53
	global_store_dwordx4 v[2:3], v[30:33], off offset:64
	s_nop 1
	v_lshlrev_b32_e32 v30, 16, v46
	v_and_b32_e32 v31, 0xffff0000, v46
	s_waitcnt lgkmcnt(5)
	v_pk_mul_f32 v[26:27], v[26:27], v[30:31]
	v_lshlrev_b32_e32 v30, 16, v47
	v_and_b32_e32 v31, 0xffff0000, v47
	v_pk_mul_f32 v[28:29], v[28:29], v[30:31]
	v_lshlrev_b32_e32 v30, 16, v48
	v_and_b32_e32 v31, 0xffff0000, v48
	s_waitcnt lgkmcnt(4)
	v_pk_mul_f32 v[30:31], v[22:23], v[30:31]
	v_lshlrev_b32_e32 v22, 16, v49
	v_and_b32_e32 v23, 0xffff0000, v49
	v_pk_mul_f32 v[32:33], v[24:25], v[22:23]
	v_cvt_pk_bf16_f32 v22, v26, v27
	v_cvt_pk_bf16_f32 v23, v28, v29
	v_cvt_pk_bf16_f32 v24, v30, v31
	v_cvt_pk_bf16_f32 v25, v32, v33
	global_store_dwordx4 v[2:3], v[22:25], off offset:80
	s_nop 1
	v_lshlrev_b32_e32 v22, 16, v42
	v_and_b32_e32 v23, 0xffff0000, v42
	s_waitcnt lgkmcnt(3)
	v_pk_mul_f32 v[18:19], v[18:19], v[22:23]
	v_lshlrev_b32_e32 v22, 16, v43
	v_and_b32_e32 v23, 0xffff0000, v43
	v_pk_mul_f32 v[20:21], v[20:21], v[22:23]
	v_lshlrev_b32_e32 v22, 16, v44
	v_and_b32_e32 v23, 0xffff0000, v44
	s_waitcnt lgkmcnt(2)
	v_pk_mul_f32 v[22:23], v[14:15], v[22:23]
	v_lshlrev_b32_e32 v14, 16, v45
	v_and_b32_e32 v15, 0xffff0000, v45
	v_pk_mul_f32 v[24:25], v[16:17], v[14:15]
	v_cvt_pk_bf16_f32 v14, v18, v19
	v_cvt_pk_bf16_f32 v15, v20, v21
	v_cvt_pk_bf16_f32 v16, v22, v23
	v_cvt_pk_bf16_f32 v17, v24, v25
	global_store_dwordx4 v[2:3], v[14:17], off offset:96
	s_nop 1
	v_lshlrev_b32_e32 v14, 16, v38
	v_and_b32_e32 v15, 0xffff0000, v38
	s_waitcnt lgkmcnt(1)
	v_pk_mul_f32 v[10:11], v[10:11], v[14:15]
	v_lshlrev_b32_e32 v14, 16, v39
	v_and_b32_e32 v15, 0xffff0000, v39
	v_pk_mul_f32 v[12:13], v[12:13], v[14:15]
	v_lshlrev_b32_e32 v14, 16, v40
	v_and_b32_e32 v15, 0xffff0000, v40
	s_waitcnt lgkmcnt(0)
	v_pk_mul_f32 v[14:15], v[6:7], v[14:15]
	v_lshlrev_b32_e32 v6, 16, v41
	v_and_b32_e32 v7, 0xffff0000, v41
	v_pk_mul_f32 v[16:17], v[8:9], v[6:7]
	v_cvt_pk_bf16_f32 v6, v10, v11
	v_cvt_pk_bf16_f32 v7, v12, v13
	v_cvt_pk_bf16_f32 v8, v14, v15
	v_cvt_pk_bf16_f32 v9, v16, v17
	global_store_dwordx4 v[2:3], v[6:9], off offset:112
	s_barrier

; #define LAS __attribute__((address_space(3)))
; __device__ __forceinline__ int crow(int r, int hi) { return (r & 3) + 8 * (r >> 2) + 4 * hi; }
; template <int MODE, bool FIXED>
; __device__ __forceinline__ void attn_unit(LAS unsigned char* lds, unsigned char* ws, const AttnParams& P, int l, int Tp, int sq, int h, int qb, int part, int np, int pslot, int tid, int wave, int lane) {
;     ...
;     LAS float* ost = (LAS float*)(lds + AT_OST + wave * AT_OST_W);
;     {
;         if (hi == 0) li_l[r32] = l_reg;
;         asm volatile("s_waitcnt lgkmcnt(0)" ::: "memory");
; #pragma unroll
;         for (int r4 = 0; r4 < 4; ++r4) { float rl[4];
; #pragma unroll
;             for (int e = 0; e < 4; ++e) rl[e] = __builtin_amdgcn_rcpf(li_l[crow(4 * r4 + e, hi)]);
; #pragma unroll
;             for (int d = 0; d < 4; ++d) { f32x4 pk = {0.f, 0.f, 0.f, 0.f}; if (MODE == 1) pk = *(const f32x4*)(park + (d * 4 + r4) * 256);
; #pragma unroll
;                 for (int e = 0; e < 4; ++e) { float v = o[d][4 * r4 + e] * rl[e]; if (MODE == 1) v = pk[e] - lam * v;
;                     ost[crow(4 * r4 + e, hi) * 132 + d * 32 + r32] = v; } } }
;     }
;     asm volatile("s_waitcnt lgkmcnt(0)" ::: "memory");
.LBB0_879:
	s_waitcnt lgkmcnt(0)
	s_barrier
	s_add_i32 s9, s13, 0
	v_readlane_b32 s4, v254, 26
	s_add_i32 s9, s9, 0x21000
	v_readlane_b32 s5, v254, 27
	v_cmp_gt_u32_e32 vcc, 32, v193
	s_and_saveexec_b64 s[4:5], vcc
	v_lshl_add_u32 v2, v195, 2, s9
	ds_write_b32 v2, v171
	s_or_b64 exec, exec, s[4:5]
	s_waitcnt lgkmcnt(0)
	v_lshl_add_u32 v2, v135, 2, s9
	ds_read_b128 v[6:9], v2
	s_mul_i32 s4, s31, 0x4200
	s_add_i32 s4, s4, 0
	v_lshlrev_b32_e32 v3, 2, v195
	v_mul_u32_u24_e32 v10, 0x840, v194
	s_waitcnt lgkmcnt(0)
	v_rcp_f32_e32 v5, v6
	v_rcp_f32_e32 v6, v7
	v_rcp_f32_e32 v7, v8
	v_rcp_f32_e32 v8, v9
	v_mul_f32_e32 v9, v66, v5
	v_add3_u32 v3, s4, v3, v10
	v_mul_f32_e32 v13, v50, v5
	v_mul_f32_e32 v10, v67, v6
	ds_write2_b32 v3, v9, v13 offset1:32
	v_mul_f32_e32 v9, v51, v6
	v_mul_f32_e32 v11, v68, v7
	ds_write2_b32 v3, v10, v9 offset0:132 offset1:164
	v_mul_f32_e32 v9, v52, v7
	v_add_u32_e32 v10, 0x400, v3
	v_mul_f32_e32 v12, v69, v8
	ds_write2_b32 v10, v11, v9 offset0:8 offset1:40
	v_mul_f32_e32 v9, v53, v8
	ds_write2_b32 v10, v12, v9 offset0:140 offset1:172
	v_mul_f32_e32 v9, v34, v5
	v_mul_f32_e32 v5, v18, v5
	v_mul_f32_e32 v11, v35, v6
	ds_write2_b32 v3, v9, v5 offset0:64 offset1:96
	v_mul_f32_e32 v5, v19, v6
	v_mul_f32_e32 v12, v36, v7
	ds_write2_b32 v3, v11, v5 offset0:196 offset1:228
	v_mul_f32_e32 v5, v20, v7
	v_mul_f32_e32 v13, v37, v8
	ds_write2_b32 v10, v12, v5 offset0:72 offset1:104
	v_mul_f32_e32 v5, v21, v8
	ds_write2_b32 v10, v13, v5 offset0:204 offset1:236
	ds_read_b128 v[6:9], v2 offset:32
	v_add_u32_e32 v14, 0x1000, v3
	s_add_i32 s8, s8, s12
	v_mov_b64_e32 v[50:51], s[50:51]
	s_movk_i32 s3, 0x2000
	s_waitcnt lgkmcnt(0)
	v_rcp_f32_e32 v5, v6
	v_rcp_f32_e32 v6, v7
	v_rcp_f32_e32 v7, v8
	v_rcp_f32_e32 v8, v9
	v_mul_f32_e32 v9, v70, v5
	v_mul_f32_e32 v13, v54, v5
	v_mul_f32_e32 v10, v71, v6
	ds_write2_b32 v14, v9, v13 offset0:32 offset1:64
	v_mul_f32_e32 v9, v55, v6
	v_mul_f32_e32 v11, v72, v7
	ds_write2_b32 v14, v10, v9 offset0:164 offset1:196
	v_mul_f32_e32 v9, v56, v7
	v_add_u32_e32 v10, 0x1400, v3
	v_mul_f32_e32 v12, v73, v8
	ds_write2_b32 v10, v11, v9 offset0:40 offset1:72
	v_mul_f32_e32 v9, v57, v8
	ds_write2_b32 v10, v12, v9 offset0:172 offset1:204
	v_mul_f32_e32 v9, v38, v5
	v_mul_f32_e32 v5, v22, v5
	v_mul_f32_e32 v11, v39, v6
	ds_write2_b32 v14, v9, v5 offset0:96 offset1:128
	v_mul_f32_e32 v5, v23, v6
	v_add_u32_e32 v6, 0x1200, v3
	v_mul_f32_e32 v12, v40, v7
	ds_write2_b32 v6, v11, v5 offset0:100 offset1:132
	v_mul_f32_e32 v5, v24, v7
	v_mul_f32_e32 v13, v41, v8
	ds_write2_b32 v10, v12, v5 offset0:104 offset1:136
	v_mul_f32_e32 v5, v25, v8
	v_add_u32_e32 v6, 0x1600, v3
	ds_write2_b32 v6, v13, v5 offset0:108 offset1:140
	ds_read_b128 v[6:9], v2 offset:64
	v_add_u32_e32 v14, 0x2000, v3
	v_mov_b32_e32 v73, v4
	s_waitcnt lgkmcnt(0)
	v_rcp_f32_e32 v5, v6
	v_rcp_f32_e32 v6, v7
	v_rcp_f32_e32 v7, v8
	v_rcp_f32_e32 v8, v9
	v_mul_f32_e32 v9, v74, v5
	v_mul_f32_e32 v13, v58, v5
	v_mul_f32_e32 v10, v75, v6
	ds_write2_b32 v14, v9, v13 offset0:64 offset1:96
	v_mul_f32_e32 v9, v59, v6
	v_mul_f32_e32 v11, v76, v7
	ds_write2_b32 v14, v10, v9 offset0:196 offset1:228
	v_mul_f32_e32 v9, v60, v7
	v_add_u32_e32 v10, 0x2400, v3
	v_mul_f32_e32 v12, v77, v8
	ds_write2_b32 v10, v11, v9 offset0:72 offset1:104
	v_mul_f32_e32 v9, v61, v8
	ds_write2_b32 v10, v12, v9 offset0:204 offset1:236
	v_mul_f32_e32 v9, v42, v5
	v_mul_f32_e32 v5, v26, v5
	v_mul_f32_e32 v11, v43, v6
	ds_write2_b32 v14, v9, v5 offset0:128 offset1:160
	v_mul_f32_e32 v5, v27, v6
	v_mul_f32_e32 v12, v44, v7
	ds_write2_b32 v10, v11, v5 offset0:4 offset1:36
	v_mul_f32_e32 v5, v28, v7
	v_mul_f32_e32 v13, v45, v8
	ds_write2_b32 v10, v12, v5 offset0:136 offset1:168
	v_mul_f32_e32 v5, v29, v8
	v_add_u32_e32 v6, 0x2800, v3
	ds_write2_b32 v6, v13, v5 offset0:12 offset1:44
	ds_read_b128 v[6:9], v2 offset:96
	v_add_u32_e32 v13, 0x3000, v3
	s_waitcnt lgkmcnt(0)
	v_rcp_f32_e32 v2, v6
	v_rcp_f32_e32 v5, v7
	v_rcp_f32_e32 v6, v8
	v_rcp_f32_e32 v7, v9
	v_mul_f32_e32 v8, v78, v2
	v_mul_f32_e32 v12, v62, v2
	v_mul_f32_e32 v9, v79, v5
	ds_write2_b32 v13, v8, v12 offset0:96 offset1:128
	v_mul_f32_e32 v8, v63, v5
	v_add_u32_e32 v12, 0x3200, v3
	v_mul_f32_e32 v10, v80, v6
	ds_write2_b32 v12, v9, v8 offset0:100 offset1:132
	v_mul_f32_e32 v8, v64, v6
	v_add_u32_e32 v9, 0x3400, v3
	v_mul_f32_e32 v11, v81, v7
	ds_write2_b32 v9, v10, v8 offset0:104 offset1:136
	v_mul_f32_e32 v8, v65, v7
	v_add_u32_e32 v10, 0x3600, v3
	ds_write2_b32 v10, v11, v8 offset0:108 offset1:140
	v_mul_f32_e32 v8, v46, v2
	v_mul_f32_e32 v2, v30, v2
	v_mul_f32_e32 v10, v47, v5
	ds_write2_b32 v13, v8, v2 offset0:160 offset1:192
	v_mul_f32_e32 v2, v31, v5
	v_mul_f32_e32 v11, v48, v6
	ds_write2_b32 v9, v10, v2 offset0:36 offset1:68
	v_mul_f32_e32 v2, v32, v6
	v_mul_f32_e32 v12, v49, v7
	ds_write2_b32 v9, v11, v2 offset0:168 offset1:200
	v_mul_f32_e32 v2, v33, v7
	v_add_u32_e32 v3, 0x3800, v3
	v_lshlrev_b32_e32 v5, 6, v193
	ds_write2_b32 v3, v12, v2 offset0:44 offset1:76
	v_lshrrev_b32_e32 v2, 1, v193
	v_and_b32_e32 v5, 64, v5
	v_mul_u32_u24_e32 v3, 0x210, v2
	v_lshlrev_b32_e32 v6, 2, v5
	v_or_b32_e32 v2, s8, v2
	v_add3_u32 v3, s4, v3, v6
	v_mad_i64_i32 v[50:51], s[4:5], v2, s70, v[50:51]
	v_lshl_add_u64 v[50:51], v[50:51], 0, s[60:61]
	v_lshlrev_b32_e32 v72, 1, v5
	s_waitcnt lgkmcnt(0)
; __device__ __forceinline__ float bflo(unsigned w) { return __uint_as_float(w << 16); }
; __device__ __forceinline__ float bfhi(unsigned w) { return __uint_as_float(w & 0xffff0000u); }
; #define LAS __attribute__((address_space(3)))
; __device__ __forceinline__ float bflo(unsigned w) { return __uint_as_float(w << 16); }
; __device__ __forceinline__ float bfhi(unsigned w) { return __uint_as_float(w & 0xffff0000u); }
; __device__ __forceinline__ unsigned cvtpk(float lo, float hi) { const f32x2_t v = {lo, hi}; const bf16x2_t b = __builtin_convertvector(v, bf16x2_t); return __builtin_bit_cast(unsigned, b); }
; template <int MODE, bool FIXED>
; __device__ __forceinline__ void attn_unit(LAS unsigned char* lds, unsigned char* ws, const AttnParams& P, int l, int Tp, int sq, int h, int qb, int part, int np, int pslot, int tid, int wave, int lane) {
;     ...
;     {
;         const int row = lane >> 1, half = lane & 1;
;         const LAS f32x4* src = (const LAS f32x4*)(ost + row * 132 + half * 64);
;         float v[64];
; #pragma unroll
;         for (int k = 0; k < 16; ++k) { const f32x4 t = src[k]; v[4 * k] = t.x; v[4 * k + 1] = t.y; v[4 * k + 2] = t.z; v[4 * k + 3] = t.w; }
;         const size_t grow = (size_t)(seq0 + q0 + wave * 32 + row);
;         float rs = 1.f;
;         if (MODE == 1) { float ss = 0.f;
; #pragma unroll
;             for (int e = 0; e < 64; ++e) ss += v[e] * v[e];
;             ss += xshfl<1>(ss); rs = (1.0f / sqrtf(ss * (1.0f / 128.0f) + NORM_EPS)) * (1.0f - lin); }
;         const v4u* zp = (const v4u*)(PROJ + grow * LDP + zcol + half * 64);
;         bf16* yb = (bf16*)(ws + WS_Y + (MODE ? 2 : 1) * SZ_Y1) + grow * 1024 + h * 128 + half * 64;
; #pragma unroll
;         for (int k = 0; k < 8; ++k) { const v4u zw = zp[k];
;             const float z[8] = {bflo(zw.x), bfhi(zw.x), bflo(zw.y), bfhi(zw.y), bflo(zw.z), bfhi(zw.z), bflo(zw.w), bfhi(zw.w)};
;             float y[8];
; #pragma unroll
;             for (int e = 0; e < 8; ++e) { float g = 1.f; if (MODE == 1) g = P.norm_gain[half * 64 + 8 * k + e]; y[e] = v[8 * k + e] * rs * g * z[e]; }
;             v4u w; w.x = cvtpk(y[0], y[1]); w.y = cvtpk(y[2], y[3]); w.z = cvtpk(y[4], y[5]); w.w = cvtpk(y[6], y[7]);
;             *(v4u*)(yb + 8 * k) = w; }
;     }
;     asm volatile("s_waitcnt lgkmcnt(0)" ::: "memory"); __builtin_amdgcn_s_barrier(); asm volatile("" ::: "memory");
	v_lshl_add_u64 v[74:75], v[50:51], 0, v[72:73]
	s_mov_b64 s[4:5], 0x2c00
	ds_read_b128 v[38:41], v3
	ds_read_b128 v[42:45], v3 offset:16
	ds_read_b128 v[46:49], v3 offset:32
	ds_read_b128 v[52:55], v3 offset:48
	ds_read_b128 v[56:59], v3 offset:64
	ds_read_b128 v[60:63], v3 offset:80
	ds_read_b128 v[64:67], v3 offset:96
	ds_read_b128 v[68:71], v3 offset:112
	ds_read_b128 v[34:37], v3 offset:128
	ds_read_b128 v[30:33], v3 offset:144
	ds_read_b128 v[26:29], v3 offset:160
	ds_read_b128 v[22:25], v3 offset:176
	ds_read_b128 v[18:21], v3 offset:192
	ds_read_b128 v[14:17], v3 offset:208
	ds_read_b128 v[10:13], v3 offset:224
	ds_read_b128 v[6:9], v3 offset:240
	v_ashrrev_i32_e32 v3, 31, v2
	v_lshl_add_u64 v[50:51], v[74:75], 0, s[4:5]
	v_readlane_b32 s4, v252, 34
	v_lshlrev_b64 v[2:3], 11, v[2:3]
	v_readlane_b32 s5, v252, 35
	s_nop 1
	v_lshl_add_u64 v[2:3], s[4:5], 0, v[2:3]
	v_lshl_add_u64 v[2:3], v[2:3], 0, s[60:61]
	v_lshl_add_u64 v[2:3], v[2:3], 0, v[72:73]
	v_add_co_u32_e32 v72, vcc, s3, v74
	s_nop 1
	v_addc_co_u32_e32 v73, vcc, 0, v75, vcc
	global_load_dwordx4 v[72:75], v[72:73], off offset:3072
	s_nop 0
	global_load_dwordx4 v[76:79], v[50:51], off offset:48
	global_load_dwordx4 v[80:83], v[50:51], off offset:32
	global_load_dwordx4 v[84:87], v[50:51], off offset:16
	s_waitcnt vmcnt(3)
	v_lshlrev_b32_e32 v88, 16, v72
	v_and_b32_e32 v89, 0xffff0000, v72
	v_lshlrev_b32_e32 v72, 16, v73
	v_and_b32_e32 v73, 0xffff0000, v73
	s_waitcnt lgkmcnt(14)
	v_pk_mul_f32 v[40:41], v[40:41], v[72:73]
	v_lshlrev_b32_e32 v72, 16, v74
	v_and_b32_e32 v73, 0xffff0000, v74
	v_pk_mul_f32 v[42:43], v[42:43], v[72:73]
	v_lshlrev_b32_e32 v72, 16, v75
	v_and_b32_e32 v73, 0xffff0000, v75
	v_pk_mul_f32 v[38:39], v[38:39], v[88:89]
	v_pk_mul_f32 v[44:45], v[44:45], v[72:73]
	v_cvt_pk_bf16_f32 v38, v38, v39
	v_cvt_pk_bf16_f32 v39, v40, v41
	v_cvt_pk_bf16_f32 v40, v42, v43
	v_cvt_pk_bf16_f32 v41, v44, v45
	global_store_dwordx4 v[2:3], v[38:41], off
	s_waitcnt vmcnt(1)
	v_lshlrev_b32_e32 v42, 16, v86
	v_and_b32_e32 v43, 0xffff0000, v86
	v_lshlrev_b32_e32 v38, 16, v84
	v_and_b32_e32 v39, 0xffff0000, v84
	v_lshlrev_b32_e32 v40, 16, v85
	v_and_b32_e32 v41, 0xffff0000, v85
	v_lshlrev_b32_e32 v44, 16, v87
	v_and_b32_e32 v45, 0xffff0000, v87
	s_waitcnt lgkmcnt(13)
	v_pk_mul_f32 v[38:39], v[46:47], v[38:39]
	v_pk_mul_f32 v[40:41], v[48:49], v[40:41]
	s_waitcnt lgkmcnt(12)
	v_pk_mul_f32 v[42:43], v[52:53], v[42:43]
	v_pk_mul_f32 v[44:45], v[54:55], v[44:45]
	v_cvt_pk_bf16_f32 v38, v38, v39
	v_cvt_pk_bf16_f32 v39, v40, v41
	v_cvt_pk_bf16_f32 v40, v42, v43
	v_cvt_pk_bf16_f32 v41, v44, v45
	global_store_dwordx4 v[2:3], v[38:41], off offset:16
	v_lshlrev_b32_e32 v42, 16, v82
	v_and_b32_e32 v43, 0xffff0000, v82
	v_lshlrev_b32_e32 v38, 16, v80
	v_and_b32_e32 v39, 0xffff0000, v80
	v_lshlrev_b32_e32 v40, 16, v81
	v_and_b32_e32 v41, 0xffff0000, v81
	v_lshlrev_b32_e32 v44, 16, v83
	v_and_b32_e32 v45, 0xffff0000, v83
	s_waitcnt lgkmcnt(11)
	v_pk_mul_f32 v[38:39], v[56:57], v[38:39]
	v_pk_mul_f32 v[40:41], v[58:59], v[40:41]
	s_waitcnt lgkmcnt(10)
	v_pk_mul_f32 v[42:43], v[60:61], v[42:43]
	v_pk_mul_f32 v[44:45], v[62:63], v[44:45]
	v_cvt_pk_bf16_f32 v38, v38, v39
	v_cvt_pk_bf16_f32 v39, v40, v41
	v_cvt_pk_bf16_f32 v40, v42, v43
	v_cvt_pk_bf16_f32 v41, v44, v45
	global_store_dwordx4 v[2:3], v[38:41], off offset:32
	v_lshlrev_b32_e32 v42, 16, v78
	v_and_b32_e32 v43, 0xffff0000, v78
	v_lshlrev_b32_e32 v38, 16, v76
	v_and_b32_e32 v39, 0xffff0000, v76
	v_lshlrev_b32_e32 v40, 16, v77
	v_and_b32_e32 v41, 0xffff0000, v77
	v_lshlrev_b32_e32 v44, 16, v79
	v_and_b32_e32 v45, 0xffff0000, v79
	s_waitcnt lgkmcnt(9)
	v_pk_mul_f32 v[38:39], v[64:65], v[38:39]
	v_pk_mul_f32 v[40:41], v[66:67], v[40:41]
	s_waitcnt lgkmcnt(8)
	v_pk_mul_f32 v[42:43], v[68:69], v[42:43]
	v_pk_mul_f32 v[44:45], v[70:71], v[44:45]
	v_cvt_pk_bf16_f32 v38, v38, v39
	v_cvt_pk_bf16_f32 v39, v40, v41
	v_cvt_pk_bf16_f32 v40, v42, v43
	v_cvt_pk_bf16_f32 v41, v44, v45
	global_store_dwordx4 v[2:3], v[38:41], off offset:48
	global_load_dwordx4 v[38:41], v[50:51], off offset:112
	s_nop 0
	global_load_dwordx4 v[42:45], v[50:51], off offset:96
	global_load_dwordx4 v[46:49], v[50:51], off offset:80
	s_nop 0
	global_load_dwordx4 v[50:53], v[50:51], off offset:64
	s_waitcnt vmcnt(0)
	v_lshlrev_b32_e32 v54, 16, v50
	v_and_b32_e32 v55, 0xffff0000, v50
	v_lshlrev_b32_e32 v50, 16, v51
	v_and_b32_e32 v51, 0xffff0000, v51
	s_waitcnt lgkmcnt(7)
	v_pk_mul_f32 v[36:37], v[36:37], v[50:51]
	v_lshlrev_b32_e32 v50, 16, v52
	v_and_b32_e32 v51, 0xffff0000, v52
	s_waitcnt lgkmcnt(6)
	v_pk_mul_f32 v[50:51], v[30:31], v[50:51]
	v_lshlrev_b32_e32 v30, 16, v53
	v_and_b32_e32 v31, 0xffff0000, v53
	v_pk_mul_f32 v[34:35], v[34:35], v[54:55]
	v_pk_mul_f32 v[52:53], v[32:33], v[30:31]
	v_cvt_pk_bf16_f32 v30, v34, v35
	v_cvt_pk_bf16_f32 v31, v36, v37
	v_cvt_pk_bf16_f32 v32, v50, v51
	v_cvt_pk_bf16_f32 v33, v52, v53
	global_store_dwordx4 v[2:3], v[30:33], off offset:64
	s_nop 1
	v_lshlrev_b32_e32 v30, 16, v46
	v_and_b32_e32 v31, 0xffff0000, v46
	s_waitcnt lgkmcnt(5)
	v_pk_mul_f32 v[26:27], v[26:27], v[30:31]
	v_lshlrev_b32_e32 v30, 16, v47
	v_and_b32_e32 v31, 0xffff0000, v47
	v_pk_mul_f32 v[28:29], v[28:29], v[30:31]
	v_lshlrev_b32_e32 v30, 16, v48
	v_and_b32_e32 v31, 0xffff0000, v48
	s_waitcnt lgkmcnt(4)
	v_pk_mul_f32 v[30:31], v[22:23], v[30:31]
	v_lshlrev_b32_e32 v22, 16, v49
	v_and_b32_e32 v23, 0xffff0000, v49
	v_pk_mul_f32 v[32:33], v[24:25], v[22:23]
	v_cvt_pk_bf16_f32 v22, v26, v27
	v_cvt_pk_bf16_f32 v23, v28, v29
	v_cvt_pk_bf16_f32 v24, v30, v31
	v_cvt_pk_bf16_f32 v25, v32, v33
	global_store_dwordx4 v[2:3], v[22:25], off offset:80
	s_nop 1
	v_lshlrev_b32_e32 v22, 16, v42
	v_and_b32_e32 v23, 0xffff0000, v42
	s_waitcnt lgkmcnt(3)
	v_pk_mul_f32 v[18:19], v[18:19], v[22:23]
	v_lshlrev_b32_e32 v22, 16, v43
	v_and_b32_e32 v23, 0xffff0000, v43
	v_pk_mul_f32 v[20:21], v[20:21], v[22:23]
	v_lshlrev_b32_e32 v22, 16, v44
	v_and_b32_e32 v23, 0xffff0000, v44
	s_waitcnt lgkmcnt(2)
	v_pk_mul_f32 v[22:23], v[14:15], v[22:23]
	v_lshlrev_b32_e32 v14, 16, v45
	v_and_b32_e32 v15, 0xffff0000, v45
	v_pk_mul_f32 v[24:25], v[16:17], v[14:15]
	v_cvt_pk_bf16_f32 v14, v18, v19
	v_cvt_pk_bf16_f32 v15, v20, v21
	v_cvt_pk_bf16_f32 v16, v22, v23
	v_cvt_pk_bf16_f32 v17, v24, v25
	global_store_dwordx4 v[2:3], v[14:17], off offset:96
	s_nop 1
	v_lshlrev_b32_e32 v14, 16, v38
	v_and_b32_e32 v15, 0xffff0000, v38
	s_waitcnt lgkmcnt(1)
	v_pk_mul_f32 v[10:11], v[10:11], v[14:15]
	v_lshlrev_b32_e32 v14, 16, v39
	v_and_b32_e32 v15, 0xffff0000, v39
	v_pk_mul_f32 v[12:13], v[12:13], v[14:15]
	v_lshlrev_b32_e32 v14, 16, v40
	v_and_b32_e32 v15, 0xffff0000, v40
	s_waitcnt lgkmcnt(0)
	v_pk_mul_f32 v[14:15], v[6:7], v[14:15]
	v_lshlrev_b32_e32 v6, 16, v41
	v_and_b32_e32 v7, 0xffff0000, v41
	v_pk_mul_f32 v[16:17], v[8:9], v[6:7]
	v_cvt_pk_bf16_f32 v6, v10, v11
	v_cvt_pk_bf16_f32 v7, v12, v13
	v_cvt_pk_bf16_f32 v8, v14, v15
	v_cvt_pk_bf16_f32 v9, v16, v17
	global_store_dwordx4 v[2:3], v[6:9], off offset:112
	s_barrier

; __device__ __forceinline__ int crow(int r, int hi) { return (r & 3) + 8 * (r >> 2) + 4 * hi; }
; template <int MODE, bool FIXED>
; __device__ __forceinline__ void attn_unit(LAS unsigned char* lds, unsigned char* ws, const AttnParams& P, int l, int Tp, int sq, int h, int qb, int part, int np, int pslot, int tid, int wave, int lane) {
;     ...
;         if (MODE == 1 && mp == 0) {
;             if (hi == 0) li_l[r32] = l_reg;
;             asm volatile("s_waitcnt lgkmcnt(0)" ::: "memory");
; #pragma unroll
;             for (int r4 = 0; r4 < 4; ++r4) { float rl[4];
; #pragma unroll
;                 for (int e = 0; e < 4; ++e) rl[e] = __builtin_amdgcn_rcpf(li_l[crow(4 * r4 + e, hi)]);
; #pragma unroll
;                 for (int d = 0; d < 4; ++d) { f32x4 t; t.x = o[d][4 * r4] * rl[0]; t.y = o[d][4 * r4 + 1] * rl[1]; t.z = o[d][4 * r4 + 2] * rl[2]; t.w = o[d][4 * r4 + 3] * rl[3];
;                     *(f32x4*)(park + (d * 4 + r4) * 256) = t; } }
;             asm volatile("s_waitcnt lgkmcnt(0)" ::: "memory");
;         }
;     }
.LBB0_890:
	s_or_b64 exec, exec, s[10:11]
	s_waitcnt lgkmcnt(0)
	ds_read_b128 v[6:9], v200
	ds_read_b128 v[10:13], v200 offset:32
	s_mov_b64 s[84:85], 0
	s_waitcnt lgkmcnt(1)
	v_rcp_f32_e32 v2, v6
	v_rcp_f32_e32 v3, v7
	v_rcp_f32_e32 v14, v8
	v_rcp_f32_e32 v15, v9
	v_pk_mul_f32 v[6:7], v[66:67], v[2:3]
	v_pk_mul_f32 v[8:9], v[68:69], v[14:15]
	global_store_dwordx4 v[156:157], v[6:9], off
	s_nop 1
	v_pk_mul_f32 v[6:7], v[50:51], v[2:3]
	v_pk_mul_f32 v[8:9], v[52:53], v[14:15]
	global_store_dwordx4 v[176:177], v[6:9], off
	s_nop 1
	v_pk_mul_f32 v[6:7], v[34:35], v[2:3]
	v_pk_mul_f32 v[8:9], v[36:37], v[14:15]
	global_store_dwordx4 v[174:175], v[6:9], off
	s_nop 1
	v_pk_mul_f32 v[6:7], v[18:19], v[2:3]
	s_waitcnt lgkmcnt(0)
	v_rcp_f32_e32 v2, v10
	v_rcp_f32_e32 v3, v11
	v_rcp_f32_e32 v10, v12
	v_rcp_f32_e32 v11, v13
	v_pk_mul_f32 v[8:9], v[20:21], v[14:15]
	global_store_dwordx4 v[172:173], v[6:9], off
	s_nop 1
	v_pk_mul_f32 v[6:7], v[70:71], v[2:3]
	v_pk_mul_f32 v[8:9], v[72:73], v[10:11]
	global_store_dwordx4 v[156:157], v[6:9], off offset:1024
	s_nop 1
	v_pk_mul_f32 v[6:7], v[54:55], v[2:3]
	v_pk_mul_f32 v[8:9], v[56:57], v[10:11]
	global_store_dwordx4 v[170:171], v[6:9], off
	s_nop 1
	v_pk_mul_f32 v[6:7], v[38:39], v[2:3]
	v_pk_mul_f32 v[8:9], v[40:41], v[10:11]
	global_store_dwordx4 v[168:169], v[6:9], off
	s_nop 1
	v_pk_mul_f32 v[6:7], v[22:23], v[2:3]
	v_pk_mul_f32 v[8:9], v[24:25], v[10:11]
	global_store_dwordx4 v[166:167], v[6:9], off
	ds_read_b128 v[6:9], v200 offset:64
	s_waitcnt lgkmcnt(0)
	v_rcp_f32_e32 v2, v6
	v_rcp_f32_e32 v3, v7
	v_rcp_f32_e32 v10, v8
	v_rcp_f32_e32 v11, v9
	v_pk_mul_f32 v[6:7], v[74:75], v[2:3]
	v_pk_mul_f32 v[8:9], v[76:77], v[10:11]
	global_store_dwordx4 v[156:157], v[6:9], off offset:2048
	s_nop 1
	v_pk_mul_f32 v[6:7], v[58:59], v[2:3]
	v_pk_mul_f32 v[8:9], v[60:61], v[10:11]
	global_store_dwordx4 v[164:165], v[6:9], off
	s_nop 1
	v_pk_mul_f32 v[6:7], v[42:43], v[2:3]
	v_pk_mul_f32 v[8:9], v[44:45], v[10:11]
	global_store_dwordx4 v[162:163], v[6:9], off
	s_nop 1
	v_pk_mul_f32 v[6:7], v[26:27], v[2:3]
	v_pk_mul_f32 v[8:9], v[28:29], v[10:11]
	global_store_dwordx4 v[160:161], v[6:9], off
	ds_read_b128 v[6:9], v200 offset:96
	s_waitcnt lgkmcnt(0)
	v_rcp_f32_e32 v2, v6
	v_rcp_f32_e32 v3, v7
	v_rcp_f32_e32 v10, v8
	v_rcp_f32_e32 v11, v9
	v_pk_mul_f32 v[6:7], v[78:79], v[2:3]
	v_pk_mul_f32 v[8:9], v[80:81], v[10:11]
	global_store_dwordx4 v[156:157], v[6:9], off offset:3072
	s_nop 1
	v_pk_mul_f32 v[6:7], v[62:63], v[2:3]
	v_pk_mul_f32 v[8:9], v[64:65], v[10:11]
	global_store_dwordx4 v[158:159], v[6:9], off
	s_nop 1
	v_pk_mul_f32 v[6:7], v[46:47], v[2:3]
	v_pk_mul_f32 v[8:9], v[48:49], v[10:11]
	global_store_dwordx4 v[154:155], v[6:9], off
	s_nop 1
	v_pk_mul_f32 v[6:7], v[30:31], v[2:3]
	v_pk_mul_f32 v[8:9], v[32:33], v[10:11]
	global_store_dwordx4 v[152:153], v[6:9], off
.LBB0_891:
	s_mov_b64 s[10:11], 64
	s_mov_b64 s[80:81], 0
	s_and_b64 vcc, exec, s[84:85]
	s_cbranch_vccnz .LBB0_919

; #define LAS __attribute__((address_space(3)))
; __device__ __forceinline__ float wave_sum(float v) { v += xshfl<1>(v); v += xshfl<2>(v); v += xshfl<4>(v); v += xshfl<8>(v); v += xshfl<16>(v); return half_sum(v); }
; __device__ __forceinline__ int crow(int r, int hi) { return (r & 3) + 8 * (r >> 2) + 4 * hi; }
; template <int MODE, bool FIXED>
; __device__ __forceinline__ void attn_unit(LAS unsigned char* lds, unsigned char* ws, const AttnParams& P, int l, int Tp, int sq, int h, int qb, int part, int np, int pslot, int tid, int wave, int lane) {
;     ...
;     float lam = 0.f; int ll_ = l; asm volatile("" : "+s"(ll_)); const float lin = 0.8f - 0.6f * expf(-0.3f * (float)ll_);
;     if (MODE == 1) { const float a = P.lam[lane] * P.lam[64 + lane], bq = P.lam[128 + lane] * P.lam[192 + lane]; lam = expf(wave_sum(a)) - expf(wave_sum(bq)) + lin; }
;     LAS float* ost = (LAS float*)(lds + AT_OST + wave * AT_OST_W);
;     {
;         if (hi == 0) li_l[r32] = l_reg;
;         asm volatile("s_waitcnt lgkmcnt(0)" ::: "memory");
; #pragma unroll
;         for (int r4 = 0; r4 < 4; ++r4) { float rl[4];
; #pragma unroll
;             for (int e = 0; e < 4; ++e) rl[e] = __builtin_amdgcn_rcpf(li_l[crow(4 * r4 + e, hi)]);
; #pragma unroll
;             for (int d = 0; d < 4; ++d) { f32x4 pk = {0.f, 0.f, 0.f, 0.f}; if (MODE == 1) pk = *(const f32x4*)(park + (d * 4 + r4) * 256);
; #pragma unroll
;                 for (int e = 0; e < 4; ++e) { float v = o[d][4 * r4 + e] * rl[e]; if (MODE == 1) v = pk[e] - lam * v;
;                     ost[crow(4 * r4 + e, hi) * 132 + d * 32 + r32] = v; } } }
.LBB0_919:
	v_readlane_b32 s6, v254, 26
	v_readlane_b32 s7, v254, 27
	s_mov_b32 s8, s6
	v_readlane_b32 s6, v254, 40
	v_lshlrev_b32_e32 v2, 2, v193
	v_readlane_b32 s7, v254, 41
	s_nop 4
	global_load_dword v3, v2, s[6:7]
	global_load_dword v5, v2, s[6:7] offset:256
	global_load_dword v6, v2, s[6:7] offset:512
	s_nop 0
	global_load_dword v2, v2, s[6:7] offset:768
	s_waitcnt vmcnt(2)
	v_mul_f32_e32 v7, v3, v5
	ds_swizzle_b32 v7, v7 offset:swizzle(SWAP,1)
	s_waitcnt vmcnt(0)
	v_mul_f32_e32 v8, v6, v2
	ds_swizzle_b32 v8, v8 offset:swizzle(SWAP,1)
	s_waitcnt lgkmcnt(1)
	v_fmac_f32_e32 v7, v3, v5
	s_waitcnt lgkmcnt(0)
	v_fmac_f32_e32 v8, v6, v2
	ds_swizzle_b32 v2, v7 offset:swizzle(SWAP,2)
	ds_swizzle_b32 v3, v8 offset:swizzle(SWAP,2)
	s_waitcnt lgkmcnt(1)
	v_add_f32_e32 v2, v7, v2
	s_waitcnt lgkmcnt(0)
	v_add_f32_e32 v3, v8, v3
	ds_swizzle_b32 v5, v2 offset:swizzle(SWAP,4)
	ds_swizzle_b32 v6, v3 offset:swizzle(SWAP,4)
	s_waitcnt lgkmcnt(1)
	v_add_f32_e32 v2, v2, v5
	s_waitcnt lgkmcnt(0)
	v_add_f32_e32 v3, v3, v6
	ds_swizzle_b32 v5, v2 offset:swizzle(SWAP,8)
	ds_swizzle_b32 v6, v3 offset:swizzle(SWAP,8)
	s_waitcnt lgkmcnt(1)
	v_add_f32_e32 v2, v2, v5
	s_waitcnt lgkmcnt(0)
	v_add_f32_e32 v3, v3, v6
	ds_swizzle_b32 v5, v2 offset:swizzle(SWAP,16)
	ds_swizzle_b32 v7, v3 offset:swizzle(SWAP,16)
	s_waitcnt lgkmcnt(1)
	v_add_f32_e32 v6, v2, v5
	s_waitcnt lgkmcnt(0)
	v_add_f32_e32 v3, v3, v7
	v_mov_b32_e32 v7, v6
	v_mov_b32_e32 v5, v3
	s_nop 0
	v_permlane32_swap_b32_e32 v6, v7
	v_permlane32_swap_b32_e32 v3, v5
	s_and_saveexec_b64 s[6:7], s[4:5]
	ds_write_b32 v207, v240
	s_or_b64 exec, exec, s[6:7]
	v_cvt_f32_i32_e32 v2, s8
	s_mov_b32 s6, 0x3fb8aa3b
	s_mov_b32 s3, 0xc2ce8ed0
	s_mov_b32 s4, 0x42b17218
	v_mul_f32_e32 v2, 0xbe99999a, v2
	v_mul_f32_e32 v8, 0x3fb8aa3b, v2
	v_fma_f32 v9, v2, s6, -v8
	v_rndne_f32_e32 v10, v8
	v_fmac_f32_e32 v9, 0x32a5705f, v2
	v_sub_f32_e32 v8, v8, v10
	v_add_f32_e32 v8, v8, v9
	v_exp_f32_e32 v8, v8
	v_cvt_i32_f32_e32 v9, v10
	v_cmp_ngt_f32_e32 vcc, s3, v2
	v_add_f32_e32 v6, v6, v7
	v_mul_f32_e32 v7, 0x3fb8aa3b, v6
	v_ldexp_f32 v8, v8, v9
	v_cndmask_b32_e32 v8, 0, v8, vcc
	v_cmp_nlt_f32_e32 vcc, s4, v2
	v_rndne_f32_e32 v9, v7
	v_add_f32_e32 v3, v3, v5
	v_cndmask_b32_e32 v2, v225, v8, vcc
	v_mov_b32_e32 v8, 0x3f4ccccd
	v_fmamk_f32 v2, v2, 0xbf19999a, v8
	v_fma_f32 v8, v6, s6, -v7
	v_fmac_f32_e32 v8, 0x32a5705f, v6
	v_sub_f32_e32 v7, v7, v9
	v_add_f32_e32 v7, v7, v8
	v_exp_f32_e32 v7, v7
	v_cvt_i32_f32_e32 v8, v9
	v_cmp_ngt_f32_e32 vcc, s3, v6
	v_mul_f32_e32 v5, 0x3fb8aa3b, v3
	s_waitcnt lgkmcnt(0)
	v_ldexp_f32 v7, v7, v8
	v_cndmask_b32_e32 v7, 0, v7, vcc
	v_cmp_nlt_f32_e32 vcc, s4, v6
	v_rndne_f32_e32 v8, v5
	v_readlane_b32 s85, v255, 0
	v_cndmask_b32_e32 v6, v225, v7, vcc
	v_fma_f32 v7, v3, s6, -v5
	v_fmac_f32_e32 v7, 0x32a5705f, v3
	v_sub_f32_e32 v5, v5, v8
	v_add_f32_e32 v5, v5, v7
	v_exp_f32_e32 v5, v5
	v_cvt_i32_f32_e32 v7, v8
	v_cmp_ngt_f32_e32 vcc, s3, v3
	s_mov_b32 s3, s77
	v_readlane_b32 s29, v255, 18
	v_ldexp_f32 v5, v5, v7
	v_cndmask_b32_e32 v5, 0, v5, vcc
	v_cmp_nlt_f32_e32 vcc, s4, v3
	s_mul_i32 s4, s31, 0x4200
	s_add_i32 s4, s4, 0
	v_cndmask_b32_e32 v3, v225, v5, vcc
	v_sub_f32_e32 v3, v6, v3
	ds_read_b128 v[6:9], v200
	v_add_f32_e32 v3, v2, v3
	v_lshlrev_b32_e32 v5, 2, v195
	v_sub_f32_e32 v2, 1.0, v2
	v_readlane_b32 s84, v255, 34
	s_waitcnt lgkmcnt(0)
	v_rcp_f32_e32 v10, v6
	v_rcp_f32_e32 v11, v7
	v_rcp_f32_e32 v12, v8
	v_rcp_f32_e32 v13, v9
	global_load_dwordx4 v[6:9], v[156:157], off
	v_mul_f32_e32 v14, v66, v10
	v_mul_f32_e32 v50, v50, v10
	s_mul_hi_i32 s8, s18, 0x8600
	s_mul_i32 s9, s18, 0x8600
	s_waitcnt vmcnt(0)
	v_fma_f32 v14, -v3, v14, v6
	v_mul_u32_u24_e32 v6, 0x840, v194
	v_add3_u32 v5, s4, v5, v6
	v_mul_f32_e32 v6, v67, v11
	v_fma_f32 v15, -v3, v6, v7
	v_mul_f32_e32 v6, v68, v12
	v_fma_f32 v16, -v3, v6, v8
	v_mul_f32_e32 v6, v69, v13
	v_fma_f32 v17, -v3, v6, v9
	global_load_dwordx4 v[6:9], v[176:177], off
	s_waitcnt vmcnt(0)
	v_fma_f32 v6, -v3, v50, v6
	ds_write2_b32 v5, v14, v6 offset1:32
	v_mul_f32_e32 v6, v51, v11
	v_fma_f32 v6, -v3, v6, v7
	ds_write2_b32 v5, v15, v6 offset0:132 offset1:164
	v_mul_f32_e32 v6, v52, v12
	v_fma_f32 v6, -v3, v6, v8
	v_add_u32_e32 v14, 0x400, v5
	ds_write2_b32 v14, v16, v6 offset0:8 offset1:40
	v_mul_f32_e32 v6, v53, v13
	v_fma_f32 v6, -v3, v6, v9
	ds_write2_b32 v14, v17, v6 offset0:140 offset1:172
	global_load_dwordx4 v[6:9], v[174:175], off
	v_mul_f32_e32 v15, v34, v10
	v_mul_f32_e32 v10, v18, v10
	s_waitcnt vmcnt(0)
	v_fma_f32 v15, -v3, v15, v6
	v_mul_f32_e32 v6, v35, v11
	v_fma_f32 v16, -v3, v6, v7
	v_mul_f32_e32 v6, v36, v12
	v_fma_f32 v17, -v3, v6, v8
	v_mul_f32_e32 v6, v37, v13
	v_fma_f32 v34, -v3, v6, v9
	global_load_dwordx4 v[6:9], v[172:173], off
	s_waitcnt vmcnt(0)
	v_fma_f32 v6, -v3, v10, v6
	ds_write2_b32 v5, v15, v6 offset0:64 offset1:96
	v_mul_f32_e32 v6, v19, v11
	v_fma_f32 v6, -v3, v6, v7
	ds_write2_b32 v5, v16, v6 offset0:196 offset1:228
	v_mul_f32_e32 v6, v20, v12
	v_fma_f32 v6, -v3, v6, v8
	ds_write2_b32 v14, v17, v6 offset0:72 offset1:104
	v_mul_f32_e32 v6, v21, v13
	v_fma_f32 v6, -v3, v6, v9
	ds_write2_b32 v14, v34, v6 offset0:204 offset1:236
	ds_read_b128 v[6:9], v200 offset:32
	s_waitcnt lgkmcnt(0)
	v_rcp_f32_e32 v10, v6
	v_rcp_f32_e32 v11, v7
	v_rcp_f32_e32 v12, v8
	v_rcp_f32_e32 v13, v9
	global_load_dwordx4 v[6:9], v[156:157], off offset:1024
	v_mul_f32_e32 v14, v70, v10
	v_mul_f32_e32 v18, v54, v10
	s_waitcnt vmcnt(0)
	v_fma_f32 v14, -v3, v14, v6
	v_mul_f32_e32 v6, v71, v11
	v_fma_f32 v15, -v3, v6, v7
	v_mul_f32_e32 v6, v72, v12
	v_fma_f32 v16, -v3, v6, v8
	v_mul_f32_e32 v6, v73, v13
	v_fma_f32 v17, -v3, v6, v9
	global_load_dwordx4 v[6:9], v[170:171], off
	s_waitcnt vmcnt(0)
; #define LAS __attribute__((address_space(3)))
; __device__ __forceinline__ int crow(int r, int hi) { return (r & 3) + 8 * (r >> 2) + 4 * hi; }
; template <int MODE, bool FIXED>
; __device__ __forceinline__ void attn_unit(LAS unsigned char* lds, unsigned char* ws, const AttnParams& P, int l, int Tp, int sq, int h, int qb, int part, int np, int pslot, int tid, int wave, int lane) {
;     ...
;         for (int r4 = 0; r4 < 4; ++r4) { float rl[4];
; #pragma unroll
;             for (int e = 0; e < 4; ++e) rl[e] = __builtin_amdgcn_rcpf(li_l[crow(4 * r4 + e, hi)]);
; #pragma unroll
;             for (int d = 0; d < 4; ++d) { f32x4 pk = {0.f, 0.f, 0.f, 0.f}; if (MODE == 1) pk = *(const f32x4*)(park + (d * 4 + r4) * 256);
; #pragma unroll
;                 for (int e = 0; e < 4; ++e) { float v = o[d][4 * r4 + e] * rl[e]; if (MODE == 1) v = pk[e] - lam * v;
;                     ost[crow(4 * r4 + e, hi) * 132 + d * 32 + r32] = v; } } }
;     }
;     asm volatile("s_waitcnt lgkmcnt(0)" ::: "memory");
;     {
;         const int row = lane >> 1, half = lane & 1;
;         const LAS f32x4* src = (const LAS f32x4*)(ost + row * 132 + half * 64);
;         float v[64];
; #pragma unroll
;         for (int k = 0; k < 16; ++k) { const f32x4 t = src[k]; v[4 * k] = t.x; v[4 * k + 1] = t.y; v[4 * k + 2] = t.z; v[4 * k + 3] = t.w; }
	v_fma_f32 v6, -v3, v18, v6
	v_add_u32_e32 v18, 0x1000, v5
	ds_write2_b32 v18, v14, v6 offset0:32 offset1:64
	v_mul_f32_e32 v6, v55, v11
	v_fma_f32 v6, -v3, v6, v7
	ds_write2_b32 v18, v15, v6 offset0:164 offset1:196
	v_mul_f32_e32 v6, v56, v12
	v_fma_f32 v6, -v3, v6, v8
	v_add_u32_e32 v14, 0x1400, v5
	ds_write2_b32 v14, v16, v6 offset0:40 offset1:72
	v_mul_f32_e32 v6, v57, v13
	v_fma_f32 v6, -v3, v6, v9
	ds_write2_b32 v14, v17, v6 offset0:172 offset1:204
	global_load_dwordx4 v[6:9], v[168:169], off
	v_mul_f32_e32 v15, v38, v10
	v_mul_f32_e32 v10, v22, v10
	s_waitcnt vmcnt(0)
	v_fma_f32 v15, -v3, v15, v6
	v_mul_f32_e32 v6, v39, v11
	v_fma_f32 v16, -v3, v6, v7
	v_mul_f32_e32 v6, v40, v12
	v_fma_f32 v17, -v3, v6, v8
	v_mul_f32_e32 v6, v41, v13
	v_fma_f32 v19, -v3, v6, v9
	global_load_dwordx4 v[6:9], v[166:167], off
	s_waitcnt vmcnt(0)
	v_fma_f32 v6, -v3, v10, v6
	ds_write2_b32 v18, v15, v6 offset0:96 offset1:128
	v_mul_f32_e32 v6, v23, v11
	v_fma_f32 v6, -v3, v6, v7
	v_add_u32_e32 v7, 0x1200, v5
	ds_write2_b32 v7, v16, v6 offset0:100 offset1:132
	v_mul_f32_e32 v6, v24, v12
	v_fma_f32 v6, -v3, v6, v8
	ds_write2_b32 v14, v17, v6 offset0:104 offset1:136
	v_mul_f32_e32 v6, v25, v13
	v_fma_f32 v6, -v3, v6, v9
	v_add_u32_e32 v7, 0x1600, v5
	ds_write2_b32 v7, v19, v6 offset0:108 offset1:140
	ds_read_b128 v[10:13], v200 offset:64
	s_waitcnt lgkmcnt(0)
	v_rcp_f32_e32 v9, v10
	v_rcp_f32_e32 v8, v11
	v_rcp_f32_e32 v7, v12
	v_rcp_f32_e32 v6, v13
	global_load_dwordx4 v[10:13], v[156:157], off offset:2048
	v_mul_f32_e32 v14, v74, v9
	v_mul_f32_e32 v18, v58, v9
	s_waitcnt vmcnt(0)
	v_fma_f32 v14, -v3, v14, v10
	v_mul_f32_e32 v10, v75, v8
	v_fma_f32 v15, -v3, v10, v11
	v_mul_f32_e32 v10, v76, v7
	v_fma_f32 v16, -v3, v10, v12
	v_mul_f32_e32 v10, v77, v6
	v_fma_f32 v17, -v3, v10, v13
	global_load_dwordx4 v[10:13], v[164:165], off
	s_waitcnt vmcnt(0)
	v_fma_f32 v10, -v3, v18, v10
	v_add_u32_e32 v18, 0x2000, v5
	ds_write2_b32 v18, v14, v10 offset0:64 offset1:96
	v_mul_f32_e32 v10, v59, v8
	v_fma_f32 v10, -v3, v10, v11
	ds_write2_b32 v18, v15, v10 offset0:196 offset1:228
	v_mul_f32_e32 v10, v60, v7
	v_fma_f32 v10, -v3, v10, v12
	v_add_u32_e32 v14, 0x2400, v5
	ds_write2_b32 v14, v16, v10 offset0:72 offset1:104
	v_mul_f32_e32 v10, v61, v6
	v_fma_f32 v10, -v3, v10, v13
	ds_write2_b32 v14, v17, v10 offset0:204 offset1:236
	global_load_dwordx4 v[10:13], v[162:163], off
	v_mul_f32_e32 v15, v42, v9
	v_mul_f32_e32 v9, v26, v9
	s_waitcnt vmcnt(0)
	v_fma_f32 v15, -v3, v15, v10
	v_mul_f32_e32 v10, v43, v8
	v_fma_f32 v16, -v3, v10, v11
	v_mul_f32_e32 v10, v44, v7
	v_fma_f32 v17, -v3, v10, v12
	v_mul_f32_e32 v10, v45, v6
	v_fma_f32 v19, -v3, v10, v13
	global_load_dwordx4 v[10:13], v[160:161], off
	v_mul_f32_e32 v7, v28, v7
	v_mul_f32_e32 v8, v27, v8
	v_mul_f32_e32 v6, v29, v6
	s_waitcnt vmcnt(0)
	v_fma_f32 v7, -v3, v7, v12
	v_fma_f32 v9, -v3, v9, v10
	v_fma_f32 v8, -v3, v8, v11
	ds_write2_b32 v14, v17, v7 offset0:136 offset1:168
	v_fma_f32 v6, -v3, v6, v13
	v_add_u32_e32 v7, 0x2800, v5
	ds_write2_b32 v18, v15, v9 offset0:128 offset1:160
	ds_write2_b32 v14, v16, v8 offset0:4 offset1:36
	ds_write2_b32 v7, v19, v6 offset0:12 offset1:44
	ds_read_b128 v[6:9], v200 offset:96
	s_waitcnt lgkmcnt(0)
	v_rcp_f32_e32 v13, v6
	v_rcp_f32_e32 v12, v7
	v_rcp_f32_e32 v11, v8
	v_rcp_f32_e32 v10, v9
	global_load_dwordx4 v[6:9], v[156:157], off offset:3072
	v_mul_f32_e32 v14, v78, v13
	v_mul_f32_e32 v18, v62, v13
	s_waitcnt vmcnt(0)
	v_fma_f32 v14, -v3, v14, v6
	v_mul_f32_e32 v6, v79, v12
	v_fma_f32 v15, -v3, v6, v7
	v_mul_f32_e32 v6, v80, v11
	v_fma_f32 v16, -v3, v6, v8
	v_mul_f32_e32 v6, v81, v10
	v_fma_f32 v17, -v3, v6, v9
	global_load_dwordx4 v[6:9], v[158:159], off
	s_waitcnt vmcnt(0)
	v_fma_f32 v6, -v3, v18, v6
	v_add_u32_e32 v18, 0x3000, v5
	ds_write2_b32 v18, v14, v6 offset0:96 offset1:128
	v_mul_f32_e32 v6, v63, v12
	v_fma_f32 v6, -v3, v6, v7
	v_add_u32_e32 v7, 0x3200, v5
	ds_write2_b32 v7, v15, v6 offset0:100 offset1:132
	v_mul_f32_e32 v6, v64, v11
	v_fma_f32 v6, -v3, v6, v8
	v_add_u32_e32 v14, 0x3400, v5
	ds_write2_b32 v14, v16, v6 offset0:104 offset1:136
	v_mul_f32_e32 v6, v65, v10
	v_fma_f32 v6, -v3, v6, v9
	v_add_u32_e32 v7, 0x3600, v5
	ds_write2_b32 v7, v17, v6 offset0:108 offset1:140
	global_load_dwordx4 v[6:9], v[154:155], off
	v_mul_f32_e32 v15, v46, v13
	v_mul_f32_e32 v13, v30, v13
	v_add_u32_e32 v5, 0x3800, v5
	s_waitcnt vmcnt(0)
	v_fma_f32 v15, -v3, v15, v6
	v_mul_f32_e32 v6, v47, v12
	v_fma_f32 v16, -v3, v6, v7
	v_mul_f32_e32 v6, v48, v11
	v_fma_f32 v17, -v3, v6, v8
	v_mul_f32_e32 v6, v49, v10
	v_fma_f32 v19, -v3, v6, v9
	global_load_dwordx4 v[6:9], v[152:153], off
	s_waitcnt vmcnt(0)
	v_fma_f32 v6, -v3, v13, v6
	ds_write2_b32 v18, v15, v6 offset0:160 offset1:192
	v_mul_f32_e32 v6, v31, v12
	v_fma_f32 v6, -v3, v6, v7
	ds_write2_b32 v14, v16, v6 offset0:36 offset1:68
	v_mul_f32_e32 v6, v32, v11
	v_fma_f32 v6, -v3, v6, v8
	ds_write2_b32 v14, v17, v6 offset0:168 offset1:200
	v_mul_f32_e32 v6, v33, v10
	v_fma_f32 v3, -v3, v6, v9
	ds_write2_b32 v5, v19, v3 offset0:44 offset1:76
	v_lshlrev_b32_e32 v3, 6, v193
	v_lshrrev_b32_e32 v5, 1, v193
	v_and_b32_e32 v76, 64, v3
	v_mul_u32_u24_e32 v6, 0x210, v5
	v_lshlrev_b32_e32 v3, 2, v76
	s_waitcnt lgkmcnt(0)
	v_add3_u32 v6, s4, v6, v3
	ds_read_b128 v[66:69], v6
	ds_read_b128 v[62:65], v6 offset:16
	ds_read_b128 v[58:61], v6 offset:32
	ds_read_b128 v[54:57], v6 offset:48
	ds_read_b128 v[50:53], v6 offset:64
	ds_read_b128 v[46:49], v6 offset:80
	ds_read_b128 v[42:45], v6 offset:96
	ds_read_b128 v[38:41], v6 offset:112
	ds_read_b128 v[34:37], v6 offset:128
	ds_read_b128 v[30:33], v6 offset:144
	ds_read_b128 v[26:29], v6 offset:160
	ds_read_b128 v[22:25], v6 offset:176
	ds_read_b128 v[18:21], v6 offset:192
	ds_read_b128 v[14:17], v6 offset:208
	ds_read_b128 v[10:13], v6 offset:224
	ds_read_b128 v[6:9], v6 offset:240
	v_or_b32_e32 v70, s77, v5
	s_waitcnt lgkmcnt(14)
; __device__ __forceinline__ float bflo(unsigned w) { return __uint_as_float(w << 16); }
; __device__ __forceinline__ float bfhi(unsigned w) { return __uint_as_float(w & 0xffff0000u); }
; __device__ __forceinline__ float bflo(unsigned w) { return __uint_as_float(w << 16); }
; __device__ __forceinline__ float bfhi(unsigned w) { return __uint_as_float(w & 0xffff0000u); }
; __device__ __forceinline__ unsigned cvtpk(float lo, float hi) { const f32x2_t v = {lo, hi}; const bf16x2_t b = __builtin_convertvector(v, bf16x2_t); return __builtin_bit_cast(unsigned, b); }
; #define norm_gain INP(2)
; template <int MODE, bool FIXED>
; __device__ __forceinline__ void attn_unit(LAS unsigned char* lds, unsigned char* ws, const AttnParams& P, int l, int Tp, int sq, int h, int qb, int part, int np, int pslot, int tid, int wave, int lane) {
;     ...
;         const size_t grow = (size_t)(seq0 + q0 + wave * 32 + row);
;         float rs = 1.f;
;         if (MODE == 1) { float ss = 0.f;
; #pragma unroll
;             for (int e = 0; e < 64; ++e) ss += v[e] * v[e];
;             ss += xshfl<1>(ss); rs = (1.0f / sqrtf(ss * (1.0f / 128.0f) + NORM_EPS)) * (1.0f - lin); }
;         const v4u* zp = (const v4u*)(PROJ + grow * LDP + zcol + half * 64);
;         bf16* yb = (bf16*)(ws + WS_Y + (MODE ? 2 : 1) * SZ_Y1) + grow * 1024 + h * 128 + half * 64;
; #pragma unroll
;         for (int k = 0; k < 8; ++k) { const v4u zw = zp[k];
;             const float z[8] = {bflo(zw.x), bfhi(zw.x), bflo(zw.y), bfhi(zw.y), bflo(zw.z), bfhi(zw.z), bflo(zw.w), bfhi(zw.w)};
;             float y[8];
; #pragma unroll
;             for (int e = 0; e < 8; ++e) { float g = 1.f; if (MODE == 1) g = P.norm_gain[half * 64 + 8 * k + e]; y[e] = v[8 * k + e] * rs * g * z[e]; }
;             v4u w; w.x = cvtpk(y[0], y[1]); w.y = cvtpk(y[2], y[3]); w.z = cvtpk(y[4], y[5]); w.w = cvtpk(y[6], y[7]);
;             *(v4u*)(yb + 8 * k) = w; }
	v_mul_f32_e32 v5, v67, v67
	v_fmac_f32_e32 v5, v66, v66
	v_fmac_f32_e32 v5, v68, v68
	v_fmac_f32_e32 v5, v69, v69
	v_fmac_f32_e32 v5, v62, v62
	v_fmac_f32_e32 v5, v63, v63
	v_fmac_f32_e32 v5, v64, v64
	v_fmac_f32_e32 v5, v65, v65
	s_waitcnt lgkmcnt(13)
	v_fmac_f32_e32 v5, v58, v58
	v_fmac_f32_e32 v5, v59, v59
	v_fmac_f32_e32 v5, v60, v60
	v_fmac_f32_e32 v5, v61, v61
	s_waitcnt lgkmcnt(12)
	v_fmac_f32_e32 v5, v54, v54
	v_fmac_f32_e32 v5, v55, v55
	v_fmac_f32_e32 v5, v56, v56
	v_fmac_f32_e32 v5, v57, v57
	s_waitcnt lgkmcnt(11)
	v_fmac_f32_e32 v5, v50, v50
	v_fmac_f32_e32 v5, v51, v51
	v_fmac_f32_e32 v5, v52, v52
	v_fmac_f32_e32 v5, v53, v53
	s_waitcnt lgkmcnt(10)
	v_fmac_f32_e32 v5, v46, v46
	v_fmac_f32_e32 v5, v47, v47
	v_fmac_f32_e32 v5, v48, v48
	v_fmac_f32_e32 v5, v49, v49
	s_waitcnt lgkmcnt(9)
	v_fmac_f32_e32 v5, v42, v42
	v_fmac_f32_e32 v5, v43, v43
	v_fmac_f32_e32 v5, v44, v44
	v_fmac_f32_e32 v5, v45, v45
	s_waitcnt lgkmcnt(8)
	v_fmac_f32_e32 v5, v38, v38
	v_fmac_f32_e32 v5, v39, v39
	v_fmac_f32_e32 v5, v40, v40
	v_fmac_f32_e32 v5, v41, v41
	s_waitcnt lgkmcnt(7)
	v_fmac_f32_e32 v5, v34, v34
	v_fmac_f32_e32 v5, v35, v35
	v_fmac_f32_e32 v5, v36, v36
	v_fmac_f32_e32 v5, v37, v37
	s_waitcnt lgkmcnt(6)
	v_fmac_f32_e32 v5, v30, v30
	v_fmac_f32_e32 v5, v31, v31
	v_fmac_f32_e32 v5, v32, v32
	v_fmac_f32_e32 v5, v33, v33
	s_waitcnt lgkmcnt(5)
	v_fmac_f32_e32 v5, v26, v26
	v_fmac_f32_e32 v5, v27, v27
	v_fmac_f32_e32 v5, v28, v28
	v_fmac_f32_e32 v5, v29, v29
	s_waitcnt lgkmcnt(4)
	v_fmac_f32_e32 v5, v22, v22
	v_fmac_f32_e32 v5, v23, v23
	v_fmac_f32_e32 v5, v24, v24
	v_fmac_f32_e32 v5, v25, v25
	s_waitcnt lgkmcnt(3)
	v_fmac_f32_e32 v5, v18, v18
	v_fmac_f32_e32 v5, v19, v19
	v_fmac_f32_e32 v5, v20, v20
	v_fmac_f32_e32 v5, v21, v21
	s_waitcnt lgkmcnt(2)
	v_fmac_f32_e32 v5, v14, v14
	v_fmac_f32_e32 v5, v15, v15
	v_fmac_f32_e32 v5, v16, v16
	v_fmac_f32_e32 v5, v17, v17
	s_waitcnt lgkmcnt(1)
	v_fmac_f32_e32 v5, v10, v10
	v_fmac_f32_e32 v5, v11, v11
	v_pk_mul_f32 v[72:73], v[12:13], v[12:13]
	s_waitcnt lgkmcnt(0)
	v_pk_mul_f32 v[74:75], v[6:7], v[6:7]
	v_add_f32_e32 v5, v72, v5
	v_add_f32_e32 v5, v73, v5
	v_add_f32_e32 v5, v74, v5
	v_pk_mul_f32 v[72:73], v[8:9], v[8:9]
	v_add_f32_e32 v5, v75, v5
	v_add_f32_e32 v5, v72, v5
	v_add_f32_e32 v5, v73, v5
	ds_swizzle_b32 v72, v5 offset:swizzle(SWAP,1)
	s_mov_b32 s77, s61
	v_ashrrev_i32_e32 v71, 31, v70
	s_waitcnt lgkmcnt(0)
	v_add_f32_e32 v5, v5, v72
	v_fmamk_f32 v5, v5, 0x3c000000, v220
	v_cmp_gt_f32_e32 vcc, s33, v5
	v_mul_f32_e32 v72, 0x4f800000, v5
	s_nop 0
	v_cndmask_b32_e32 v5, v5, v72, vcc
	v_sqrt_f32_e32 v72, v5
	s_nop 0
	v_add_u32_e32 v73, -1, v72
	v_fma_f32 v74, -v73, v72, v5
	v_cmp_ge_f32_e64 s[4:5], 0, v74
	v_add_u32_e32 v74, 1, v72
	s_nop 0
	v_cndmask_b32_e64 v73, v72, v73, s[4:5]
	v_fma_f32 v72, -v74, v72, v5
	v_cmp_lt_f32_e64 s[4:5], 0, v72
	s_nop 1
	v_cndmask_b32_e64 v72, v73, v74, s[4:5]
	v_mul_f32_e32 v73, 0x37800000, v72
	v_cndmask_b32_e32 v72, v72, v73, vcc
	v_cmp_class_f32_e32 vcc, v5, v221
	s_nop 1
	v_cndmask_b32_e32 v5, v72, v5, vcc
	v_div_scale_f32 v72, s[4:5], v5, v5, 1.0
	v_rcp_f32_e32 v73, v72
	s_nop 0
	v_fma_f32 v74, -v72, v73, 1.0
	v_fmac_f32_e32 v73, v74, v73
	v_div_scale_f32 v74, vcc, 1.0, v5, 1.0
	v_mul_f32_e32 v75, v74, v73
	v_fma_f32 v77, -v72, v75, v74
	v_fmac_f32_e32 v75, v77, v73
	v_fma_f32 v72, -v72, v75, v74
	v_div_fmas_f32 v72, v72, v73, v75
	v_div_fixup_f32 v5, v72, v5, 1.0
	v_mov_b64_e32 v[72:73], s[50:51]
	v_mad_i64_i32 v[72:73], s[4:5], v70, s70, v[72:73]
	v_lshl_add_u64 v[72:73], v[72:73], 0, s[76:77]
	v_lshlrev_b32_e32 v74, 1, v76
	v_mov_b32_e32 v75, v4
	v_lshl_add_u64 v[76:77], v[72:73], 0, v[74:75]
	s_mov_b64 s[4:5], 0x4c00
	v_lshl_add_u64 v[72:73], v[76:77], 0, s[4:5]
	v_readlane_b32 s4, v252, 38
	v_lshlrev_b64 v[70:71], 11, v[70:71]
	v_readlane_b32 s5, v252, 39
	v_mul_f32_e32 v2, v2, v5
	v_pk_mul_f32 v[68:69], v[68:69], v[2:3] op_sel_hi:[1,0]
	v_lshl_add_u64 v[70:71], s[4:5], 0, v[70:71]
	v_lshl_add_u64 v[70:71], v[70:71], 0, s[76:77]
	s_mov_b32 s77, s3
	s_movk_i32 s3, 0x4000
	v_lshl_add_u64 v[70:71], v[70:71], 0, v[74:75]
	v_add_co_u32_e32 v74, vcc, s3, v76
	v_pk_mul_f32 v[62:63], v[62:63], v[2:3] op_sel_hi:[1,0]
	s_nop 0
	v_addc_co_u32_e32 v75, vcc, 0, v77, vcc
	global_load_dwordx4 v[74:77], v[74:75], off offset:3072
	s_nop 0
	global_load_dwordx4 v[78:81], v[72:73], off offset:48
	global_load_dwordx4 v[82:85], v[72:73], off offset:32
	global_load_dwordx4 v[86:89], v[72:73], off offset:16
	global_load_dwordx4 v[90:93], v3, s[38:39] offset:16
	global_load_dwordx4 v[94:97], v3, s[38:39]
	v_pk_mul_f32 v[66:67], v[66:67], v[2:3] op_sel_hi:[1,0]
	v_pk_mul_f32 v[64:65], v[64:65], v[2:3] op_sel_hi:[1,0]
	v_pk_mul_f32 v[58:59], v[58:59], v[2:3] op_sel_hi:[1,0]
	v_pk_mul_f32 v[60:61], v[60:61], v[2:3] op_sel_hi:[1,0]
	v_pk_mul_f32 v[54:55], v[54:55], v[2:3] op_sel_hi:[1,0]
	v_pk_mul_f32 v[56:57], v[56:57], v[2:3] op_sel_hi:[1,0]
	v_pk_mul_f32 v[50:51], v[50:51], v[2:3] op_sel_hi:[1,0]
	v_pk_mul_f32 v[52:53], v[52:53], v[2:3] op_sel_hi:[1,0]
	v_pk_mul_f32 v[46:47], v[46:47], v[2:3] op_sel_hi:[1,0]
	v_pk_mul_f32 v[48:49], v[48:49], v[2:3] op_sel_hi:[1,0]
	v_pk_mul_f32 v[42:43], v[42:43], v[2:3] op_sel_hi:[1,0]
	v_pk_mul_f32 v[44:45], v[44:45], v[2:3] op_sel_hi:[1,0]
	v_pk_mul_f32 v[38:39], v[38:39], v[2:3] op_sel_hi:[1,0]
	v_pk_mul_f32 v[40:41], v[40:41], v[2:3] op_sel_hi:[1,0]
	v_pk_mul_f32 v[36:37], v[36:37], v[2:3] op_sel_hi:[1,0]
	v_pk_mul_f32 v[30:31], v[30:31], v[2:3] op_sel_hi:[1,0]
	v_pk_mul_f32 v[34:35], v[34:35], v[2:3] op_sel_hi:[1,0]
	v_pk_mul_f32 v[32:33], v[32:33], v[2:3] op_sel_hi:[1,0]
	v_pk_mul_f32 v[26:27], v[26:27], v[2:3] op_sel_hi:[1,0]
	v_pk_mul_f32 v[28:29], v[28:29], v[2:3] op_sel_hi:[1,0]
	v_pk_mul_f32 v[22:23], v[22:23], v[2:3] op_sel_hi:[1,0]
	v_pk_mul_f32 v[24:25], v[24:25], v[2:3] op_sel_hi:[1,0]
	v_pk_mul_f32 v[18:19], v[18:19], v[2:3] op_sel_hi:[1,0]
	v_pk_mul_f32 v[20:21], v[20:21], v[2:3] op_sel_hi:[1,0]
	v_pk_mul_f32 v[14:15], v[14:15], v[2:3] op_sel_hi:[1,0]
	v_pk_mul_f32 v[16:17], v[16:17], v[2:3] op_sel_hi:[1,0]
	v_pk_mul_f32 v[10:11], v[10:11], v[2:3] op_sel_hi:[1,0]
	v_pk_mul_f32 v[12:13], v[12:13], v[2:3] op_sel_hi:[1,0]
	v_pk_mul_f32 v[6:7], v[6:7], v[2:3] op_sel_hi:[1,0]
	s_waitcnt vmcnt(5)
; __device__ __forceinline__ float bflo(unsigned w) { return __uint_as_float(w << 16); }
; __device__ __forceinline__ float bfhi(unsigned w) { return __uint_as_float(w & 0xffff0000u); }
; __device__ __forceinline__ float bflo(unsigned w) { return __uint_as_float(w << 16); }
; __device__ __forceinline__ float bfhi(unsigned w) { return __uint_as_float(w & 0xffff0000u); }
; __device__ __forceinline__ unsigned cvtpk(float lo, float hi) { const f32x2_t v = {lo, hi}; const bf16x2_t b = __builtin_convertvector(v, bf16x2_t); return __builtin_bit_cast(unsigned, b); }
; #define norm_gain INP(2)
; template <int MODE, bool FIXED>
; __device__ __forceinline__ void attn_unit(LAS unsigned char* lds, unsigned char* ws, const AttnParams& P, int l, int Tp, int sq, int h, int qb, int part, int np, int pslot, int tid, int wave, int lane) {
;     ...
;         const v4u* zp = (const v4u*)(PROJ + grow * LDP + zcol + half * 64);
;         bf16* yb = (bf16*)(ws + WS_Y + (MODE ? 2 : 1) * SZ_Y1) + grow * 1024 + h * 128 + half * 64;
; #pragma unroll
;         for (int k = 0; k < 8; ++k) { const v4u zw = zp[k];
;             const float z[8] = {bflo(zw.x), bfhi(zw.x), bflo(zw.y), bfhi(zw.y), bflo(zw.z), bfhi(zw.z), bflo(zw.w), bfhi(zw.w)};
;             float y[8];
; #pragma unroll
;             for (int e = 0; e < 8; ++e) { float g = 1.f; if (MODE == 1) g = P.norm_gain[half * 64 + 8 * k + e]; y[e] = v[8 * k + e] * rs * g * z[e]; }
;             v4u w; w.x = cvtpk(y[0], y[1]); w.y = cvtpk(y[2], y[3]); w.z = cvtpk(y[4], y[5]); w.w = cvtpk(y[6], y[7]);
;             *(v4u*)(yb + 8 * k) = w; }
	v_lshlrev_b32_e32 v98, 16, v74
	v_and_b32_e32 v99, 0xffff0000, v74
	v_lshlrev_b32_e32 v74, 16, v75
	v_and_b32_e32 v75, 0xffff0000, v75
	s_waitcnt vmcnt(0)
	v_pk_mul_f32 v[68:69], v[96:97], v[68:69]
	v_pk_mul_f32 v[62:63], v[90:91], v[62:63]
	v_pk_mul_f32 v[68:69], v[68:69], v[74:75]
	v_lshlrev_b32_e32 v74, 16, v76
	v_and_b32_e32 v75, 0xffff0000, v76
	v_pk_mul_f32 v[66:67], v[94:95], v[66:67]
	v_pk_mul_f32 v[74:75], v[62:63], v[74:75]
	v_lshlrev_b32_e32 v62, 16, v77
	v_and_b32_e32 v63, 0xffff0000, v77
	v_pk_mul_f32 v[64:65], v[92:93], v[64:65]
	v_pk_mul_f32 v[66:67], v[66:67], v[98:99]
	v_pk_mul_f32 v[76:77], v[64:65], v[62:63]
	v_cvt_pk_bf16_f32 v62, v66, v67
	v_cvt_pk_bf16_f32 v63, v68, v69
	v_cvt_pk_bf16_f32 v64, v74, v75
	v_cvt_pk_bf16_f32 v65, v76, v77
	global_store_dwordx4 v[70:71], v[62:65], off
	global_load_dwordx4 v[62:65], v3, s[38:39] offset:48
	s_nop 0
	global_load_dwordx4 v[66:69], v3, s[38:39] offset:32
	v_lshlrev_b32_e32 v74, 16, v86
	v_and_b32_e32 v75, 0xffff0000, v86
	s_waitcnt vmcnt(1)
	v_pk_mul_f32 v[54:55], v[62:63], v[54:55]
	s_waitcnt vmcnt(0)
	v_pk_mul_f32 v[58:59], v[66:67], v[58:59]
	v_lshlrev_b32_e32 v66, 16, v87
	v_and_b32_e32 v67, 0xffff0000, v87
	v_pk_mul_f32 v[60:61], v[68:69], v[60:61]
	v_pk_mul_f32 v[56:57], v[64:65], v[56:57]
	v_pk_mul_f32 v[60:61], v[60:61], v[66:67]
	v_lshlrev_b32_e32 v66, 16, v88
	v_and_b32_e32 v67, 0xffff0000, v88
	v_pk_mul_f32 v[62:63], v[54:55], v[66:67]
	v_lshlrev_b32_e32 v54, 16, v89
	v_and_b32_e32 v55, 0xffff0000, v89
	v_pk_mul_f32 v[58:59], v[58:59], v[74:75]
	v_pk_mul_f32 v[64:65], v[56:57], v[54:55]
	v_cvt_pk_bf16_f32 v54, v58, v59
	v_cvt_pk_bf16_f32 v55, v60, v61
	v_cvt_pk_bf16_f32 v56, v62, v63
	v_cvt_pk_bf16_f32 v57, v64, v65
	global_store_dwordx4 v[70:71], v[54:57], off offset:16
	global_load_dwordx4 v[54:57], v3, s[38:39] offset:80
	s_nop 0
	global_load_dwordx4 v[58:61], v3, s[38:39] offset:64
	v_lshlrev_b32_e32 v62, 16, v82
	v_and_b32_e32 v63, 0xffff0000, v82
	s_waitcnt vmcnt(1)
	v_pk_mul_f32 v[46:47], v[54:55], v[46:47]
	s_waitcnt vmcnt(0)
	v_pk_mul_f32 v[50:51], v[58:59], v[50:51]
	v_lshlrev_b32_e32 v58, 16, v83
	v_and_b32_e32 v59, 0xffff0000, v83
	v_pk_mul_f32 v[52:53], v[60:61], v[52:53]
	v_pk_mul_f32 v[48:49], v[56:57], v[48:49]
	v_pk_mul_f32 v[52:53], v[52:53], v[58:59]
	v_lshlrev_b32_e32 v58, 16, v84
	v_and_b32_e32 v59, 0xffff0000, v84
	v_pk_mul_f32 v[54:55], v[46:47], v[58:59]
	v_lshlrev_b32_e32 v46, 16, v85
	v_and_b32_e32 v47, 0xffff0000, v85
	v_pk_mul_f32 v[50:51], v[50:51], v[62:63]
	v_pk_mul_f32 v[56:57], v[48:49], v[46:47]
	v_cvt_pk_bf16_f32 v46, v50, v51
	v_cvt_pk_bf16_f32 v47, v52, v53
	v_cvt_pk_bf16_f32 v48, v54, v55
	v_cvt_pk_bf16_f32 v49, v56, v57
	global_store_dwordx4 v[70:71], v[46:49], off offset:32
	global_load_dwordx4 v[46:49], v3, s[38:39] offset:112
	s_nop 0
	global_load_dwordx4 v[50:53], v3, s[38:39] offset:96
	v_lshlrev_b32_e32 v54, 16, v78
	v_and_b32_e32 v55, 0xffff0000, v78
	s_waitcnt vmcnt(1)
	v_pk_mul_f32 v[38:39], v[46:47], v[38:39]
	s_waitcnt vmcnt(0)
	v_pk_mul_f32 v[42:43], v[50:51], v[42:43]
	v_lshlrev_b32_e32 v50, 16, v79
	v_and_b32_e32 v51, 0xffff0000, v79
	v_pk_mul_f32 v[44:45], v[52:53], v[44:45]
	v_pk_mul_f32 v[40:41], v[48:49], v[40:41]
	v_pk_mul_f32 v[44:45], v[44:45], v[50:51]
	v_lshlrev_b32_e32 v50, 16, v80
	v_and_b32_e32 v51, 0xffff0000, v80
	v_pk_mul_f32 v[46:47], v[38:39], v[50:51]
	v_lshlrev_b32_e32 v38, 16, v81
	v_and_b32_e32 v39, 0xffff0000, v81
	v_pk_mul_f32 v[42:43], v[42:43], v[54:55]
	v_pk_mul_f32 v[48:49], v[40:41], v[38:39]
	v_cvt_pk_bf16_f32 v38, v42, v43
	v_cvt_pk_bf16_f32 v39, v44, v45
	v_cvt_pk_bf16_f32 v40, v46, v47
	v_cvt_pk_bf16_f32 v41, v48, v49
	global_store_dwordx4 v[70:71], v[38:41], off offset:48
	global_load_dwordx4 v[38:41], v[72:73], off offset:112
	s_nop 0
	global_load_dwordx4 v[42:45], v[72:73], off offset:96
	global_load_dwordx4 v[46:49], v[72:73], off offset:80
	global_load_dwordx4 v[54:57], v[72:73], off offset:64
	global_load_dwordx4 v[50:53], v3, s[38:39] offset:144
	global_load_dwordx4 v[60:63], v3, s[38:39] offset:128
	s_waitcnt vmcnt(2)
; __device__ __forceinline__ float bflo(unsigned w) { return __uint_as_float(w << 16); }
; __device__ __forceinline__ float bfhi(unsigned w) { return __uint_as_float(w & 0xffff0000u); }
; __device__ __forceinline__ float bflo(unsigned w) { return __uint_as_float(w << 16); }
; __device__ __forceinline__ float bfhi(unsigned w) { return __uint_as_float(w & 0xffff0000u); }
; __device__ __forceinline__ unsigned cvtpk(float lo, float hi) { const f32x2_t v = {lo, hi}; const bf16x2_t b = __builtin_convertvector(v, bf16x2_t); return __builtin_bit_cast(unsigned, b); }
; #define norm_gain INP(2)
; template <int MODE, bool FIXED>
; __device__ __forceinline__ void attn_unit(LAS unsigned char* lds, unsigned char* ws, const AttnParams& P, int l, int Tp, int sq, int h, int qb, int part, int np, int pslot, int tid, int wave, int lane) {
;     ...
;         const v4u* zp = (const v4u*)(PROJ + grow * LDP + zcol + half * 64);
;         bf16* yb = (bf16*)(ws + WS_Y + (MODE ? 2 : 1) * SZ_Y1) + grow * 1024 + h * 128 + half * 64;
; #pragma unroll
;         for (int k = 0; k < 8; ++k) { const v4u zw = zp[k];
;             const float z[8] = {bflo(zw.x), bfhi(zw.x), bflo(zw.y), bfhi(zw.y), bflo(zw.z), bfhi(zw.z), bflo(zw.w), bfhi(zw.w)};
;             float y[8];
; #pragma unroll
;             for (int e = 0; e < 8; ++e) { float g = 1.f; if (MODE == 1) g = P.norm_gain[half * 64 + 8 * k + e]; y[e] = v[8 * k + e] * rs * g * z[e]; }
;             v4u w; w.x = cvtpk(y[0], y[1]); w.y = cvtpk(y[2], y[3]); w.z = cvtpk(y[4], y[5]); w.w = cvtpk(y[6], y[7]);
;             *(v4u*)(yb + 8 * k) = w; }
;     }
;     asm volatile("s_waitcnt lgkmcnt(0)" ::: "memory"); __builtin_amdgcn_s_barrier(); asm volatile("" ::: "memory");
	v_lshlrev_b32_e32 v58, 16, v54
	v_and_b32_e32 v59, 0xffff0000, v54
	v_lshlrev_b32_e32 v54, 16, v55
	v_and_b32_e32 v55, 0xffff0000, v55
	s_waitcnt vmcnt(0)
	v_pk_mul_f32 v[36:37], v[62:63], v[36:37]
	v_pk_mul_f32 v[30:31], v[50:51], v[30:31]
	v_pk_mul_f32 v[36:37], v[36:37], v[54:55]
	v_lshlrev_b32_e32 v54, 16, v56
	v_and_b32_e32 v55, 0xffff0000, v56
	v_pk_mul_f32 v[34:35], v[60:61], v[34:35]
	v_pk_mul_f32 v[50:51], v[30:31], v[54:55]
	v_lshlrev_b32_e32 v30, 16, v57
	v_and_b32_e32 v31, 0xffff0000, v57
	v_pk_mul_f32 v[32:33], v[52:53], v[32:33]
	v_pk_mul_f32 v[34:35], v[34:35], v[58:59]
	v_pk_mul_f32 v[52:53], v[32:33], v[30:31]
	v_cvt_pk_bf16_f32 v30, v34, v35
	v_cvt_pk_bf16_f32 v31, v36, v37
	v_cvt_pk_bf16_f32 v32, v50, v51
	v_cvt_pk_bf16_f32 v33, v52, v53
	global_store_dwordx4 v[70:71], v[30:33], off offset:64
	global_load_dwordx4 v[30:33], v3, s[38:39] offset:176
	s_nop 0
	global_load_dwordx4 v[34:37], v3, s[38:39] offset:160
	v_lshlrev_b32_e32 v50, 16, v46
	v_and_b32_e32 v51, 0xffff0000, v46
	s_waitcnt vmcnt(1)
	v_pk_mul_f32 v[22:23], v[30:31], v[22:23]
	s_waitcnt vmcnt(0)
	v_pk_mul_f32 v[26:27], v[34:35], v[26:27]
	v_lshlrev_b32_e32 v34, 16, v47
	v_and_b32_e32 v35, 0xffff0000, v47
	v_pk_mul_f32 v[28:29], v[36:37], v[28:29]
	v_pk_mul_f32 v[24:25], v[24:25], v[32:33]
	v_pk_mul_f32 v[28:29], v[28:29], v[34:35]
	v_lshlrev_b32_e32 v34, 16, v48
	v_and_b32_e32 v35, 0xffff0000, v48
	v_pk_mul_f32 v[30:31], v[22:23], v[34:35]
	v_lshlrev_b32_e32 v22, 16, v49
	v_and_b32_e32 v23, 0xffff0000, v49
	v_pk_mul_f32 v[26:27], v[26:27], v[50:51]
	v_pk_mul_f32 v[32:33], v[24:25], v[22:23]
	v_cvt_pk_bf16_f32 v22, v26, v27
	v_cvt_pk_bf16_f32 v23, v28, v29
	v_cvt_pk_bf16_f32 v24, v30, v31
	v_cvt_pk_bf16_f32 v25, v32, v33
	global_store_dwordx4 v[70:71], v[22:25], off offset:80
	global_load_dwordx4 v[22:25], v3, s[38:39] offset:208
	s_nop 0
	global_load_dwordx4 v[26:29], v3, s[38:39] offset:192
	v_lshlrev_b32_e32 v30, 16, v42
	v_and_b32_e32 v31, 0xffff0000, v42
	s_waitcnt vmcnt(1)
	v_pk_mul_f32 v[14:15], v[14:15], v[22:23]
	s_waitcnt vmcnt(0)
	v_pk_mul_f32 v[18:19], v[18:19], v[26:27]
	v_lshlrev_b32_e32 v26, 16, v43
	v_and_b32_e32 v27, 0xffff0000, v43
	v_pk_mul_f32 v[20:21], v[20:21], v[28:29]
	v_pk_mul_f32 v[16:17], v[16:17], v[24:25]
	v_pk_mul_f32 v[20:21], v[20:21], v[26:27]
	v_lshlrev_b32_e32 v26, 16, v44
	v_and_b32_e32 v27, 0xffff0000, v44
	v_pk_mul_f32 v[22:23], v[14:15], v[26:27]
	v_lshlrev_b32_e32 v14, 16, v45
	v_and_b32_e32 v15, 0xffff0000, v45
	v_pk_mul_f32 v[18:19], v[18:19], v[30:31]
	v_pk_mul_f32 v[24:25], v[16:17], v[14:15]
	v_cvt_pk_bf16_f32 v14, v18, v19
	v_cvt_pk_bf16_f32 v15, v20, v21
	v_cvt_pk_bf16_f32 v16, v22, v23
	v_cvt_pk_bf16_f32 v17, v24, v25
	global_store_dwordx4 v[70:71], v[14:17], off offset:96
	global_load_dwordx4 v[14:17], v3, s[38:39] offset:240
	s_nop 0
	global_load_dwordx4 v[18:21], v3, s[38:39] offset:224
	v_pk_mul_f32 v[2:3], v[8:9], v[2:3] op_sel_hi:[1,0]
	v_lshlrev_b32_e32 v22, 16, v38
	v_and_b32_e32 v23, 0xffff0000, v38
	s_waitcnt vmcnt(1)
	v_pk_mul_f32 v[6:7], v[6:7], v[14:15]
	s_waitcnt vmcnt(0)
	v_pk_mul_f32 v[10:11], v[10:11], v[18:19]
	v_lshlrev_b32_e32 v18, 16, v39
	v_and_b32_e32 v19, 0xffff0000, v39
	v_pk_mul_f32 v[12:13], v[12:13], v[20:21]
	v_pk_mul_f32 v[2:3], v[2:3], v[16:17]
	v_pk_mul_f32 v[12:13], v[12:13], v[18:19]
	v_lshlrev_b32_e32 v18, 16, v40
	v_and_b32_e32 v19, 0xffff0000, v40
	v_pk_mul_f32 v[14:15], v[6:7], v[18:19]
	v_lshlrev_b32_e32 v6, 16, v41
	v_and_b32_e32 v7, 0xffff0000, v41
	v_pk_mul_f32 v[10:11], v[10:11], v[22:23]
	v_pk_mul_f32 v[2:3], v[2:3], v[6:7]
	v_cvt_pk_bf16_f32 v6, v10, v11
	v_cvt_pk_bf16_f32 v7, v12, v13
	v_cvt_pk_bf16_f32 v8, v14, v15
	v_cvt_pk_bf16_f32 v9, v2, v3
	global_store_dwordx4 v[70:71], v[6:9], off offset:112
	s_barrier

; #define MFMA32(a, b, c) __builtin_amdgcn_mfma_f32_32x32x16_bf16((a), (b), (c), 0, 0, 0)
; #define SBAR() __builtin_amdgcn_sched_barrier(0)
; template <int D0> __device__ __forceinline__ void pv_one(f32x16& od, int vb, bf16x8 pa0, bf16x8 pa1, bf16x8 pa2, bf16x8 pa3) {
;     const s16x4 l0 = tr_read<v_rd_off(D0, 0, 0)>(vb), h0 = tr_read<v_rd_off(D0, 0, 1)>(vb), l1 = tr_read<v_rd_off(D0, 1, 0)>(vb), h1 = tr_read<v_rd_off(D0, 1, 1)>(vb);
;     const s16x4 l2 = tr_read<v_rd_off(D0, 2, 0)>(vb), h2 = tr_read<v_rd_off(D0, 2, 1)>(vb), l3 = tr_read<v_rd_off(D0, 3, 0)>(vb), h3 = tr_read<v_rd_off(D0, 3, 1)>(vb);
;     asm volatile("s_waitcnt lgkmcnt(0)" ::: "memory"); SBAR();
;     ...
;     od = MFMA32(pa0, PK(l0, h0), od); od = MFMA32(pa1, PK(l1, h1), od); od = MFMA32(pa2, PK(l2, h2), od); od = MFMA32(pa3, PK(l3, h3), od);
;     ...
; }
; __device__ __forceinline__ void pv_d0(f32x16* o, int vb, bf16x8 pa0, bf16x8 pa1, bf16x8 pa2, bf16x8 pa3) {
;     pv_one<0>(o[0], vb, pa0, pa1, pa2, pa3); pv_one<1>(o[1], vb, pa0, pa1, pa2, pa3); pv_one<2>(o[2], vb, pa0, pa1, pa2, pa3); pv_one<3>(o[3], vb, pa0, pa1, pa2, pa3);
; template <bool FIXED>
; __device__ __forceinline__ float softmax_tile(f32x16& p0, f32x16& p1, float& m_reg, float& l_reg, bf16x8& pa0, bf16x8& pa1, bf16x8& pa2, bf16x8& pa3) {
;     float alpha = 1.f;
;     if (!FIXED) {
;         float pmax = p0[0];
; #pragma unroll
;         for (int r = 1; r < 16; ++r) pmax = fmaxf(pmax, p0[r]);
; #pragma unroll
;         for (int r = 0; r < 16; ++r) pmax = fmaxf(pmax, p1[r]);
;         pmax = half_max(pmax);
;         if (!__all(pmax - m_reg <= ATT_THR)) { const float mn = fmaxf(m_reg, pmax); alpha = __builtin_amdgcn_exp2f(m_reg - mn); m_reg = mn; }
;         const float mn = m_reg;
; #pragma unroll
;         for (int r = 0; r < 16; ++r) { p0[r] = __builtin_amdgcn_exp2f(p0[r] - mn); p1[r] = __builtin_amdgcn_exp2f(p1[r] - mn); }
;     } else {
; #pragma unroll
;         for (int r = 0; r < 16; ++r) { p0[r] = __builtin_amdgcn_exp2f(p0[r]); p1[r] = __builtin_amdgcn_exp2f(p1[r]); }
;     }
;     float ps = 0.f;
; #pragma unroll
;     for (int r = 0; r < 16; ++r) ps += p0[r];
; #pragma unroll
;     for (int r = 0; r < 16; ++r) ps += p1[r];
;     ps = half_sum(ps);
;     l_reg = l_reg * alpha + ps;
;     ...
;     PK4(p0, 0, pa0); PK4(p0, 8, pa1); PK4(p1, 0, pa2); PK4(p1, 8, pa3);
;     ...
;     return alpha;
.Lattn_exp1:
	v_add_u32_e32 v5, s29, v200
	ds_read_b64_tr_b16 v[228:229], v5 offset:0
	ds_read_b64_tr_b16 v[230:231], v5 offset:2048
	ds_read_b64_tr_b16 v[240:241], v5 offset:512
	ds_read_b64_tr_b16 v[242:243], v5 offset:2560
	ds_read_b64_tr_b16 v[244:245], v5 offset:1024
	ds_read_b64_tr_b16 v[246:247], v5 offset:3072
	s_nop 2
	v_exp_f32_e32 v70, v70
	v_exp_f32_e32 v71, v71
	v_add_f32_e32 v2, 0, v70
	v_exp_f32_e32 v72, v72
	v_add_f32_e32 v2, v71, v2
	v_exp_f32_e32 v73, v73
	v_add_f32_e32 v2, v72, v2
	v_exp_f32_e32 v74, v74
	v_add_f32_e32 v2, v73, v2
	v_exp_f32_e32 v75, v75
	v_add_f32_e32 v2, v74, v2
	v_exp_f32_e32 v76, v76
	v_add_f32_e32 v2, v75, v2
	v_exp_f32_e32 v77, v77
	v_add_f32_e32 v2, v76, v2
	v_cvt_pk_bf16_f32 v70, v70, v71
	v_add_f32_e32 v2, v77, v2
	v_cvt_pk_bf16_f32 v71, v72, v73
	v_cvt_pk_bf16_f32 v72, v74, v75
	v_cvt_pk_bf16_f32 v73, v76, v77
	ds_read_b64_tr_b16 v[74:75], v5 offset:1536
	ds_read_b64_tr_b16 v[76:77], v5 offset:3584
	v_permlane32_swap_b32_e32 v70, v72
	v_permlane32_swap_b32_e32 v71, v73
	s_waitcnt lgkmcnt(6)
	s_nop 0
	v_mfma_f32_32x32x16_bf16 v[54:69], v[70:73], v[228:231], v[54:69]
	ds_read_b64_tr_b16 v[228:229], v5 offset:4096
	ds_read_b64_tr_b16 v[230:231], v5 offset:6144
	v_exp_f32_e32 v78, v78
	v_exp_f32_e32 v79, v79
	v_add_f32_e32 v2, v78, v2
	v_exp_f32_e32 v80, v80
	v_add_f32_e32 v2, v79, v2
	v_exp_f32_e32 v81, v81
	s_waitcnt lgkmcnt(6)
	v_mfma_f32_32x32x16_bf16 v[38:53], v[70:73], v[240:243], v[38:53]
	ds_read_b64_tr_b16 v[240:241], v5 offset:4608
	ds_read_b64_tr_b16 v[242:243], v5 offset:6656
	v_add_f32_e32 v2, v80, v2
	v_exp_f32_e32 v82, v82
	v_add_f32_e32 v2, v81, v2
	v_exp_f32_e32 v83, v83
	v_add_f32_e32 v2, v82, v2
	v_exp_f32_e32 v84, v84
	s_waitcnt lgkmcnt(6)
	v_mfma_f32_32x32x16_bf16 v[22:37], v[70:73], v[244:247], v[22:37]
	ds_read_b64_tr_b16 v[244:245], v5 offset:5120
	ds_read_b64_tr_b16 v[246:247], v5 offset:7168
	v_add_f32_e32 v2, v83, v2
	v_exp_f32_e32 v85, v85
	v_add_f32_e32 v2, v84, v2
	v_cvt_pk_bf16_f32 v78, v78, v79
	v_add_f32_e32 v2, v85, v2
	s_waitcnt lgkmcnt(6)
	v_mfma_f32_32x32x16_bf16 v[6:21], v[70:73], v[74:77], v[6:21]
	v_cvt_pk_bf16_f32 v79, v80, v81
	v_cvt_pk_bf16_f32 v80, v82, v83
	v_cvt_pk_bf16_f32 v81, v84, v85
	ds_read_b64_tr_b16 v[74:75], v5 offset:5632
	ds_read_b64_tr_b16 v[76:77], v5 offset:7680
	v_permlane32_swap_b32_e32 v78, v80
	v_permlane32_swap_b32_e32 v79, v81
	s_waitcnt lgkmcnt(6)
	s_nop 0
	v_mfma_f32_32x32x16_bf16 v[54:69], v[78:81], v[228:231], v[54:69]
	ds_read_b64_tr_b16 v[228:229], v5 offset:8192
	ds_read_b64_tr_b16 v[230:231], v5 offset:10240
	v_exp_f32_e32 v86, v86
	v_exp_f32_e32 v87, v87
	v_add_f32_e32 v2, v86, v2
	v_exp_f32_e32 v88, v88
	v_add_f32_e32 v2, v87, v2
	v_exp_f32_e32 v89, v89
	s_waitcnt lgkmcnt(6)
	v_mfma_f32_32x32x16_bf16 v[38:53], v[78:81], v[240:243], v[38:53]
	s_min_i32 s3, s100, s101
	s_mul_i32 s98, s3, 0x218000
	s_lshl_b32 s73, s31, 11
	s_add_i32 s73, s73, s53
	s_mov_b32 m0, s73
	v_lshl_add_u64 v[106:107], v[102:103], 0, s[98:99]
	v_lshl_add_u64 v[108:109], v[104:105], 0, s[98:99]
	global_load_lds_dwordx4 v[106:107], off
	ds_read_b64_tr_b16 v[240:241], v5 offset:8704
	ds_read_b64_tr_b16 v[242:243], v5 offset:10752
	v_add_f32_e32 v2, v88, v2
	v_exp_f32_e32 v90, v90
	v_add_f32_e32 v2, v89, v2
	v_exp_f32_e32 v91, v91
	v_add_f32_e32 v2, v90, v2
	v_exp_f32_e32 v92, v92
	s_waitcnt lgkmcnt(6)
	v_mfma_f32_32x32x16_bf16 v[22:37], v[78:81], v[244:247], v[22:37]
	ds_read_b64_tr_b16 v[244:245], v5 offset:9216
	ds_read_b64_tr_b16 v[246:247], v5 offset:11264
	v_add_f32_e32 v2, v91, v2
	v_exp_f32_e32 v93, v93
	v_add_f32_e32 v2, v92, v2
	v_cvt_pk_bf16_f32 v86, v86, v87
	v_add_f32_e32 v2, v93, v2
	s_waitcnt lgkmcnt(6)
	v_mfma_f32_32x32x16_bf16 v[6:21], v[78:81], v[74:77], v[6:21]
	v_cvt_pk_bf16_f32 v87, v88, v89
	v_cvt_pk_bf16_f32 v88, v90, v91
	v_cvt_pk_bf16_f32 v89, v92, v93
	ds_read_b64_tr_b16 v[74:75], v5 offset:9728
	ds_read_b64_tr_b16 v[76:77], v5 offset:11776
	v_permlane32_swap_b32_e32 v86, v88
	v_permlane32_swap_b32_e32 v87, v89
	s_waitcnt lgkmcnt(6)
	s_nop 0
	v_mfma_f32_32x32x16_bf16 v[54:69], v[86:89], v[228:231], v[54:69]
	ds_read_b64_tr_b16 v[228:229], v5 offset:12288
	ds_read_b64_tr_b16 v[230:231], v5 offset:14336
	v_exp_f32_e32 v94, v94
	v_exp_f32_e32 v95, v95
	v_add_f32_e32 v2, v94, v2
	v_exp_f32_e32 v96, v96
	v_add_f32_e32 v2, v95, v2
	v_exp_f32_e32 v97, v97
	s_waitcnt lgkmcnt(6)
	v_mfma_f32_32x32x16_bf16 v[38:53], v[86:89], v[240:243], v[38:53]
	s_add_i32 m0, s73, 0x380
	s_lshl_b32 s3, s31, 10
	s_add_i32 s3, s3, s53
	global_load_lds_dwordx4 v[106:107], off offset:128
	ds_read_b64_tr_b16 v[240:241], v5 offset:12800
	ds_read_b64_tr_b16 v[242:243], v5 offset:14848
	v_add_f32_e32 v2, v96, v2
	v_exp_f32_e32 v98, v98
	v_add_f32_e32 v2, v97, v2
	v_exp_f32_e32 v99, v99
	v_add_f32_e32 v2, v98, v2
	v_exp_f32_e32 v100, v100
	s_waitcnt lgkmcnt(6)
	v_mfma_f32_32x32x16_bf16 v[22:37], v[86:89], v[244:247], v[22:37]
	ds_read_b64_tr_b16 v[244:245], v5 offset:13312
	ds_read_b64_tr_b16 v[246:247], v5 offset:15360
	v_add_f32_e32 v2, v99, v2
	v_exp_f32_e32 v101, v101
	v_add_f32_e32 v2, v100, v2
	v_cvt_pk_bf16_f32 v94, v94, v95
	v_add_f32_e32 v2, v101, v2
	s_waitcnt lgkmcnt(6)
	v_mfma_f32_32x32x16_bf16 v[6:21], v[86:89], v[74:77], v[6:21]
	v_cvt_pk_bf16_f32 v95, v96, v97
	v_cvt_pk_bf16_f32 v96, v98, v99
	v_cvt_pk_bf16_f32 v97, v100, v101
	ds_read_b64_tr_b16 v[74:75], v5 offset:13824
	ds_read_b64_tr_b16 v[76:77], v5 offset:15872
	v_permlane32_swap_b32_e32 v94, v96
	v_permlane32_swap_b32_e32 v95, v97
	v_mov_b32_e32 v3, v2
	s_waitcnt lgkmcnt(6)
	s_nop 0
	v_mfma_f32_32x32x16_bf16 v[54:69], v[94:97], v[228:231], v[54:69]
	v_add_u32_e32 v238, 2, v236
	s_waitcnt lgkmcnt(4)
	v_mfma_f32_32x32x16_bf16 v[38:53], v[94:97], v[240:243], v[38:53]
	s_add_i32 m0, s3, 0x10000
	s_add_i32 s100, s100, 1
	s_add_i32 s53, s53, 0x4000
	global_load_lds_dwordx4 v[108:109], off
	s_and_b32 s53, s53, 0xc000
	v_permlane32_swap_b32_e32 v2, v3
	s_waitcnt lgkmcnt(2)
	v_mfma_f32_32x32x16_bf16 v[22:37], v[94:97], v[244:247], v[22:37]
	s_waitcnt lgkmcnt(0)
	v_mfma_f32_32x32x16_bf16 v[6:21], v[94:97], v[74:77], v[6:21]
	s_and_saveexec_b64 s[10:11], vcc
	s_xor_b64 s[10:11], exec, s[10:11]
	v_add_u32_e32 v236, 2, v236
	s_or_saveexec_b64 s[14:15], s[10:11]
	v_add_f32_e32 v2, v2, v3
	v_add_f32_e32 v219, v219, v2
	s_xor_b64 exec, exec, s[14:15]
	s_cbranch_execz .LBB0_936
	s_and_b32 s29, s60, 0xc000
	s_add_i32 s12, s29, 0x8000
	v_add_u32_e32 v2, s12, v207
	s_waitcnt vmcnt(6)
	s_barrier
	v_add_u32_e32 v3, v2, v167
	ds_read_b128 v[70:73], v3 offset:32768
	v_add_u32_e32 v3, v2, v212
	ds_read_b128 v[90:93], v3 offset:32768
	v_add_u32_e32 v3, v2, v214
	ds_read_b128 v[94:97], v3 offset:32768
	v_add_u32_e32 v3, v2, v216
	ds_read_b128 v[98:101], v3 offset:32768
	v_add_u32_e32 v3, s12, v211
	ds_read_b128 v[86:89], v3 offset:32768
	v_add_u32_e32 v3, s12, v213
	ds_read_b128 v[228:231], v3 offset:32768
	v_add_u32_e32 v3, s12, v215
	ds_read_b128 v[240:243], v3 offset:32768
	v_add_u32_e32 v3, s12, v217
	ds_read_b128 v[244:247], v3 offset:32768
	v_add_u32_e32 v3, 0x7f, v235
	v_cmp_le_i32_e64 s[10:11], s27, v3
	v_cmp_gt_i32_e32 vcc, s27, v3
	v_cmp_ge_i32_e64 s[12:13], s18, v237
	v_cvt_f32_i32_e32 v2, v237
	s_and_b64 s[10:11], s[10:11], s[12:13]
	s_cmp_eq_u64 s[10:11], 0
	s_cbranch_scc0 .Lattn_nl2
	s_waitcnt lgkmcnt(7)
	v_mfma_f32_32x32x16_bf16 v[70:85], v[70:73], v[114:117], 0
	v_cndmask_b32_e64 v3, -v189, v189, vcc
	v_sub_f32_e32 v2, v191, v2
	v_mul_f32_e64 v2, v2, -v3
	v_cvt_pk_bf16_f32 v5, v2, v3
	v_lshlrev_b32_e32 v196, 16, v5
	v_and_b32_e32 v197, 0xffff0000, v5
	s_waitcnt lgkmcnt(6)
	v_mfma_f32_32x32x16_bf16 v[70:85], v[90:93], v[118:121], v[70:85]
	v_pk_add_f32 v[2:3], v[2:3], v[196:197] neg_lo:[0,1] neg_hi:[0,1]
	s_nop 0
	v_cvt_pk_bf16_f32 v2, v2, v3
	v_and_b32_e32 v3, 0xffff, v5
	v_lshl_or_b32 v183, v2, 16, v3
	s_waitcnt lgkmcnt(5)
	v_mfma_f32_32x32x16_bf16 v[70:85], v[94:97], v[122:125], v[70:85]
	v_lshrrev_b32_e32 v3, 16, v5
	v_and_or_b32 v2, v2, s28, v3
	v_cndmask_b32_e64 v3, 0, v2, s[4:5]
	v_cndmask_b32_e64 v2, 0, v183, s[4:5]
	v_mov_b32_e32 v5, v4
	s_waitcnt lgkmcnt(4)
	v_mfma_f32_32x32x16_bf16 v[70:85], v[98:101], v[126:129], v[70:85]
	s_waitcnt lgkmcnt(3)
	v_mfma_f32_32x32x16_bf16 v[86:101], v[86:89], v[114:117], 0
	s_waitcnt lgkmcnt(2)
	v_mfma_f32_32x32x16_bf16 v[86:101], v[228:231], v[118:121], v[86:101]
	s_waitcnt lgkmcnt(1)
	v_mfma_f32_32x32x16_bf16 v[86:101], v[240:243], v[122:125], v[86:101]
	s_waitcnt lgkmcnt(0)
	v_mfma_f32_32x32x16_bf16 v[86:101], v[244:247], v[126:129], v[86:101]
	v_mfma_f32_32x32x16_bf16 v[70:85], v[110:113], v[2:5], v[70:85]
	v_mfma_f32_32x32x16_bf16 v[86:101], v[176:179], v[2:5], v[86:101]
	s_branch .Lattn_exp2

; __device__ __forceinline__ int crow(int r, int hi) { return (r & 3) + 8 * (r >> 2) + 4 * hi; }
; template <int MODE, bool FIXED>
; __device__ __forceinline__ void attn_unit(LAS unsigned char* lds, unsigned char* ws, const AttnParams& P, int l, int Tp, int sq, int h, int qb, int part, int np, int pslot, int tid, int wave, int lane) {
;     ...
;         if (MODE == 1 && mp == 0) {
;             if (hi == 0) li_l[r32] = l_reg;
;             asm volatile("s_waitcnt lgkmcnt(0)" ::: "memory");
; #pragma unroll
;             for (int r4 = 0; r4 < 4; ++r4) { float rl[4];
; #pragma unroll
;                 for (int e = 0; e < 4; ++e) rl[e] = __builtin_amdgcn_rcpf(li_l[crow(4 * r4 + e, hi)]);
; #pragma unroll
;                 for (int d = 0; d < 4; ++d) { f32x4 t; t.x = o[d][4 * r4] * rl[0]; t.y = o[d][4 * r4 + 1] * rl[1]; t.z = o[d][4 * r4 + 2] * rl[2]; t.w = o[d][4 * r4 + 3] * rl[3];
;                     *(f32x4*)(park + (d * 4 + r4) * 256) = t; } }
;             asm volatile("s_waitcnt lgkmcnt(0)" ::: "memory");
;         }
;     }
.LBB0_958:
	s_and_saveexec_b64 s[14:15], s[4:5]
	ds_write_b32 v195, v219
	s_or_b64 exec, exec, s[14:15]
	s_waitcnt lgkmcnt(0)
	ds_read_b128 v[70:73], v169
	ds_read_b128 v[74:77], v169 offset:32
	s_mov_b64 s[14:15], -1
	s_waitcnt lgkmcnt(0)
	v_rcp_f32_e32 v2, v70
	v_rcp_f32_e32 v3, v71
	v_rcp_f32_e32 v78, v72
	v_rcp_f32_e32 v79, v73
	v_pk_mul_f32 v[70:71], v[54:55], v[2:3]
	v_pk_mul_f32 v[72:73], v[56:57], v[78:79]
	global_store_dwordx4 v[142:143], v[70:73], off
	s_nop 1
	v_pk_mul_f32 v[70:71], v[38:39], v[2:3]
	v_pk_mul_f32 v[72:73], v[40:41], v[78:79]
	global_store_dwordx4 v[164:165], v[70:73], off
	s_nop 1
	v_pk_mul_f32 v[70:71], v[22:23], v[2:3]
	v_pk_mul_f32 v[72:73], v[24:25], v[78:79]
	global_store_dwordx4 v[162:163], v[70:73], off
	s_nop 1
	v_pk_mul_f32 v[70:71], v[6:7], v[2:3]
	v_rcp_f32_e32 v2, v74
	v_rcp_f32_e32 v3, v75
	v_rcp_f32_e32 v74, v76
	v_rcp_f32_e32 v75, v77
	v_pk_mul_f32 v[72:73], v[8:9], v[78:79]
	global_store_dwordx4 v[160:161], v[70:73], off
	s_nop 1
	v_pk_mul_f32 v[70:71], v[58:59], v[2:3]
	v_pk_mul_f32 v[72:73], v[60:61], v[74:75]
	global_store_dwordx4 v[142:143], v[70:73], off offset:1024
	s_nop 1
	v_pk_mul_f32 v[70:71], v[42:43], v[2:3]
	v_pk_mul_f32 v[72:73], v[44:45], v[74:75]
	global_store_dwordx4 v[158:159], v[70:73], off
	s_nop 1
	v_pk_mul_f32 v[70:71], v[26:27], v[2:3]
	v_pk_mul_f32 v[72:73], v[28:29], v[74:75]
	global_store_dwordx4 v[156:157], v[70:73], off
	s_nop 1
	v_pk_mul_f32 v[70:71], v[10:11], v[2:3]
	v_pk_mul_f32 v[72:73], v[12:13], v[74:75]
	global_store_dwordx4 v[154:155], v[70:73], off
	ds_read_b128 v[70:73], v169 offset:64
	s_waitcnt lgkmcnt(0)
	v_rcp_f32_e32 v2, v70
	v_rcp_f32_e32 v3, v71
	v_rcp_f32_e32 v74, v72
	v_rcp_f32_e32 v75, v73
	v_pk_mul_f32 v[70:71], v[62:63], v[2:3]
	v_pk_mul_f32 v[72:73], v[64:65], v[74:75]
	global_store_dwordx4 v[142:143], v[70:73], off offset:2048
	s_nop 1
	v_pk_mul_f32 v[70:71], v[46:47], v[2:3]
	v_pk_mul_f32 v[72:73], v[48:49], v[74:75]
	global_store_dwordx4 v[152:153], v[70:73], off
	s_nop 1
	v_pk_mul_f32 v[70:71], v[30:31], v[2:3]
	v_pk_mul_f32 v[72:73], v[32:33], v[74:75]
	global_store_dwordx4 v[148:149], v[70:73], off
	s_nop 1
	v_pk_mul_f32 v[70:71], v[14:15], v[2:3]
	v_pk_mul_f32 v[72:73], v[16:17], v[74:75]
	global_store_dwordx4 v[146:147], v[70:73], off
	ds_read_b128 v[70:73], v169 offset:96
	s_waitcnt lgkmcnt(0)
	v_rcp_f32_e32 v2, v70
	v_rcp_f32_e32 v3, v71
	v_rcp_f32_e32 v74, v72
	v_rcp_f32_e32 v75, v73
	v_pk_mul_f32 v[70:71], v[66:67], v[2:3]
	v_pk_mul_f32 v[72:73], v[68:69], v[74:75]
	global_store_dwordx4 v[142:143], v[70:73], off offset:3072
	s_nop 1
	v_pk_mul_f32 v[70:71], v[50:51], v[2:3]
	v_pk_mul_f32 v[72:73], v[52:53], v[74:75]
	global_store_dwordx4 v[144:145], v[70:73], off
	s_nop 1
	v_pk_mul_f32 v[70:71], v[34:35], v[2:3]
	v_pk_mul_f32 v[72:73], v[36:37], v[74:75]
	global_store_dwordx4 v[132:133], v[70:73], off
	s_nop 1
	v_pk_mul_f32 v[70:71], v[18:19], v[2:3]
	v_pk_mul_f32 v[72:73], v[20:21], v[74:75]
	global_store_dwordx4 v[130:131], v[70:73], off
	s_and_b64 vcc, exec, s[12:13]
	s_cbranch_vccz .LBB0_956

; #define LAS __attribute__((address_space(3)))
; __device__ __forceinline__ float wave_sum(float v) { v += xshfl<1>(v); v += xshfl<2>(v); v += xshfl<4>(v); v += xshfl<8>(v); v += xshfl<16>(v); return half_sum(v); }
; __device__ __forceinline__ int crow(int r, int hi) { return (r & 3) + 8 * (r >> 2) + 4 * hi; }
; template <int MODE, bool FIXED>
; __device__ __forceinline__ void attn_unit(LAS unsigned char* lds, unsigned char* ws, const AttnParams& P, int l, int Tp, int sq, int h, int qb, int part, int np, int pslot, int tid, int wave, int lane) {
;     ...
;     float lam = 0.f; int ll_ = l; asm volatile("" : "+s"(ll_)); const float lin = 0.8f - 0.6f * expf(-0.3f * (float)ll_);
;     if (MODE == 1) { const float a = P.lam[lane] * P.lam[64 + lane], bq = P.lam[128 + lane] * P.lam[192 + lane]; lam = expf(wave_sum(a)) - expf(wave_sum(bq)) + lin; }
;     LAS float* ost = (LAS float*)(lds + AT_OST + wave * AT_OST_W);
;     {
;         if (hi == 0) li_l[r32] = l_reg;
;         asm volatile("s_waitcnt lgkmcnt(0)" ::: "memory");
; #pragma unroll
;         for (int r4 = 0; r4 < 4; ++r4) { float rl[4];
; #pragma unroll
;             for (int e = 0; e < 4; ++e) rl[e] = __builtin_amdgcn_rcpf(li_l[crow(4 * r4 + e, hi)]);
; #pragma unroll
;             for (int d = 0; d < 4; ++d) { f32x4 pk = {0.f, 0.f, 0.f, 0.f}; if (MODE == 1) pk = *(const f32x4*)(park + (d * 4 + r4) * 256);
; #pragma unroll
;                 for (int e = 0; e < 4; ++e) { float v = o[d][4 * r4 + e] * rl[e]; if (MODE == 1) v = pk[e] - lam * v;
;                     ost[crow(4 * r4 + e, hi) * 132 + d * 32 + r32] = v; } } }
.LBB0_965:
	s_and_b64 vcc, exec, s[80:81]
	v_readlane_b32 s85, v255, 0
	v_readlane_b32 s29, v255, 18
	v_readlane_b32 s84, v255, 34
	s_cbranch_vccz .LBB0_969
	v_readlane_b32 s6, v254, 26
	v_readlane_b32 s7, v254, 27
	s_mov_b32 s8, s6
	v_readlane_b32 s6, v254, 40
	v_lshlrev_b32_e32 v2, 2, v193
	v_readlane_b32 s7, v254, 41
	s_nop 4
	global_load_dword v3, v2, s[6:7]
	global_load_dword v5, v2, s[6:7] offset:256
	global_load_dword v70, v2, s[6:7] offset:512
	s_nop 0
	global_load_dword v2, v2, s[6:7] offset:768
	s_waitcnt vmcnt(0)
	v_mul_f32_e32 v71, v3, v5
	ds_swizzle_b32 v71, v71 offset:swizzle(SWAP,1)
	v_mul_f32_e32 v72, v70, v2
	ds_swizzle_b32 v72, v72 offset:swizzle(SWAP,1)
	s_waitcnt lgkmcnt(0)
	v_fmac_f32_e32 v71, v3, v5
	v_fmac_f32_e32 v72, v70, v2
	ds_swizzle_b32 v2, v71 offset:swizzle(SWAP,2)
	ds_swizzle_b32 v3, v72 offset:swizzle(SWAP,2)
	s_waitcnt lgkmcnt(1)
	v_add_f32_e32 v2, v71, v2
	s_waitcnt lgkmcnt(0)
	v_add_f32_e32 v3, v72, v3
	ds_swizzle_b32 v5, v2 offset:swizzle(SWAP,4)
	ds_swizzle_b32 v70, v3 offset:swizzle(SWAP,4)
	s_waitcnt lgkmcnt(1)
	v_add_f32_e32 v2, v2, v5
	s_waitcnt lgkmcnt(0)
	v_add_f32_e32 v3, v3, v70
	ds_swizzle_b32 v5, v2 offset:swizzle(SWAP,8)
	ds_swizzle_b32 v70, v3 offset:swizzle(SWAP,8)
	s_waitcnt lgkmcnt(1)
	v_add_f32_e32 v2, v2, v5
	s_waitcnt lgkmcnt(0)
	v_add_f32_e32 v3, v3, v70
	ds_swizzle_b32 v5, v2 offset:swizzle(SWAP,16)
	ds_swizzle_b32 v71, v3 offset:swizzle(SWAP,16)
	s_waitcnt lgkmcnt(1)
	v_add_f32_e32 v70, v2, v5
	s_waitcnt lgkmcnt(0)
	v_add_f32_e32 v3, v3, v71
	v_mov_b32_e32 v71, v70
	v_mov_b32_e32 v5, v3
	s_nop 0
	v_permlane32_swap_b32_e32 v70, v71
	v_permlane32_swap_b32_e32 v3, v5
	s_and_saveexec_b64 s[6:7], s[4:5]
	ds_write_b32 v195, v219
	s_or_b64 exec, exec, s[6:7]
	v_cvt_f32_i32_e32 v2, s8
	s_mov_b32 s6, 0x3fb8aa3b
	s_mov_b32 s3, 0xc2ce8ed0
	s_mov_b32 s4, 0x42b17218
	v_mul_f32_e32 v2, 0xbe99999a, v2
	v_mul_f32_e32 v72, 0x3fb8aa3b, v2
	v_fma_f32 v73, v2, s6, -v72
	v_rndne_f32_e32 v74, v72
	v_fmac_f32_e32 v73, 0x32a5705f, v2
	v_sub_f32_e32 v72, v72, v74
	v_add_f32_e32 v72, v72, v73
	v_exp_f32_e32 v72, v72
	v_cvt_i32_f32_e32 v73, v74
	v_cmp_ngt_f32_e32 vcc, s3, v2
	v_add_f32_e32 v70, v70, v71
	v_mul_f32_e32 v71, 0x3fb8aa3b, v70
	v_ldexp_f32 v72, v72, v73
	v_cndmask_b32_e32 v72, 0, v72, vcc
	v_cmp_nlt_f32_e32 vcc, s4, v2
	v_rndne_f32_e32 v73, v71
	v_add_f32_e32 v3, v3, v5
	v_cndmask_b32_e32 v2, v225, v72, vcc
	v_mov_b32_e32 v72, 0x3f4ccccd
	v_fmamk_f32 v2, v2, 0xbf19999a, v72
	v_fma_f32 v72, v70, s6, -v71
	v_fmac_f32_e32 v72, 0x32a5705f, v70
	v_sub_f32_e32 v71, v71, v73
	v_add_f32_e32 v71, v71, v72
	v_exp_f32_e32 v71, v71
	v_cvt_i32_f32_e32 v72, v73
	v_cmp_ngt_f32_e32 vcc, s3, v70
	v_mul_f32_e32 v5, 0x3fb8aa3b, v3
	s_waitcnt lgkmcnt(0)
	v_ldexp_f32 v71, v71, v72
	v_cndmask_b32_e32 v71, 0, v71, vcc
	v_cmp_nlt_f32_e32 vcc, s4, v70
	v_rndne_f32_e32 v72, v5
	s_nop 0
	v_cndmask_b32_e32 v70, v225, v71, vcc
	v_fma_f32 v71, v3, s6, -v5
	v_fmac_f32_e32 v71, 0x32a5705f, v3
	v_sub_f32_e32 v5, v5, v72
	v_add_f32_e32 v5, v5, v71
	v_exp_f32_e32 v5, v5
	v_cvt_i32_f32_e32 v71, v72
	v_cmp_ngt_f32_e32 vcc, s3, v3
	s_movk_i32 s3, 0x4000
	v_ldexp_f32 v5, v5, v71
	v_cndmask_b32_e32 v5, 0, v5, vcc
	v_cmp_nlt_f32_e32 vcc, s4, v3
	s_mul_i32 s4, s31, 0x4200
	s_add_i32 s4, s4, 0
	v_cndmask_b32_e32 v3, v225, v5, vcc
	v_sub_f32_e32 v3, v70, v3
	ds_read_b128 v[70:73], v169
	v_add_f32_e32 v3, v2, v3
	v_sub_f32_e32 v2, 1.0, v2
	s_waitcnt lgkmcnt(0)
	v_rcp_f32_e32 v74, v70
	v_rcp_f32_e32 v75, v71
	v_rcp_f32_e32 v76, v72
	v_rcp_f32_e32 v77, v73
	global_load_dwordx4 v[70:73], v[142:143], off
	v_mul_f32_e32 v5, v54, v74
	v_mul_f32_e32 v54, v55, v75
	v_mul_f32_e32 v38, v38, v74
	v_mul_f32_e32 v22, v22, v74
	v_mul_f32_e32 v6, v6, v74
	s_waitcnt vmcnt(0)
	v_fma_f32 v71, -v3, v54, v71
	v_mul_f32_e32 v54, v56, v76
	v_fma_f32 v72, -v3, v54, v72
	v_mul_f32_e32 v54, v57, v77
	v_fma_f32 v73, -v3, v54, v73
	global_load_dwordx4 v[54:57], v[164:165], off
	v_fma_f32 v70, -v3, v5, v70
	v_mul_u32_u24_e32 v5, 0x840, v194
	v_add3_u32 v5, s4, v166, v5
	s_waitcnt vmcnt(0)
	v_fma_f32 v38, -v3, v38, v54
	ds_write2_b32 v5, v70, v38 offset1:32
	v_mul_f32_e32 v38, v39, v75
	v_fma_f32 v38, -v3, v38, v55
	ds_write2_b32 v5, v71, v38 offset0:132 offset1:164
	v_mul_f32_e32 v38, v40, v76
	v_fma_f32 v38, -v3, v38, v56
	v_add_u32_e32 v54, 0x400, v5
	ds_write2_b32 v54, v72, v38 offset0:8 offset1:40
	v_mul_f32_e32 v38, v41, v77
	v_fma_f32 v38, -v3, v38, v57
	ds_write2_b32 v54, v73, v38 offset0:140 offset1:172
	global_load_dwordx4 v[38:41], v[162:163], off
	s_waitcnt vmcnt(0)
	v_fma_f32 v38, -v3, v22, v38
	v_mul_f32_e32 v22, v23, v75
	v_fma_f32 v39, -v3, v22, v39
	v_mul_f32_e32 v22, v24, v76
	v_fma_f32 v40, -v3, v22, v40
	v_mul_f32_e32 v22, v25, v77
	v_fma_f32 v41, -v3, v22, v41
	global_load_dwordx4 v[22:25], v[160:161], off
	s_waitcnt vmcnt(0)
	v_fma_f32 v6, -v3, v6, v22
	ds_write2_b32 v5, v38, v6 offset0:64 offset1:96
	v_mul_f32_e32 v6, v7, v75
	v_fma_f32 v6, -v3, v6, v23
	ds_write2_b32 v5, v39, v6 offset0:196 offset1:228
	v_mul_f32_e32 v6, v8, v76
	v_fma_f32 v6, -v3, v6, v24
	ds_write2_b32 v54, v40, v6 offset0:72 offset1:104
	v_mul_f32_e32 v6, v9, v77
	v_fma_f32 v6, -v3, v6, v25
	ds_write2_b32 v54, v41, v6 offset0:204 offset1:236
	ds_read_b128 v[6:9], v169 offset:32
	s_waitcnt lgkmcnt(0)
	v_rcp_f32_e32 v22, v6
	v_rcp_f32_e32 v23, v7
	v_rcp_f32_e32 v24, v8
	v_rcp_f32_e32 v25, v9
	global_load_dwordx4 v[6:9], v[142:143], off offset:1024
	v_mul_f32_e32 v38, v58, v22
	v_mul_f32_e32 v42, v42, v22
	v_mul_f32_e32 v26, v26, v22
	v_mul_f32_e32 v10, v10, v22
	s_waitcnt vmcnt(0)
; #define LAS __attribute__((address_space(3)))
; __device__ __forceinline__ int crow(int r, int hi) { return (r & 3) + 8 * (r >> 2) + 4 * hi; }
; template <int MODE, bool FIXED>
; __device__ __forceinline__ void attn_unit(LAS unsigned char* lds, unsigned char* ws, const AttnParams& P, int l, int Tp, int sq, int h, int qb, int part, int np, int pslot, int tid, int wave, int lane) {
;     ...
;         for (int r4 = 0; r4 < 4; ++r4) { float rl[4];
; #pragma unroll
;             for (int e = 0; e < 4; ++e) rl[e] = __builtin_amdgcn_rcpf(li_l[crow(4 * r4 + e, hi)]);
; #pragma unroll
;             for (int d = 0; d < 4; ++d) { f32x4 pk = {0.f, 0.f, 0.f, 0.f}; if (MODE == 1) pk = *(const f32x4*)(park + (d * 4 + r4) * 256);
; #pragma unroll
;                 for (int e = 0; e < 4; ++e) { float v = o[d][4 * r4 + e] * rl[e]; if (MODE == 1) v = pk[e] - lam * v;
;                     ost[crow(4 * r4 + e, hi) * 132 + d * 32 + r32] = v; } } }
;     }
;     asm volatile("s_waitcnt lgkmcnt(0)" ::: "memory");
;     {
;         const int row = lane >> 1, half = lane & 1;
;         const LAS f32x4* src = (const LAS f32x4*)(ost + row * 132 + half * 64);
;         float v[64];
; #pragma unroll
;         for (int k = 0; k < 16; ++k) { const f32x4 t = src[k]; v[4 * k] = t.x; v[4 * k + 1] = t.y; v[4 * k + 2] = t.z; v[4 * k + 3] = t.w; }
	v_fma_f32 v38, -v3, v38, v6
	v_mul_f32_e32 v6, v59, v23
	v_fma_f32 v39, -v3, v6, v7
	v_mul_f32_e32 v6, v60, v24
	v_fma_f32 v40, -v3, v6, v8
	v_mul_f32_e32 v6, v61, v25
	v_fma_f32 v41, -v3, v6, v9
	global_load_dwordx4 v[6:9], v[158:159], off
	s_waitcnt vmcnt(0)
	v_fma_f32 v6, -v3, v42, v6
	v_add_u32_e32 v42, 0x1000, v5
	ds_write2_b32 v42, v38, v6 offset0:32 offset1:64
	v_mul_f32_e32 v6, v43, v23
	v_fma_f32 v6, -v3, v6, v7
	ds_write2_b32 v42, v39, v6 offset0:164 offset1:196
	v_mul_f32_e32 v6, v44, v24
	v_fma_f32 v6, -v3, v6, v8
	v_add_u32_e32 v38, 0x1400, v5
	ds_write2_b32 v38, v40, v6 offset0:40 offset1:72
	v_mul_f32_e32 v6, v45, v25
	v_fma_f32 v6, -v3, v6, v9
	ds_write2_b32 v38, v41, v6 offset0:172 offset1:204
	global_load_dwordx4 v[6:9], v[156:157], off
	s_waitcnt vmcnt(0)
	v_fma_f32 v26, -v3, v26, v6
	v_mul_f32_e32 v6, v27, v23
	v_fma_f32 v27, -v3, v6, v7
	v_mul_f32_e32 v6, v28, v24
	v_fma_f32 v28, -v3, v6, v8
	v_mul_f32_e32 v6, v29, v25
	v_fma_f32 v29, -v3, v6, v9
	global_load_dwordx4 v[6:9], v[154:155], off
	s_waitcnt vmcnt(0)
	v_fma_f32 v6, -v3, v10, v6
	ds_write2_b32 v42, v26, v6 offset0:96 offset1:128
	v_mul_f32_e32 v6, v11, v23
	v_fma_f32 v6, -v3, v6, v7
	v_add_u32_e32 v7, 0x1200, v5
	ds_write2_b32 v7, v27, v6 offset0:100 offset1:132
	v_mul_f32_e32 v6, v12, v24
	v_fma_f32 v6, -v3, v6, v8
	ds_write2_b32 v38, v28, v6 offset0:104 offset1:136
	v_mul_f32_e32 v6, v13, v25
	v_fma_f32 v6, -v3, v6, v9
	v_add_u32_e32 v7, 0x1600, v5
	ds_write2_b32 v7, v29, v6 offset0:108 offset1:140
	ds_read_b128 v[10:13], v169 offset:64
	s_waitcnt lgkmcnt(0)
	v_rcp_f32_e32 v9, v10
	v_rcp_f32_e32 v8, v11
	v_rcp_f32_e32 v7, v12
	v_rcp_f32_e32 v6, v13
	global_load_dwordx4 v[10:13], v[142:143], off offset:2048
	v_mul_f32_e32 v22, v62, v9
	v_mul_f32_e32 v26, v46, v9
	s_waitcnt vmcnt(0)
	v_fma_f32 v22, -v3, v22, v10
	v_mul_f32_e32 v10, v63, v8
	v_fma_f32 v23, -v3, v10, v11
	v_mul_f32_e32 v10, v64, v7
	v_fma_f32 v24, -v3, v10, v12
	v_mul_f32_e32 v10, v65, v6
	v_fma_f32 v25, -v3, v10, v13
	global_load_dwordx4 v[10:13], v[152:153], off
	s_waitcnt vmcnt(0)
	v_fma_f32 v10, -v3, v26, v10
	v_add_u32_e32 v26, 0x2000, v5
	ds_write2_b32 v26, v22, v10 offset0:64 offset1:96
	v_mul_f32_e32 v10, v47, v8
	v_fma_f32 v10, -v3, v10, v11
	ds_write2_b32 v26, v23, v10 offset0:196 offset1:228
	v_mul_f32_e32 v10, v48, v7
	v_fma_f32 v10, -v3, v10, v12
	v_add_u32_e32 v22, 0x2400, v5
	ds_write2_b32 v22, v24, v10 offset0:72 offset1:104
	v_mul_f32_e32 v10, v49, v6
	v_fma_f32 v10, -v3, v10, v13
	ds_write2_b32 v22, v25, v10 offset0:204 offset1:236
	global_load_dwordx4 v[10:13], v[148:149], off
	v_mul_f32_e32 v23, v30, v9
	v_mul_f32_e32 v9, v14, v9
	s_waitcnt vmcnt(0)
	v_fma_f32 v23, -v3, v23, v10
	v_mul_f32_e32 v10, v31, v8
	v_fma_f32 v24, -v3, v10, v11
	v_mul_f32_e32 v10, v32, v7
	v_fma_f32 v25, -v3, v10, v12
	v_mul_f32_e32 v10, v33, v6
	v_fma_f32 v27, -v3, v10, v13
	global_load_dwordx4 v[10:13], v[146:147], off
	v_mul_f32_e32 v7, v16, v7
	v_mul_f32_e32 v8, v15, v8
	v_mul_f32_e32 v6, v17, v6
	s_waitcnt vmcnt(0)
	v_fma_f32 v7, -v3, v7, v12
	v_fma_f32 v9, -v3, v9, v10
	v_fma_f32 v8, -v3, v8, v11
	ds_write2_b32 v22, v25, v7 offset0:136 offset1:168
	v_fma_f32 v6, -v3, v6, v13
	v_add_u32_e32 v7, 0x2800, v5
	ds_write2_b32 v26, v23, v9 offset0:128 offset1:160
	ds_write2_b32 v22, v24, v8 offset0:4 offset1:36
	ds_write2_b32 v7, v27, v6 offset0:12 offset1:44
	ds_read_b128 v[6:9], v169 offset:96
	s_waitcnt lgkmcnt(0)
	v_rcp_f32_e32 v13, v6
	v_rcp_f32_e32 v12, v7
	v_rcp_f32_e32 v11, v8
	v_rcp_f32_e32 v10, v9
	global_load_dwordx4 v[6:9], v[142:143], off offset:3072
	v_mul_f32_e32 v14, v66, v13
	v_mul_f32_e32 v22, v50, v13
	s_waitcnt vmcnt(0)
	v_fma_f32 v14, -v3, v14, v6
	v_mul_f32_e32 v6, v67, v12
	v_fma_f32 v15, -v3, v6, v7
	v_mul_f32_e32 v6, v68, v11
	v_fma_f32 v16, -v3, v6, v8
	v_mul_f32_e32 v6, v69, v10
	v_fma_f32 v17, -v3, v6, v9
	global_load_dwordx4 v[6:9], v[144:145], off
	s_waitcnt vmcnt(0)
	v_fma_f32 v6, -v3, v22, v6
	v_add_u32_e32 v22, 0x3000, v5
	ds_write2_b32 v22, v14, v6 offset0:96 offset1:128
	v_mul_f32_e32 v6, v51, v12
	v_fma_f32 v6, -v3, v6, v7
	v_add_u32_e32 v7, 0x3200, v5
	ds_write2_b32 v7, v15, v6 offset0:100 offset1:132
	v_mul_f32_e32 v6, v52, v11
	v_fma_f32 v6, -v3, v6, v8
	v_add_u32_e32 v14, 0x3400, v5
	ds_write2_b32 v14, v16, v6 offset0:104 offset1:136
	v_mul_f32_e32 v6, v53, v10
	v_fma_f32 v6, -v3, v6, v9
	v_add_u32_e32 v7, 0x3600, v5
	ds_write2_b32 v7, v17, v6 offset0:108 offset1:140
	global_load_dwordx4 v[6:9], v[132:133], off
	v_mul_f32_e32 v15, v34, v13
	v_mul_f32_e32 v13, v18, v13
	v_add_u32_e32 v5, 0x3800, v5
	s_waitcnt vmcnt(0)
	v_fma_f32 v15, -v3, v15, v6
	v_mul_f32_e32 v6, v35, v12
	v_fma_f32 v16, -v3, v6, v7
	v_mul_f32_e32 v6, v36, v11
	v_fma_f32 v17, -v3, v6, v8
	v_mul_f32_e32 v6, v37, v10
	v_fma_f32 v23, -v3, v6, v9
	global_load_dwordx4 v[6:9], v[130:131], off
	s_waitcnt vmcnt(0)
	v_fma_f32 v6, -v3, v13, v6
	ds_write2_b32 v22, v15, v6 offset0:160 offset1:192
	v_mul_f32_e32 v6, v19, v12
	v_fma_f32 v6, -v3, v6, v7
	ds_write2_b32 v14, v16, v6 offset0:36 offset1:68
	v_mul_f32_e32 v6, v20, v11
	v_fma_f32 v6, -v3, v6, v8
	ds_write2_b32 v14, v17, v6 offset0:168 offset1:200
	v_mul_f32_e32 v6, v21, v10
	v_fma_f32 v3, -v3, v6, v9
	ds_write2_b32 v5, v23, v3 offset0:44 offset1:76
	v_lshlrev_b32_e32 v3, 6, v193
	v_lshrrev_b32_e32 v5, 1, v193
	v_and_b32_e32 v76, 64, v3
	v_mul_u32_u24_e32 v6, 0x210, v5
	v_lshlrev_b32_e32 v3, 2, v76
	s_waitcnt lgkmcnt(0)
; __device__ __forceinline__ float bflo(unsigned w) { return __uint_as_float(w << 16); }
; __device__ __forceinline__ float bfhi(unsigned w) { return __uint_as_float(w & 0xffff0000u); }
; #define LAS __attribute__((address_space(3)))
; __device__ __forceinline__ float bflo(unsigned w) { return __uint_as_float(w << 16); }
; __device__ __forceinline__ float bfhi(unsigned w) { return __uint_as_float(w & 0xffff0000u); }
; __device__ __forceinline__ unsigned cvtpk(float lo, float hi) { const f32x2_t v = {lo, hi}; const bf16x2_t b = __builtin_convertvector(v, bf16x2_t); return __builtin_bit_cast(unsigned, b); }
; #define norm_gain INP(2)
; template <int MODE, bool FIXED>
; __device__ __forceinline__ void attn_unit(LAS unsigned char* lds, unsigned char* ws, const AttnParams& P, int l, int Tp, int sq, int h, int qb, int part, int np, int pslot, int tid, int wave, int lane) {
;     ...
;     {
;         const int row = lane >> 1, half = lane & 1;
;         const LAS f32x4* src = (const LAS f32x4*)(ost + row * 132 + half * 64);
;         float v[64];
; #pragma unroll
;         for (int k = 0; k < 16; ++k) { const f32x4 t = src[k]; v[4 * k] = t.x; v[4 * k + 1] = t.y; v[4 * k + 2] = t.z; v[4 * k + 3] = t.w; }
;         const size_t grow = (size_t)(seq0 + q0 + wave * 32 + row);
;         float rs = 1.f;
;         if (MODE == 1) { float ss = 0.f;
; #pragma unroll
;             for (int e = 0; e < 64; ++e) ss += v[e] * v[e];
;             ss += xshfl<1>(ss); rs = (1.0f / sqrtf(ss * (1.0f / 128.0f) + NORM_EPS)) * (1.0f - lin); }
;         const v4u* zp = (const v4u*)(PROJ + grow * LDP + zcol + half * 64);
;         bf16* yb = (bf16*)(ws + WS_Y + (MODE ? 2 : 1) * SZ_Y1) + grow * 1024 + h * 128 + half * 64;
; #pragma unroll
;         for (int k = 0; k < 8; ++k) { const v4u zw = zp[k];
;             const float z[8] = {bflo(zw.x), bfhi(zw.x), bflo(zw.y), bfhi(zw.y), bflo(zw.z), bfhi(zw.z), bflo(zw.w), bfhi(zw.w)};
;             float y[8];
; #pragma unroll
;             for (int e = 0; e < 8; ++e) { float g = 1.f; if (MODE == 1) g = P.norm_gain[half * 64 + 8 * k + e]; y[e] = v[8 * k + e] * rs * g * z[e]; }
;             v4u w; w.x = cvtpk(y[0], y[1]); w.y = cvtpk(y[2], y[3]); w.z = cvtpk(y[4], y[5]); w.w = cvtpk(y[6], y[7]);
;             *(v4u*)(yb + 8 * k) = w; }
	v_add3_u32 v6, s4, v6, v3
	ds_read_b128 v[66:69], v6
	ds_read_b128 v[62:65], v6 offset:16
	ds_read_b128 v[58:61], v6 offset:32
	ds_read_b128 v[54:57], v6 offset:48
	ds_read_b128 v[50:53], v6 offset:64
	ds_read_b128 v[46:49], v6 offset:80
	ds_read_b128 v[42:45], v6 offset:96
	ds_read_b128 v[38:41], v6 offset:112
	ds_read_b128 v[34:37], v6 offset:128
	ds_read_b128 v[30:33], v6 offset:144
	ds_read_b128 v[26:29], v6 offset:160
	ds_read_b128 v[22:25], v6 offset:176
	ds_read_b128 v[18:21], v6 offset:192
	ds_read_b128 v[14:17], v6 offset:208
	ds_read_b128 v[10:13], v6 offset:224
	ds_read_b128 v[6:9], v6 offset:240
	v_or_b32_e32 v70, s77, v5
	s_waitcnt lgkmcnt(14)
	v_mul_f32_e32 v5, v67, v67
	v_fmac_f32_e32 v5, v66, v66
	v_fmac_f32_e32 v5, v68, v68
	v_fmac_f32_e32 v5, v69, v69
	v_fmac_f32_e32 v5, v62, v62
	v_fmac_f32_e32 v5, v63, v63
	v_fmac_f32_e32 v5, v64, v64
	v_fmac_f32_e32 v5, v65, v65
	s_waitcnt lgkmcnt(13)
	v_fmac_f32_e32 v5, v58, v58
	v_fmac_f32_e32 v5, v59, v59
	v_fmac_f32_e32 v5, v60, v60
	v_fmac_f32_e32 v5, v61, v61
	s_waitcnt lgkmcnt(12)
	v_fmac_f32_e32 v5, v54, v54
	v_fmac_f32_e32 v5, v55, v55
	v_fmac_f32_e32 v5, v56, v56
	v_fmac_f32_e32 v5, v57, v57
	s_waitcnt lgkmcnt(11)
	v_fmac_f32_e32 v5, v50, v50
	v_fmac_f32_e32 v5, v51, v51
	v_fmac_f32_e32 v5, v52, v52
	v_fmac_f32_e32 v5, v53, v53
	s_waitcnt lgkmcnt(10)
	v_fmac_f32_e32 v5, v46, v46
	v_fmac_f32_e32 v5, v47, v47
	v_fmac_f32_e32 v5, v48, v48
	v_fmac_f32_e32 v5, v49, v49
	s_waitcnt lgkmcnt(9)
	v_fmac_f32_e32 v5, v42, v42
	v_fmac_f32_e32 v5, v43, v43
	v_fmac_f32_e32 v5, v44, v44
	v_fmac_f32_e32 v5, v45, v45
	s_waitcnt lgkmcnt(8)
	v_fmac_f32_e32 v5, v38, v38
	v_fmac_f32_e32 v5, v39, v39
	v_fmac_f32_e32 v5, v40, v40
	v_fmac_f32_e32 v5, v41, v41
	s_waitcnt lgkmcnt(7)
	v_fmac_f32_e32 v5, v34, v34
	v_fmac_f32_e32 v5, v35, v35
	v_fmac_f32_e32 v5, v36, v36
	v_fmac_f32_e32 v5, v37, v37
	s_waitcnt lgkmcnt(6)
	v_fmac_f32_e32 v5, v30, v30
	v_fmac_f32_e32 v5, v31, v31
	v_fmac_f32_e32 v5, v32, v32
	v_fmac_f32_e32 v5, v33, v33
	s_waitcnt lgkmcnt(5)
	v_fmac_f32_e32 v5, v26, v26
	v_fmac_f32_e32 v5, v27, v27
	v_fmac_f32_e32 v5, v28, v28
	v_fmac_f32_e32 v5, v29, v29
	s_waitcnt lgkmcnt(4)
	v_fmac_f32_e32 v5, v22, v22
	v_fmac_f32_e32 v5, v23, v23
	v_fmac_f32_e32 v5, v24, v24
	v_fmac_f32_e32 v5, v25, v25
	s_waitcnt lgkmcnt(3)
	v_fmac_f32_e32 v5, v18, v18
	v_fmac_f32_e32 v5, v19, v19
	v_fmac_f32_e32 v5, v20, v20
	v_fmac_f32_e32 v5, v21, v21
	s_waitcnt lgkmcnt(2)
	v_fmac_f32_e32 v5, v14, v14
	v_fmac_f32_e32 v5, v15, v15
	v_fmac_f32_e32 v5, v16, v16
	v_fmac_f32_e32 v5, v17, v17
	s_waitcnt lgkmcnt(1)
	v_fmac_f32_e32 v5, v10, v10
	v_fmac_f32_e32 v5, v11, v11
	v_pk_mul_f32 v[72:73], v[12:13], v[12:13]
	s_waitcnt lgkmcnt(0)
	v_pk_mul_f32 v[74:75], v[6:7], v[6:7]
	v_add_f32_e32 v5, v72, v5
	v_add_f32_e32 v5, v73, v5
	v_add_f32_e32 v5, v74, v5
	v_pk_mul_f32 v[72:73], v[8:9], v[8:9]
	v_add_f32_e32 v5, v75, v5
	v_add_f32_e32 v5, v72, v5
	v_add_f32_e32 v5, v73, v5
	ds_swizzle_b32 v72, v5 offset:swizzle(SWAP,1)
	s_mov_b32 s77, s61
	v_ashrrev_i32_e32 v71, 31, v70
	s_waitcnt lgkmcnt(0)
	v_add_f32_e32 v5, v5, v72
	v_fmamk_f32 v5, v5, 0x3c000000, v220
	v_cmp_gt_f32_e32 vcc, s33, v5
	v_mul_f32_e32 v72, 0x4f800000, v5
	s_nop 0
	v_cndmask_b32_e32 v5, v5, v72, vcc
	v_sqrt_f32_e32 v72, v5
	s_nop 0
	v_add_u32_e32 v73, -1, v72
	v_fma_f32 v74, -v73, v72, v5
	v_cmp_ge_f32_e64 s[4:5], 0, v74
	v_add_u32_e32 v74, 1, v72
	s_nop 0
	v_cndmask_b32_e64 v73, v72, v73, s[4:5]
	v_fma_f32 v72, -v74, v72, v5
	v_cmp_lt_f32_e64 s[4:5], 0, v72
	s_nop 1
	v_cndmask_b32_e64 v72, v73, v74, s[4:5]
	v_mul_f32_e32 v73, 0x37800000, v72
	v_cndmask_b32_e32 v72, v72, v73, vcc
	v_cmp_class_f32_e32 vcc, v5, v221
	s_nop 1
	v_cndmask_b32_e32 v5, v72, v5, vcc
	v_div_scale_f32 v72, s[4:5], v5, v5, 1.0
	v_rcp_f32_e32 v73, v72
	s_nop 0
	v_fma_f32 v74, -v72, v73, 1.0
	v_fmac_f32_e32 v73, v74, v73
	v_div_scale_f32 v74, vcc, 1.0, v5, 1.0
	v_mul_f32_e32 v75, v74, v73
	v_fma_f32 v77, -v72, v75, v74
	v_fmac_f32_e32 v75, v77, v73
	v_fma_f32 v72, -v72, v75, v74
	v_div_fmas_f32 v72, v72, v73, v75
	v_div_fixup_f32 v5, v72, v5, 1.0
	v_mov_b64_e32 v[72:73], s[50:51]
	v_mad_i64_i32 v[72:73], s[4:5], v70, s70, v[72:73]
	v_lshl_add_u64 v[72:73], v[72:73], 0, s[76:77]
	v_lshlrev_b32_e32 v74, 1, v76
	v_mov_b32_e32 v75, v4
	v_lshl_add_u64 v[76:77], v[72:73], 0, v[74:75]
	s_mov_b64 s[4:5], 0x4c00
	v_lshl_add_u64 v[72:73], v[76:77], 0, s[4:5]
	v_readlane_b32 s4, v252, 38
	v_lshlrev_b64 v[70:71], 11, v[70:71]
	v_readlane_b32 s5, v252, 39
	v_mul_f32_e32 v2, v2, v5
	v_pk_mul_f32 v[68:69], v[68:69], v[2:3] op_sel_hi:[1,0]
	v_lshl_add_u64 v[70:71], s[4:5], 0, v[70:71]
	v_lshl_add_u64 v[70:71], v[70:71], 0, s[76:77]
	v_lshl_add_u64 v[70:71], v[70:71], 0, v[74:75]
	v_add_co_u32_e32 v74, vcc, s3, v76
	v_pk_mul_f32 v[62:63], v[62:63], v[2:3] op_sel_hi:[1,0]
	s_nop 0
	v_addc_co_u32_e32 v75, vcc, 0, v77, vcc
	global_load_dwordx4 v[74:77], v[74:75], off offset:3072
	s_nop 0
	global_load_dwordx4 v[78:81], v[72:73], off offset:48
	global_load_dwordx4 v[82:85], v[72:73], off offset:32
	global_load_dwordx4 v[86:89], v[72:73], off offset:16
	global_load_dwordx4 v[90:93], v3, s[38:39] offset:16
	global_load_dwordx4 v[94:97], v3, s[38:39]
	v_pk_mul_f32 v[66:67], v[66:67], v[2:3] op_sel_hi:[1,0]
	v_pk_mul_f32 v[64:65], v[64:65], v[2:3] op_sel_hi:[1,0]
	v_pk_mul_f32 v[58:59], v[58:59], v[2:3] op_sel_hi:[1,0]
	v_pk_mul_f32 v[60:61], v[60:61], v[2:3] op_sel_hi:[1,0]
	v_pk_mul_f32 v[54:55], v[54:55], v[2:3] op_sel_hi:[1,0]
	v_pk_mul_f32 v[56:57], v[56:57], v[2:3] op_sel_hi:[1,0]
	v_pk_mul_f32 v[50:51], v[50:51], v[2:3] op_sel_hi:[1,0]
	v_pk_mul_f32 v[52:53], v[52:53], v[2:3] op_sel_hi:[1,0]
	v_pk_mul_f32 v[46:47], v[46:47], v[2:3] op_sel_hi:[1,0]
	v_pk_mul_f32 v[48:49], v[48:49], v[2:3] op_sel_hi:[1,0]
	v_pk_mul_f32 v[42:43], v[42:43], v[2:3] op_sel_hi:[1,0]
	v_pk_mul_f32 v[44:45], v[44:45], v[2:3] op_sel_hi:[1,0]
	v_pk_mul_f32 v[38:39], v[38:39], v[2:3] op_sel_hi:[1,0]
	v_pk_mul_f32 v[40:41], v[40:41], v[2:3] op_sel_hi:[1,0]
	v_pk_mul_f32 v[36:37], v[36:37], v[2:3] op_sel_hi:[1,0]
	v_pk_mul_f32 v[30:31], v[30:31], v[2:3] op_sel_hi:[1,0]
	v_pk_mul_f32 v[34:35], v[34:35], v[2:3] op_sel_hi:[1,0]
	v_pk_mul_f32 v[32:33], v[32:33], v[2:3] op_sel_hi:[1,0]
	v_pk_mul_f32 v[26:27], v[26:27], v[2:3] op_sel_hi:[1,0]
	v_pk_mul_f32 v[28:29], v[28:29], v[2:3] op_sel_hi:[1,0]
	v_pk_mul_f32 v[22:23], v[22:23], v[2:3] op_sel_hi:[1,0]
	v_pk_mul_f32 v[24:25], v[24:25], v[2:3] op_sel_hi:[1,0]
	v_pk_mul_f32 v[18:19], v[18:19], v[2:3] op_sel_hi:[1,0]
	v_pk_mul_f32 v[20:21], v[20:21], v[2:3] op_sel_hi:[1,0]
	v_pk_mul_f32 v[14:15], v[14:15], v[2:3] op_sel_hi:[1,0]
	v_pk_mul_f32 v[16:17], v[16:17], v[2:3] op_sel_hi:[1,0]
	v_pk_mul_f32 v[10:11], v[10:11], v[2:3] op_sel_hi:[1,0]
	v_pk_mul_f32 v[12:13], v[12:13], v[2:3] op_sel_hi:[1,0]
	v_pk_mul_f32 v[6:7], v[6:7], v[2:3] op_sel_hi:[1,0]
	s_waitcnt vmcnt(5)
; __device__ __forceinline__ float bflo(unsigned w) { return __uint_as_float(w << 16); }
; __device__ __forceinline__ float bfhi(unsigned w) { return __uint_as_float(w & 0xffff0000u); }
; __device__ __forceinline__ float bflo(unsigned w) { return __uint_as_float(w << 16); }
; __device__ __forceinline__ float bfhi(unsigned w) { return __uint_as_float(w & 0xffff0000u); }
; __device__ __forceinline__ unsigned cvtpk(float lo, float hi) { const f32x2_t v = {lo, hi}; const bf16x2_t b = __builtin_convertvector(v, bf16x2_t); return __builtin_bit_cast(unsigned, b); }
; #define norm_gain INP(2)
; template <int MODE, bool FIXED>
; __device__ __forceinline__ void attn_unit(LAS unsigned char* lds, unsigned char* ws, const AttnParams& P, int l, int Tp, int sq, int h, int qb, int part, int np, int pslot, int tid, int wave, int lane) {
;     ...
;         const v4u* zp = (const v4u*)(PROJ + grow * LDP + zcol + half * 64);
;         bf16* yb = (bf16*)(ws + WS_Y + (MODE ? 2 : 1) * SZ_Y1) + grow * 1024 + h * 128 + half * 64;
; #pragma unroll
;         for (int k = 0; k < 8; ++k) { const v4u zw = zp[k];
;             const float z[8] = {bflo(zw.x), bfhi(zw.x), bflo(zw.y), bfhi(zw.y), bflo(zw.z), bfhi(zw.z), bflo(zw.w), bfhi(zw.w)};
;             float y[8];
; #pragma unroll
;             for (int e = 0; e < 8; ++e) { float g = 1.f; if (MODE == 1) g = P.norm_gain[half * 64 + 8 * k + e]; y[e] = v[8 * k + e] * rs * g * z[e]; }
;             v4u w; w.x = cvtpk(y[0], y[1]); w.y = cvtpk(y[2], y[3]); w.z = cvtpk(y[4], y[5]); w.w = cvtpk(y[6], y[7]);
;             *(v4u*)(yb + 8 * k) = w; }
	v_lshlrev_b32_e32 v98, 16, v74
	v_and_b32_e32 v99, 0xffff0000, v74
	v_lshlrev_b32_e32 v74, 16, v75
	v_and_b32_e32 v75, 0xffff0000, v75
	s_waitcnt vmcnt(0)
	v_pk_mul_f32 v[68:69], v[96:97], v[68:69]
	v_pk_mul_f32 v[62:63], v[90:91], v[62:63]
	v_pk_mul_f32 v[68:69], v[68:69], v[74:75]
	v_lshlrev_b32_e32 v74, 16, v76
	v_and_b32_e32 v75, 0xffff0000, v76
	v_pk_mul_f32 v[66:67], v[94:95], v[66:67]
	v_pk_mul_f32 v[74:75], v[62:63], v[74:75]
	v_lshlrev_b32_e32 v62, 16, v77
	v_and_b32_e32 v63, 0xffff0000, v77
	v_pk_mul_f32 v[64:65], v[92:93], v[64:65]
	v_pk_mul_f32 v[66:67], v[66:67], v[98:99]
	v_pk_mul_f32 v[76:77], v[64:65], v[62:63]
	v_cvt_pk_bf16_f32 v62, v66, v67
	v_cvt_pk_bf16_f32 v63, v68, v69
	v_cvt_pk_bf16_f32 v64, v74, v75
	v_cvt_pk_bf16_f32 v65, v76, v77
	global_store_dwordx4 v[70:71], v[62:65], off
	global_load_dwordx4 v[62:65], v3, s[38:39] offset:48
	s_nop 0
	global_load_dwordx4 v[66:69], v3, s[38:39] offset:32
	v_lshlrev_b32_e32 v74, 16, v86
	v_and_b32_e32 v75, 0xffff0000, v86
	s_waitcnt vmcnt(1)
	v_pk_mul_f32 v[54:55], v[62:63], v[54:55]
	s_waitcnt vmcnt(0)
	v_pk_mul_f32 v[58:59], v[66:67], v[58:59]
	v_lshlrev_b32_e32 v66, 16, v87
	v_and_b32_e32 v67, 0xffff0000, v87
	v_pk_mul_f32 v[60:61], v[68:69], v[60:61]
	v_pk_mul_f32 v[56:57], v[64:65], v[56:57]
	v_pk_mul_f32 v[60:61], v[60:61], v[66:67]
	v_lshlrev_b32_e32 v66, 16, v88
	v_and_b32_e32 v67, 0xffff0000, v88
	v_pk_mul_f32 v[62:63], v[54:55], v[66:67]
	v_lshlrev_b32_e32 v54, 16, v89
	v_and_b32_e32 v55, 0xffff0000, v89
	v_pk_mul_f32 v[58:59], v[58:59], v[74:75]
	v_pk_mul_f32 v[64:65], v[56:57], v[54:55]
	v_cvt_pk_bf16_f32 v54, v58, v59
	v_cvt_pk_bf16_f32 v55, v60, v61
	v_cvt_pk_bf16_f32 v56, v62, v63
	v_cvt_pk_bf16_f32 v57, v64, v65
	global_store_dwordx4 v[70:71], v[54:57], off offset:16
	global_load_dwordx4 v[54:57], v3, s[38:39] offset:80
	s_nop 0
	global_load_dwordx4 v[58:61], v3, s[38:39] offset:64
	v_lshlrev_b32_e32 v62, 16, v82
	v_and_b32_e32 v63, 0xffff0000, v82
	s_waitcnt vmcnt(1)
	v_pk_mul_f32 v[46:47], v[54:55], v[46:47]
	s_waitcnt vmcnt(0)
	v_pk_mul_f32 v[50:51], v[58:59], v[50:51]
	v_lshlrev_b32_e32 v58, 16, v83
	v_and_b32_e32 v59, 0xffff0000, v83
	v_pk_mul_f32 v[52:53], v[60:61], v[52:53]
	v_pk_mul_f32 v[48:49], v[56:57], v[48:49]
	v_pk_mul_f32 v[52:53], v[52:53], v[58:59]
	v_lshlrev_b32_e32 v58, 16, v84
	v_and_b32_e32 v59, 0xffff0000, v84
	v_pk_mul_f32 v[54:55], v[46:47], v[58:59]
	v_lshlrev_b32_e32 v46, 16, v85
	v_and_b32_e32 v47, 0xffff0000, v85
	v_pk_mul_f32 v[50:51], v[50:51], v[62:63]
	v_pk_mul_f32 v[56:57], v[48:49], v[46:47]
	v_cvt_pk_bf16_f32 v46, v50, v51
	v_cvt_pk_bf16_f32 v47, v52, v53
	v_cvt_pk_bf16_f32 v48, v54, v55
	v_cvt_pk_bf16_f32 v49, v56, v57
	global_store_dwordx4 v[70:71], v[46:49], off offset:32
	global_load_dwordx4 v[46:49], v3, s[38:39] offset:112
	s_nop 0
	global_load_dwordx4 v[50:53], v3, s[38:39] offset:96
	v_lshlrev_b32_e32 v54, 16, v78
	v_and_b32_e32 v55, 0xffff0000, v78
	s_waitcnt vmcnt(1)
	v_pk_mul_f32 v[38:39], v[46:47], v[38:39]
	s_waitcnt vmcnt(0)
	v_pk_mul_f32 v[42:43], v[50:51], v[42:43]
	v_lshlrev_b32_e32 v50, 16, v79
	v_and_b32_e32 v51, 0xffff0000, v79
	v_pk_mul_f32 v[44:45], v[52:53], v[44:45]
	v_pk_mul_f32 v[40:41], v[48:49], v[40:41]
	v_pk_mul_f32 v[44:45], v[44:45], v[50:51]
	v_lshlrev_b32_e32 v50, 16, v80
	v_and_b32_e32 v51, 0xffff0000, v80
	v_pk_mul_f32 v[46:47], v[38:39], v[50:51]
	v_lshlrev_b32_e32 v38, 16, v81
	v_and_b32_e32 v39, 0xffff0000, v81
	v_pk_mul_f32 v[42:43], v[42:43], v[54:55]
	v_pk_mul_f32 v[48:49], v[40:41], v[38:39]
	v_cvt_pk_bf16_f32 v38, v42, v43
	v_cvt_pk_bf16_f32 v39, v44, v45
	v_cvt_pk_bf16_f32 v40, v46, v47
	v_cvt_pk_bf16_f32 v41, v48, v49
	global_store_dwordx4 v[70:71], v[38:41], off offset:48
	global_load_dwordx4 v[38:41], v[72:73], off offset:112
	s_nop 0
	global_load_dwordx4 v[42:45], v[72:73], off offset:96
	global_load_dwordx4 v[46:49], v[72:73], off offset:80
	global_load_dwordx4 v[54:57], v[72:73], off offset:64
	global_load_dwordx4 v[50:53], v3, s[38:39] offset:144
	global_load_dwordx4 v[60:63], v3, s[38:39] offset:128
	s_waitcnt vmcnt(2)
; __device__ __forceinline__ float bflo(unsigned w) { return __uint_as_float(w << 16); }
; __device__ __forceinline__ float bfhi(unsigned w) { return __uint_as_float(w & 0xffff0000u); }
; __device__ __forceinline__ float bflo(unsigned w) { return __uint_as_float(w << 16); }
; __device__ __forceinline__ float bfhi(unsigned w) { return __uint_as_float(w & 0xffff0000u); }
; __device__ __forceinline__ unsigned cvtpk(float lo, float hi) { const f32x2_t v = {lo, hi}; const bf16x2_t b = __builtin_convertvector(v, bf16x2_t); return __builtin_bit_cast(unsigned, b); }
; #define norm_gain INP(2)
; template <int MODE, bool FIXED>
; __device__ __forceinline__ void attn_unit(LAS unsigned char* lds, unsigned char* ws, const AttnParams& P, int l, int Tp, int sq, int h, int qb, int part, int np, int pslot, int tid, int wave, int lane) {
;     ...
;         const v4u* zp = (const v4u*)(PROJ + grow * LDP + zcol + half * 64);
;         bf16* yb = (bf16*)(ws + WS_Y + (MODE ? 2 : 1) * SZ_Y1) + grow * 1024 + h * 128 + half * 64;
; #pragma unroll
;         for (int k = 0; k < 8; ++k) { const v4u zw = zp[k];
;             const float z[8] = {bflo(zw.x), bfhi(zw.x), bflo(zw.y), bfhi(zw.y), bflo(zw.z), bfhi(zw.z), bflo(zw.w), bfhi(zw.w)};
;             float y[8];
; #pragma unroll
;             for (int e = 0; e < 8; ++e) { float g = 1.f; if (MODE == 1) g = P.norm_gain[half * 64 + 8 * k + e]; y[e] = v[8 * k + e] * rs * g * z[e]; }
;             v4u w; w.x = cvtpk(y[0], y[1]); w.y = cvtpk(y[2], y[3]); w.z = cvtpk(y[4], y[5]); w.w = cvtpk(y[6], y[7]);
;             *(v4u*)(yb + 8 * k) = w; }
;     }
;     asm volatile("s_waitcnt lgkmcnt(0)" ::: "memory"); __builtin_amdgcn_s_barrier(); asm volatile("" ::: "memory");
	v_lshlrev_b32_e32 v58, 16, v54
	v_and_b32_e32 v59, 0xffff0000, v54
	v_lshlrev_b32_e32 v54, 16, v55
	v_and_b32_e32 v55, 0xffff0000, v55
	s_waitcnt vmcnt(0)
	v_pk_mul_f32 v[36:37], v[62:63], v[36:37]
	v_pk_mul_f32 v[30:31], v[50:51], v[30:31]
	v_pk_mul_f32 v[36:37], v[36:37], v[54:55]
	v_lshlrev_b32_e32 v54, 16, v56
	v_and_b32_e32 v55, 0xffff0000, v56
	v_pk_mul_f32 v[34:35], v[60:61], v[34:35]
	v_pk_mul_f32 v[50:51], v[30:31], v[54:55]
	v_lshlrev_b32_e32 v30, 16, v57
	v_and_b32_e32 v31, 0xffff0000, v57
	v_pk_mul_f32 v[32:33], v[52:53], v[32:33]
	v_pk_mul_f32 v[34:35], v[34:35], v[58:59]
	v_pk_mul_f32 v[52:53], v[32:33], v[30:31]
	v_cvt_pk_bf16_f32 v30, v34, v35
	v_cvt_pk_bf16_f32 v31, v36, v37
	v_cvt_pk_bf16_f32 v32, v50, v51
	v_cvt_pk_bf16_f32 v33, v52, v53
	global_store_dwordx4 v[70:71], v[30:33], off offset:64
	global_load_dwordx4 v[30:33], v3, s[38:39] offset:176
	s_nop 0
	global_load_dwordx4 v[34:37], v3, s[38:39] offset:160
	v_lshlrev_b32_e32 v50, 16, v46
	v_and_b32_e32 v51, 0xffff0000, v46
	s_waitcnt vmcnt(1)
	v_pk_mul_f32 v[22:23], v[30:31], v[22:23]
	s_waitcnt vmcnt(0)
	v_pk_mul_f32 v[26:27], v[34:35], v[26:27]
	v_lshlrev_b32_e32 v34, 16, v47
	v_and_b32_e32 v35, 0xffff0000, v47
	v_pk_mul_f32 v[28:29], v[36:37], v[28:29]
	v_pk_mul_f32 v[24:25], v[24:25], v[32:33]
	v_pk_mul_f32 v[28:29], v[28:29], v[34:35]
	v_lshlrev_b32_e32 v34, 16, v48
	v_and_b32_e32 v35, 0xffff0000, v48
	v_pk_mul_f32 v[30:31], v[22:23], v[34:35]
	v_lshlrev_b32_e32 v22, 16, v49
	v_and_b32_e32 v23, 0xffff0000, v49
	v_pk_mul_f32 v[26:27], v[26:27], v[50:51]
	v_pk_mul_f32 v[32:33], v[24:25], v[22:23]
	v_cvt_pk_bf16_f32 v22, v26, v27
	v_cvt_pk_bf16_f32 v23, v28, v29
	v_cvt_pk_bf16_f32 v24, v30, v31
	v_cvt_pk_bf16_f32 v25, v32, v33
	global_store_dwordx4 v[70:71], v[22:25], off offset:80
	global_load_dwordx4 v[22:25], v3, s[38:39] offset:208
	s_nop 0
	global_load_dwordx4 v[26:29], v3, s[38:39] offset:192
	v_lshlrev_b32_e32 v30, 16, v42
	v_and_b32_e32 v31, 0xffff0000, v42
	s_waitcnt vmcnt(1)
	v_pk_mul_f32 v[14:15], v[14:15], v[22:23]
	s_waitcnt vmcnt(0)
	v_pk_mul_f32 v[18:19], v[18:19], v[26:27]
	v_lshlrev_b32_e32 v26, 16, v43
	v_and_b32_e32 v27, 0xffff0000, v43
	v_pk_mul_f32 v[20:21], v[20:21], v[28:29]
	v_pk_mul_f32 v[16:17], v[16:17], v[24:25]
	v_pk_mul_f32 v[20:21], v[20:21], v[26:27]
	v_lshlrev_b32_e32 v26, 16, v44
	v_and_b32_e32 v27, 0xffff0000, v44
	v_pk_mul_f32 v[22:23], v[14:15], v[26:27]
	v_lshlrev_b32_e32 v14, 16, v45
	v_and_b32_e32 v15, 0xffff0000, v45
	v_pk_mul_f32 v[18:19], v[18:19], v[30:31]
	v_pk_mul_f32 v[24:25], v[16:17], v[14:15]
	v_cvt_pk_bf16_f32 v14, v18, v19
	v_cvt_pk_bf16_f32 v15, v20, v21
	v_cvt_pk_bf16_f32 v16, v22, v23
	v_cvt_pk_bf16_f32 v17, v24, v25
	global_store_dwordx4 v[70:71], v[14:17], off offset:96
	global_load_dwordx4 v[14:17], v3, s[38:39] offset:240
	s_nop 0
	global_load_dwordx4 v[18:21], v3, s[38:39] offset:224
	v_pk_mul_f32 v[2:3], v[8:9], v[2:3] op_sel_hi:[1,0]
	v_lshlrev_b32_e32 v22, 16, v38
	v_and_b32_e32 v23, 0xffff0000, v38
	s_waitcnt vmcnt(1)
	v_pk_mul_f32 v[6:7], v[6:7], v[14:15]
	s_waitcnt vmcnt(0)
	v_pk_mul_f32 v[10:11], v[10:11], v[18:19]
	v_lshlrev_b32_e32 v18, 16, v39
	v_and_b32_e32 v19, 0xffff0000, v39
	v_pk_mul_f32 v[12:13], v[12:13], v[20:21]
	v_pk_mul_f32 v[2:3], v[2:3], v[16:17]
	v_pk_mul_f32 v[12:13], v[12:13], v[18:19]
	v_lshlrev_b32_e32 v18, 16, v40
	v_and_b32_e32 v19, 0xffff0000, v40
	v_pk_mul_f32 v[14:15], v[6:7], v[18:19]
	v_lshlrev_b32_e32 v6, 16, v41
	v_and_b32_e32 v7, 0xffff0000, v41
	v_pk_mul_f32 v[10:11], v[10:11], v[22:23]
	v_pk_mul_f32 v[2:3], v[2:3], v[6:7]
	v_cvt_pk_bf16_f32 v6, v10, v11
	v_cvt_pk_bf16_f32 v7, v12, v13
	v_cvt_pk_bf16_f32 v8, v14, v15
	v_cvt_pk_bf16_f32 v9, v2, v3
	global_store_dwordx4 v[70:71], v[6:9], off offset:112
	s_barrier

; __device__ __forceinline__ void gdn_scan_unit(LAS unsigned char* lds, unsigned char* ws, int Tp, int sq, int h, int d, int half, int tid, int wave, int lane) {
;     ...
;         for (int n = 0; n < Nc; ++n) {
;             const LAS unsigned char* buf = lds + (n & 1) * SC_BUF + lane * 16;
;             const float gam = *(const LAS float*)(lds + (n & 1) * SC_BUF + REC_GAM);
;     ...
;             bf16x8 A[8], B[8];
; #pragma unroll
;             for (int e = 0; e < 8; ++e) { A[e] = LDF(FWO(e & 1, e >> 2, (e >> 1) & 1)); B[e] = LDF(FWO(e & 1, 2 + (e >> 2), (e >> 1) & 1)); }
;             v4u ua[2], ub[2];
; #pragma unroll
;             for (int i = 0; i < 2; ++i) { const LAS v4u* pu = (const LAS v4u*)(lds + (n & 1) * SC_BUF + REC_FU + ((w * 2 + i) * 64 + lane) * 32); ua[i] = pu[0]; ub[i] = pu[1]; }
;             __builtin_amdgcn_sched_barrier(0);
;             bf16x8 Sf[4][2];
; #pragma unroll
;             for (int t = 0; t < 4; ++t) { Sf[t][0] = pack8(S[t], 0); Sf[t][1] = pack8(S[t], 1); }
;             f32x16 V[2];
; #pragma unroll
;             for (int i = 0; i < 2; ++i) { const v4u a = ua[i], b = ub[i];
;                 V[i][0] = bflo(a.x); V[i][1] = bfhi(a.x); V[i][2] = bflo(a.y); V[i][3] = bfhi(a.y); V[i][4] = bflo(a.z); V[i][5] = bfhi(a.z); V[i][6] = bflo(a.w); V[i][7] = bfhi(a.w);
;                 V[i][8] = bflo(b.x); V[i][9] = bfhi(b.x); V[i][10] = bflo(b.y); V[i][11] = bfhi(b.y); V[i][12] = bflo(b.z); V[i][13] = bfhi(b.z); V[i][14] = bflo(b.w); V[i][15] = bfhi(b.w); }
;             __builtin_amdgcn_sched_barrier(0);
; #pragma unroll
;             for (int e = 0; e < 8; ++e) V[e & 1] = MFMA32(A[e], Sf[e >> 2][(e >> 1) & 1], V[e & 1]);
;             __builtin_amdgcn_sched_barrier(0);
; #pragma unroll
;             for (int e = 0; e < 8; ++e) A[e] = LDF(FQO(e & 1, e >> 2, (e >> 1) & 1));
;             __builtin_amdgcn_sched_barrier(0);
; #pragma unroll
;             for (int e = 0; e < 8; ++e) V[e & 1] = MFMA32(B[e], Sf[2 + (e >> 2)][(e >> 1) & 1], V[e & 1]);
;             __builtin_amdgcn_sched_barrier(0);
; #pragma unroll
;             for (int e = 0; e < 8; ++e) B[e] = LDF(FQO(e & 1, 2 + (e >> 2), (e >> 1) & 1));
;             __builtin_amdgcn_sched_barrier(0);
;             f32x16 O[2];
; #pragma unroll
;             for (int i = 0; i < 2; ++i)
; #pragma unroll
;                 for (int r = 0; r < 16; ++r) O[i][r] = 0.f;
; #pragma unroll
.LBB0_974:
	s_bitcmp1_b32 s4, 0
	s_cselect_b32 s9, 0x12000, 0
	s_add_i32 s9, s9, 0
	v_add_u32_e32 v190, s9, v3
	ds_read_b128 v[82:85], v190
	ds_read_b128 v[86:89], v190 offset:1024
	ds_read_b128 v[90:93], v190 offset:4096
	ds_read_b128 v[70:73], v190 offset:5120
	ds_read_b128 v[94:97], v190 offset:8192
	ds_read_b128 v[98:101], v190 offset:9216
	ds_read_b128 v[158:161], v190 offset:12288
	ds_read_b128 v[74:77], v190 offset:13312
	ds_read_b128 v[162:165], v190 offset:2048
	ds_read_b128 v[166:169], v190 offset:3072
	ds_read_b128 v[170:173], v190 offset:6144
	ds_read_b128 v[174:177], v190 offset:7168
	ds_read_b128 v[178:181], v190 offset:10240
	ds_read_b128 v[182:185], v190 offset:11264
	ds_read_b128 v[186:189], v190 offset:14336
	ds_read_b128 v[200:203], v190 offset:15360
	v_mov_b32_e32 v2, s9
	s_add_i32 s9, s9, s5
	v_add_u32_e32 v78, s9, v136
	ds_read_b32 v2, v2 offset:51200
	ds_read_b128 v[102:105], v78 offset:57344
	ds_read_b128 v[106:109], v78 offset:57360
	ds_read_b128 v[110:113], v78 offset:59392
	ds_read_b128 v[114:117], v78 offset:59408
	v_cvt_pk_bf16_f32 v78, v54, v55
	v_cvt_pk_bf16_f32 v79, v56, v57
	v_cvt_pk_bf16_f32 v80, v58, v59
	v_cvt_pk_bf16_f32 v81, v60, v61
	v_cvt_pk_bf16_f32 v204, v62, v63
	v_cvt_pk_bf16_f32 v205, v64, v65
	v_cvt_pk_bf16_f32 v206, v66, v67
	v_cvt_pk_bf16_f32 v207, v68, v69
	v_cvt_pk_bf16_f32 v208, v38, v39
	v_cvt_pk_bf16_f32 v209, v40, v41
	v_cvt_pk_bf16_f32 v210, v42, v43
	v_cvt_pk_bf16_f32 v211, v44, v45
	v_cvt_pk_bf16_f32 v212, v46, v47
	v_cvt_pk_bf16_f32 v213, v48, v49
	v_cvt_pk_bf16_f32 v214, v50, v51
	v_cvt_pk_bf16_f32 v215, v52, v53
	v_cvt_pk_bf16_f32 v142, v22, v23
	v_cvt_pk_bf16_f32 v143, v24, v25
	v_cvt_pk_bf16_f32 v144, v26, v27
	v_cvt_pk_bf16_f32 v145, v28, v29
	v_cvt_pk_bf16_f32 v146, v30, v31
	v_cvt_pk_bf16_f32 v147, v32, v33
	v_cvt_pk_bf16_f32 v148, v34, v35
	v_cvt_pk_bf16_f32 v149, v36, v37
	v_cvt_pk_bf16_f32 v150, v6, v7
	v_cvt_pk_bf16_f32 v151, v8, v9
	v_cvt_pk_bf16_f32 v152, v10, v11
	v_cvt_pk_bf16_f32 v153, v12, v13
	v_cvt_pk_bf16_f32 v154, v14, v15
	v_cvt_pk_bf16_f32 v155, v16, v17
	v_cvt_pk_bf16_f32 v156, v18, v19
	v_cvt_pk_bf16_f32 v157, v20, v21
	s_waitcnt lgkmcnt(0)
	v_lshlrev_b32_e32 v118, 16, v102
	v_and_b32_e32 v119, 0xffff0000, v102
	v_lshlrev_b32_e32 v120, 16, v103
	v_and_b32_e32 v121, 0xffff0000, v103
	v_lshlrev_b32_e32 v122, 16, v104
	v_and_b32_e32 v123, 0xffff0000, v104
	v_lshlrev_b32_e32 v124, 16, v105
	v_and_b32_e32 v125, 0xffff0000, v105
	v_lshlrev_b32_e32 v126, 16, v106
	v_and_b32_e32 v127, 0xffff0000, v106
	v_lshlrev_b32_e32 v128, 16, v107
	v_and_b32_e32 v129, 0xffff0000, v107
	v_lshlrev_b32_e32 v130, 16, v108
	v_and_b32_e32 v131, 0xffff0000, v108
	v_lshlrev_b32_e32 v132, 16, v109
	v_and_b32_e32 v133, 0xffff0000, v109
	v_lshlrev_b32_e32 v102, 16, v110
	v_and_b32_e32 v103, 0xffff0000, v110
	v_lshlrev_b32_e32 v104, 16, v111
	v_and_b32_e32 v105, 0xffff0000, v111
	v_lshlrev_b32_e32 v106, 16, v112
	v_and_b32_e32 v107, 0xffff0000, v112
	v_lshlrev_b32_e32 v108, 16, v113
	v_and_b32_e32 v109, 0xffff0000, v113
	v_lshlrev_b32_e32 v110, 16, v114
	v_and_b32_e32 v111, 0xffff0000, v114
	v_lshlrev_b32_e32 v112, 16, v115
	v_and_b32_e32 v113, 0xffff0000, v115
	v_lshlrev_b32_e32 v114, 16, v116
	v_and_b32_e32 v115, 0xffff0000, v116
	v_lshlrev_b32_e32 v116, 16, v117
	v_and_b32_e32 v117, 0xffff0000, v117
	v_mfma_f32_32x32x16_bf16 v[118:133], v[82:85], v[78:81], v[118:133]
	s_nop 0
	v_mfma_f32_32x32x16_bf16 v[102:117], v[94:97], v[78:81], v[102:117]
	v_mfma_f32_32x32x16_bf16 v[118:133], v[86:89], v[204:207], v[118:133]
	v_mfma_f32_32x32x16_bf16 v[102:117], v[98:101], v[204:207], v[102:117]
	v_mfma_f32_32x32x16_bf16 v[118:133], v[162:165], v[208:211], v[118:133]
	v_mfma_f32_32x32x16_bf16 v[102:117], v[178:181], v[208:211], v[102:117]
	v_mfma_f32_32x32x16_bf16 v[118:133], v[166:169], v[212:215], v[118:133]
	v_mfma_f32_32x32x16_bf16 v[102:117], v[182:185], v[212:215], v[102:117]
	ds_read_b128 v[82:85], v190 offset:16384
	ds_read_b128 v[162:165], v190 offset:17408
	ds_read_b128 v[166:169], v190 offset:24576
	ds_read_b128 v[178:181], v190 offset:25600
	ds_read_b128 v[182:185], v190 offset:18432
	ds_read_b128 v[216:219], v190 offset:19456
	ds_read_b128 v[236:239], v190 offset:26624
	ds_read_b128 v[240:243], v190 offset:27648
	v_mfma_f32_32x32x16_bf16 v[118:133], v[90:93], v[142:145], v[118:133]
	v_mfma_f32_32x32x16_bf16 v[102:117], v[158:161], v[142:145], v[102:117]
	v_mfma_f32_32x32x16_bf16 v[118:133], v[70:73], v[146:149], v[118:133]
	v_mfma_f32_32x32x16_bf16 v[102:117], v[74:77], v[146:149], v[102:117]
	v_mfma_f32_32x32x16_bf16 v[118:133], v[170:173], v[150:153], v[118:133]
	v_mfma_f32_32x32x16_bf16 v[102:117], v[186:189], v[150:153], v[102:117]
	v_mfma_f32_32x32x16_bf16 v[118:133], v[174:177], v[154:157], v[118:133]
	v_mfma_f32_32x32x16_bf16 v[102:117], v[200:203], v[154:157], v[102:117]
	ds_read_b128 v[158:161], v190 offset:20480
	ds_read_b128 v[170:173], v190 offset:21504
	ds_read_b128 v[174:177], v190 offset:28672
	ds_read_b128 v[186:189], v190 offset:29696
	ds_read_b128 v[200:203], v190 offset:22528
	ds_read_b128 v[244:247], v190 offset:23552
	ds_read_b128 v[228:231], v190 offset:30720
	ds_read_b128 v[194:197], v190 offset:31744
	s_waitcnt lgkmcnt(14)
	v_mfma_f32_32x32x16_bf16 v[86:101], v[82:85], v[78:81], 0
	s_waitcnt lgkmcnt(13)
	v_mfma_f32_32x32x16_bf16 v[70:85], v[166:169], v[78:81], 0
	v_mfma_f32_32x32x16_bf16 v[86:101], v[162:165], v[204:207], v[86:101]
	s_waitcnt lgkmcnt(12)
	v_mfma_f32_32x32x16_bf16 v[70:85], v[178:181], v[204:207], v[70:85]
	s_waitcnt lgkmcnt(11)
	v_mfma_f32_32x32x16_bf16 v[86:101], v[182:185], v[208:211], v[86:101]
	s_waitcnt lgkmcnt(9)
; #define MFMA32(a, b, c) __builtin_amdgcn_mfma_f32_32x32x16_bf16((a), (b), (c), 0, 0, 0)
; __device__ __forceinline__ void gdn_scan_unit(LAS unsigned char* lds, unsigned char* ws, int Tp, int sq, int h, int d, int half, int tid, int wave, int lane) {
;     ...
;             for (int e = 0; e < 8; ++e) O[e & 1] = MFMA32(A[e], Sf[e >> 2][(e >> 1) & 1], O[e & 1]);
;             __builtin_amdgcn_sched_barrier(0);
; #pragma unroll
;             for (int e = 0; e < 8; ++e) A[e] = LDF(FKO(e & 3, 0, e >> 2));
;             bf16x8 Vf[2][2];
; #pragma unroll
;             for (int i = 0; i < 2; ++i) { Vf[i][0] = pack8(V[i], 0); Vf[i][1] = pack8(V[i], 1); }
; #pragma unroll
;             for (int t = 0; t < 4; ++t)
; #pragma unroll
;                 for (int r = 0; r < 16; ++r) S[t][r] *= gam;
;             __builtin_amdgcn_sched_barrier(0);
; #pragma unroll
;             for (int e = 0; e < 8; ++e) O[e & 1] = MFMA32(B[e], Sf[2 + (e >> 2)][(e >> 1) & 1], O[e & 1]);
;             __builtin_amdgcn_sched_barrier(0);
; #pragma unroll
;             for (int e = 0; e < 8; ++e) B[e] = LDF(FKO(e & 3, 1, e >> 2));
;             __builtin_amdgcn_sched_barrier(0);
; #pragma unroll
;             for (int e = 0; e < 8; ++e) S[e & 3] = MFMA32(A[e], Vf[0][e >> 2], S[e & 3]);
;             __builtin_amdgcn_sched_barrier(0);
;             A[0] = LDF(FQKO(0, 0, 0)); A[1] = LDF(FQKO(1, 0, 0)); A[2] = LDF(FQKO(0, 0, 1)); A[3] = LDF(FQKO(1, 0, 1)); A[4] = LDF(FQKO(1, 1, 0)); A[5] = LDF(FQKO(1, 1, 1));
;             __builtin_amdgcn_sched_barrier(0);
; #pragma unroll
;             for (int e = 0; e < 8; ++e) S[e & 3] = MFMA32(B[e], Vf[1][e >> 2], S[e & 3]);
	v_mfma_f32_32x32x16_bf16 v[70:85], v[236:239], v[208:211], v[70:85]
	v_mfma_f32_32x32x16_bf16 v[86:101], v[216:219], v[212:215], v[86:101]
	s_waitcnt lgkmcnt(8)
	v_mfma_f32_32x32x16_bf16 v[70:85], v[240:243], v[212:215], v[70:85]
	ds_read_b128 v[162:165], v190 offset:32768
	ds_read_b128 v[166:169], v190 offset:33792
	ds_read_b128 v[178:181], v190 offset:36864
	ds_read_b128 v[182:185], v190 offset:37888
	ds_read_b128 v[204:207], v190 offset:40960
	ds_read_b128 v[208:211], v190 offset:41984
	ds_read_b128 v[212:215], v190 offset:45056
	ds_read_b128 v[216:219], v190 offset:46080
	v_pk_mul_f32 v[68:69], v[68:69], v[2:3] op_sel_hi:[1,0]
	v_pk_mul_f32 v[66:67], v[66:67], v[2:3] op_sel_hi:[1,0]
	v_pk_mul_f32 v[64:65], v[64:65], v[2:3] op_sel_hi:[1,0]
	v_pk_mul_f32 v[62:63], v[62:63], v[2:3] op_sel_hi:[1,0]
	v_pk_mul_f32 v[60:61], v[60:61], v[2:3] op_sel_hi:[1,0]
	v_pk_mul_f32 v[58:59], v[58:59], v[2:3] op_sel_hi:[1,0]
	v_pk_mul_f32 v[56:57], v[56:57], v[2:3] op_sel_hi:[1,0]
	v_pk_mul_f32 v[54:55], v[54:55], v[2:3] op_sel_hi:[1,0]
	v_pk_mul_f32 v[52:53], v[52:53], v[2:3] op_sel_hi:[1,0]
	v_pk_mul_f32 v[50:51], v[50:51], v[2:3] op_sel_hi:[1,0]
	v_pk_mul_f32 v[48:49], v[48:49], v[2:3] op_sel_hi:[1,0]
	v_pk_mul_f32 v[46:47], v[46:47], v[2:3] op_sel_hi:[1,0]
	v_pk_mul_f32 v[44:45], v[44:45], v[2:3] op_sel_hi:[1,0]
	v_pk_mul_f32 v[42:43], v[42:43], v[2:3] op_sel_hi:[1,0]
	v_pk_mul_f32 v[40:41], v[40:41], v[2:3] op_sel_hi:[1,0]
	v_pk_mul_f32 v[38:39], v[38:39], v[2:3] op_sel_hi:[1,0]
	v_pk_mul_f32 v[36:37], v[36:37], v[2:3] op_sel_hi:[1,0]
	v_pk_mul_f32 v[34:35], v[34:35], v[2:3] op_sel_hi:[1,0]
	v_pk_mul_f32 v[32:33], v[32:33], v[2:3] op_sel_hi:[1,0]
	v_pk_mul_f32 v[30:31], v[30:31], v[2:3] op_sel_hi:[1,0]
	v_pk_mul_f32 v[28:29], v[28:29], v[2:3] op_sel_hi:[1,0]
	v_pk_mul_f32 v[26:27], v[26:27], v[2:3] op_sel_hi:[1,0]
	v_pk_mul_f32 v[24:25], v[24:25], v[2:3] op_sel_hi:[1,0]
	v_pk_mul_f32 v[22:23], v[22:23], v[2:3] op_sel_hi:[1,0]
	v_pk_mul_f32 v[20:21], v[20:21], v[2:3] op_sel_hi:[1,0]
	v_pk_mul_f32 v[18:19], v[18:19], v[2:3] op_sel_hi:[1,0]
	v_pk_mul_f32 v[16:17], v[16:17], v[2:3] op_sel_hi:[1,0]
	v_pk_mul_f32 v[14:15], v[14:15], v[2:3] op_sel_hi:[1,0]
	v_pk_mul_f32 v[12:13], v[12:13], v[2:3] op_sel_hi:[1,0]
	v_pk_mul_f32 v[10:11], v[10:11], v[2:3] op_sel_hi:[1,0]
	v_pk_mul_f32 v[8:9], v[8:9], v[2:3] op_sel_hi:[1,0]
	v_pk_mul_f32 v[6:7], v[6:7], v[2:3] op_sel_hi:[1,0]
	v_cvt_pk_bf16_f32 v118, v118, v119
	v_cvt_pk_bf16_f32 v119, v120, v121
	v_cvt_pk_bf16_f32 v120, v122, v123
	v_cvt_pk_bf16_f32 v121, v124, v125
	v_cvt_pk_bf16_f32 v122, v126, v127
	v_cvt_pk_bf16_f32 v123, v128, v129
	v_cvt_pk_bf16_f32 v124, v130, v131
	v_cvt_pk_bf16_f32 v125, v132, v133
	v_cvt_pk_bf16_f32 v102, v102, v103
	v_cvt_pk_bf16_f32 v103, v104, v105
	v_cvt_pk_bf16_f32 v104, v106, v107
	v_cvt_pk_bf16_f32 v105, v108, v109
	v_cvt_pk_bf16_f32 v106, v110, v111
	v_cvt_pk_bf16_f32 v107, v112, v113
	v_cvt_pk_bf16_f32 v108, v114, v115
	v_cvt_pk_bf16_f32 v109, v116, v117
	s_waitcnt lgkmcnt(14)
	v_mfma_f32_32x32x16_bf16 v[86:101], v[158:161], v[142:145], v[86:101]
	s_waitcnt lgkmcnt(13)
	v_mfma_f32_32x32x16_bf16 v[70:85], v[174:177], v[142:145], v[70:85]
	v_mfma_f32_32x32x16_bf16 v[86:101], v[170:173], v[146:149], v[86:101]
	s_waitcnt lgkmcnt(12)
	v_mfma_f32_32x32x16_bf16 v[70:85], v[186:189], v[146:149], v[70:85]
	s_waitcnt lgkmcnt(11)
	v_mfma_f32_32x32x16_bf16 v[86:101], v[200:203], v[150:153], v[86:101]
	s_waitcnt lgkmcnt(9)
	v_mfma_f32_32x32x16_bf16 v[70:85], v[228:231], v[150:153], v[70:85]
	v_mfma_f32_32x32x16_bf16 v[86:101], v[244:247], v[154:157], v[86:101]
	s_waitcnt lgkmcnt(8)
	v_mfma_f32_32x32x16_bf16 v[70:85], v[194:197], v[154:157], v[70:85]
	ds_read_b128 v[110:113], v190 offset:34816
	ds_read_b128 v[114:117], v190 offset:35840
	ds_read_b128 v[126:129], v190 offset:38912
	ds_read_b128 v[130:133], v190 offset:39936
	ds_read_b128 v[142:145], v190 offset:43008
	ds_read_b128 v[146:149], v190 offset:44032
	ds_read_b128 v[150:153], v190 offset:47104
	ds_read_b128 v[154:157], v190 offset:48128
	s_waitcnt lgkmcnt(14)
	v_mfma_f32_32x32x16_bf16 v[54:69], v[162:165], v[118:121], v[54:69]
	s_waitcnt lgkmcnt(13)
	v_mfma_f32_32x32x16_bf16 v[38:53], v[178:181], v[118:121], v[38:53]
	s_waitcnt lgkmcnt(11)
	v_mfma_f32_32x32x16_bf16 v[22:37], v[204:207], v[118:121], v[22:37]
	s_waitcnt lgkmcnt(9)
	v_mfma_f32_32x32x16_bf16 v[6:21], v[212:215], v[118:121], v[6:21]
	v_mfma_f32_32x32x16_bf16 v[54:69], v[166:169], v[122:125], v[54:69]
	v_mfma_f32_32x32x16_bf16 v[38:53], v[182:185], v[122:125], v[38:53]
	v_mfma_f32_32x32x16_bf16 v[22:37], v[208:211], v[122:125], v[22:37]
	s_waitcnt lgkmcnt(8)
	v_mfma_f32_32x32x16_bf16 v[6:21], v[216:219], v[122:125], v[6:21]
	ds_read_b128 v[158:161], v190 offset:49152
	ds_read_b128 v[162:165], v190 offset:50176
	ds_read_b128 v[166:169], v190 offset:53248
	ds_read_b128 v[170:173], v190 offset:54272
	ds_read_b128 v[174:177], v190 offset:55296
	ds_read_b128 v[178:181], v190 offset:56320
	s_waitcnt lgkmcnt(13)
	v_mfma_f32_32x32x16_bf16 v[54:69], v[110:113], v[102:105], v[54:69]
	s_waitcnt lgkmcnt(11)
	v_mfma_f32_32x32x16_bf16 v[38:53], v[126:129], v[102:105], v[38:53]
	s_waitcnt lgkmcnt(9)
	v_mfma_f32_32x32x16_bf16 v[22:37], v[142:145], v[102:105], v[22:37]
	s_waitcnt lgkmcnt(7)
	v_mfma_f32_32x32x16_bf16 v[6:21], v[150:153], v[102:105], v[6:21]
	v_mfma_f32_32x32x16_bf16 v[54:69], v[114:117], v[106:109], v[54:69]
	v_mfma_f32_32x32x16_bf16 v[38:53], v[130:133], v[106:109], v[38:53]
	v_mfma_f32_32x32x16_bf16 v[22:37], v[146:149], v[106:109], v[22:37]
	s_waitcnt lgkmcnt(6)
	v_mfma_f32_32x32x16_bf16 v[6:21], v[154:157], v[106:109], v[6:21]
	s_waitcnt lgkmcnt(5)
; __device__ __forceinline__ bf16 f2bf1(float f) { return (bf16)(cvtpk(f, 0.f) & 0xffffu); }
; #define MFMA32(a, b, c) __builtin_amdgcn_mfma_f32_32x32x16_bf16((a), (b), (c), 0, 0, 0)
; __device__ __forceinline__ void gdn_scan_unit(LAS unsigned char* lds, unsigned char* ws, int Tp, int sq, int h, int d, int half, int tid, int wave, int lane) {
;     ...
;             O[0] = MFMA32(A[0], Vf[0][0], O[0]); O[1] = MFMA32(A[1], Vf[0][0], O[1]); O[0] = MFMA32(A[2], Vf[0][1], O[0]); O[1] = MFMA32(A[3], Vf[0][1], O[1]);
;             O[1] = MFMA32(A[4], Vf[1][0], O[1]); O[1] = MFMA32(A[5], Vf[1][1], O[1]);
;     ...
;             { const int tau0 = 64 * n + 4 * hi;
; #pragma unroll
;               for (int i = 0; i < 2; ++i)
; #pragma unroll
;                 for (int r = 0; r < 16; ++r) { const int tau = tau0 + 32 * i + (r & 3) + 8 * (r >> 2); const int trow = d ? Tp - 1 - tau : tau;
;                     __builtin_amdgcn_raw_buffer_store_b16((short)f2bf1(O[i][r]), orsrc, (trow * 1024 + r32) * 2, 0, 0); } }
	v_mfma_f32_32x32x16_bf16 v[86:101], v[158:161], v[118:121], v[86:101]
	v_cndmask_b32_e32 v2, v137, v5, vcc
	v_lshl_or_b32 v2, v2, 11, v135
	s_add_i32 s4, s4, 1
	v_subrev_u32_e32 v137, 64, v137
	s_cmp_eq_u32 s72, s4
	s_waitcnt lgkmcnt(4)
	v_mfma_f32_32x32x16_bf16 v[86:101], v[162:165], v[122:125], v[86:101]
	s_waitcnt lgkmcnt(3)
	v_mfma_f32_32x32x16_bf16 v[70:85], v[166:169], v[118:121], v[70:85]
	s_nop 9
	v_cvt_pk_bf16_f32 v86, v86, s0
	buffer_store_short v86, v2, s[44:47], 0 offen
	v_xor_b32_e32 v86, 0x1ffffe, v5
	v_add_u32_e32 v2, 1, v5
	v_add_u32_e32 v86, s35, v86
	v_cndmask_b32_e32 v2, v86, v2, vcc
	v_cvt_pk_bf16_f32 v86, v87, s0
	v_lshl_or_b32 v2, v2, 11, v135
	buffer_store_short v86, v2, s[44:47], 0 offen
	v_xor_b32_e32 v86, 0x1ffffd, v5
	v_add_u32_e32 v2, 2, v5
	v_add_u32_e32 v86, s35, v86
	v_cndmask_b32_e32 v2, v86, v2, vcc
	v_cvt_pk_bf16_f32 v86, v88, s0
	v_lshl_or_b32 v2, v2, 11, v135
	buffer_store_short v86, v2, s[44:47], 0 offen
	v_xor_b32_e32 v86, 0x1ffffc, v5
	v_add_u32_e32 v2, 3, v5
	v_add_u32_e32 v86, s35, v86
	v_cndmask_b32_e32 v2, v86, v2, vcc
	v_cvt_pk_bf16_f32 v86, v89, s0
	v_lshl_or_b32 v2, v2, 11, v135
	buffer_store_short v86, v2, s[44:47], 0 offen
	v_xor_b32_e32 v86, 0x1ffff7, v5
	v_add_u32_e32 v2, 8, v5
	v_add_u32_e32 v86, s35, v86
	v_cndmask_b32_e32 v2, v86, v2, vcc
	v_cvt_pk_bf16_f32 v86, v90, s0
	v_lshl_or_b32 v2, v2, 11, v135
	buffer_store_short v86, v2, s[44:47], 0 offen
	v_xor_b32_e32 v86, 0x1ffff6, v5
	v_add_u32_e32 v2, 9, v5
	v_add_u32_e32 v86, s35, v86
	v_cndmask_b32_e32 v2, v86, v2, vcc
	v_cvt_pk_bf16_f32 v86, v91, s0
	v_lshl_or_b32 v2, v2, 11, v135
	buffer_store_short v86, v2, s[44:47], 0 offen
	v_xor_b32_e32 v86, 0x1ffff5, v5
	v_add_u32_e32 v2, 10, v5
	v_add_u32_e32 v86, s35, v86
	v_cndmask_b32_e32 v2, v86, v2, vcc
	v_cvt_pk_bf16_f32 v86, v92, s0
	v_lshl_or_b32 v2, v2, 11, v135
	buffer_store_short v86, v2, s[44:47], 0 offen
	v_xor_b32_e32 v86, 0x1ffff4, v5
	v_add_u32_e32 v2, 11, v5
	v_add_u32_e32 v86, s35, v86
	v_cndmask_b32_e32 v2, v86, v2, vcc
	v_cvt_pk_bf16_f32 v86, v93, s0
	v_lshl_or_b32 v2, v2, 11, v135
	buffer_store_short v86, v2, s[44:47], 0 offen
	v_xor_b32_e32 v86, 0x1fffef, v5
	v_add_u32_e32 v2, 16, v5
	v_add_u32_e32 v86, s35, v86
	v_cndmask_b32_e32 v2, v86, v2, vcc
	v_cvt_pk_bf16_f32 v86, v94, s0
	v_lshl_or_b32 v2, v2, 11, v135
	buffer_store_short v86, v2, s[44:47], 0 offen
	v_xor_b32_e32 v86, 0x1fffee, v5
	v_add_u32_e32 v2, 17, v5
	v_add_u32_e32 v86, s35, v86
	v_cndmask_b32_e32 v2, v86, v2, vcc
	v_cvt_pk_bf16_f32 v86, v95, s0
	v_lshl_or_b32 v2, v2, 11, v135
	buffer_store_short v86, v2, s[44:47], 0 offen
	v_xor_b32_e32 v86, 0x1fffed, v5
	v_add_u32_e32 v2, 18, v5
	v_add_u32_e32 v86, s35, v86
	v_cndmask_b32_e32 v2, v86, v2, vcc
	s_waitcnt lgkmcnt(2)
	v_mfma_f32_32x32x16_bf16 v[70:85], v[170:173], v[122:125], v[70:85]
	v_cvt_pk_bf16_f32 v86, v96, s0
	v_lshl_or_b32 v2, v2, 11, v135
	buffer_store_short v86, v2, s[44:47], 0 offen
	v_xor_b32_e32 v86, 0x1fffec, v5
	v_add_u32_e32 v2, 19, v5
	v_add_u32_e32 v86, s35, v86
	v_cndmask_b32_e32 v2, v86, v2, vcc
	v_cvt_pk_bf16_f32 v86, v97, s0
	v_lshl_or_b32 v2, v2, 11, v135
	buffer_store_short v86, v2, s[44:47], 0 offen
	v_xor_b32_e32 v86, 0x1fffe7, v5
	v_add_u32_e32 v2, 24, v5
	v_add_u32_e32 v86, s35, v86
	v_cndmask_b32_e32 v2, v86, v2, vcc
	s_waitcnt lgkmcnt(1)
	v_mfma_f32_32x32x16_bf16 v[70:85], v[174:177], v[102:105], v[70:85]
	v_cvt_pk_bf16_f32 v86, v98, s0
	v_lshl_or_b32 v2, v2, 11, v135
	buffer_store_short v86, v2, s[44:47], 0 offen
	v_xor_b32_e32 v86, 0x1fffe6, v5
	v_add_u32_e32 v2, 25, v5
	v_add_u32_e32 v86, s35, v86
	v_cndmask_b32_e32 v2, v86, v2, vcc
	v_cvt_pk_bf16_f32 v86, v99, s0
	v_lshl_or_b32 v2, v2, 11, v135
	buffer_store_short v86, v2, s[44:47], 0 offen
	v_xor_b32_e32 v86, 0x1fffe5, v5
	v_add_u32_e32 v2, 26, v5
	v_add_u32_e32 v86, s35, v86
	v_cndmask_b32_e32 v2, v86, v2, vcc
	s_waitcnt lgkmcnt(0)
; __device__ __forceinline__ bf16 f2bf1(float f) { return (bf16)(cvtpk(f, 0.f) & 0xffffu); }
; #define MFMA32(a, b, c) __builtin_amdgcn_mfma_f32_32x32x16_bf16((a), (b), (c), 0, 0, 0)
; #define SCAN_BAR() do { asm volatile("s_waitcnt lgkmcnt(0)" ::: "memory"); __builtin_amdgcn_s_barrier(); asm volatile("" ::: "memory"); } while (0)
; __device__ __forceinline__ void gdn_scan_unit(LAS unsigned char* lds, unsigned char* ws, int Tp, int sq, int h, int d, int half, int tid, int wave, int lane) {
;     ...
;             O[0] = MFMA32(A[0], Vf[0][0], O[0]); O[1] = MFMA32(A[1], Vf[0][0], O[1]); O[0] = MFMA32(A[2], Vf[0][1], O[0]); O[1] = MFMA32(A[3], Vf[0][1], O[1]);
;             O[1] = MFMA32(A[4], Vf[1][0], O[1]); O[1] = MFMA32(A[5], Vf[1][1], O[1]);
;     ...
;             { const int tau0 = 64 * n + 4 * hi;
; #pragma unroll
;               for (int i = 0; i < 2; ++i)
; #pragma unroll
;                 for (int r = 0; r < 16; ++r) { const int tau = tau0 + 32 * i + (r & 3) + 8 * (r >> 2); const int trow = d ? Tp - 1 - tau : tau;
;                     __builtin_amdgcn_raw_buffer_store_b16((short)f2bf1(O[i][r]), orsrc, (trow * 1024 + r32) * 2, 0, 0); } }
;             SCAN_BAR();
	v_mfma_f32_32x32x16_bf16 v[70:85], v[178:181], v[106:109], v[70:85]
	v_cvt_pk_bf16_f32 v86, v100, s0
	v_lshl_or_b32 v2, v2, 11, v135
	buffer_store_short v86, v2, s[44:47], 0 offen
	v_xor_b32_e32 v86, 0x1fffe4, v5
	v_add_u32_e32 v2, 27, v5
	v_add_u32_e32 v86, s35, v86
	v_cndmask_b32_e32 v2, v86, v2, vcc
	v_cvt_pk_bf16_f32 v86, v101, s0
	v_lshl_or_b32 v2, v2, 11, v135
	buffer_store_short v86, v2, s[44:47], 0 offen
	v_xor_b32_e32 v86, 0x1fffdf, v5
	v_add_u32_e32 v2, 32, v5
	v_add_u32_e32 v86, s35, v86
	v_cndmask_b32_e32 v2, v86, v2, vcc
	v_cvt_pk_bf16_f32 v70, v70, s0
	v_lshl_or_b32 v2, v2, 11, v135
	buffer_store_short v70, v2, s[44:47], 0 offen
	v_xor_b32_e32 v70, 0x1fffde, v5
	v_add_u32_e32 v2, 33, v5
	v_add_u32_e32 v70, s35, v70
	v_cndmask_b32_e32 v2, v70, v2, vcc
	v_cvt_pk_bf16_f32 v70, v71, s0
	v_lshl_or_b32 v2, v2, 11, v135
	buffer_store_short v70, v2, s[44:47], 0 offen
	v_xor_b32_e32 v70, 0x1fffdd, v5
	v_add_u32_e32 v2, 34, v5
	v_add_u32_e32 v70, s35, v70
	v_cndmask_b32_e32 v2, v70, v2, vcc
	v_cvt_pk_bf16_f32 v70, v72, s0
	v_lshl_or_b32 v2, v2, 11, v135
	buffer_store_short v70, v2, s[44:47], 0 offen
	v_xor_b32_e32 v70, 0x1fffdc, v5
	v_add_u32_e32 v2, 35, v5
	v_add_u32_e32 v70, s35, v70
	v_cndmask_b32_e32 v2, v70, v2, vcc
	v_cvt_pk_bf16_f32 v70, v73, s0
	v_lshl_or_b32 v2, v2, 11, v135
	buffer_store_short v70, v2, s[44:47], 0 offen
	v_xor_b32_e32 v70, 0x1fffd7, v5
	v_add_u32_e32 v2, 40, v5
	v_add_u32_e32 v70, s35, v70
	v_cndmask_b32_e32 v2, v70, v2, vcc
	v_cvt_pk_bf16_f32 v70, v74, s0
	v_lshl_or_b32 v2, v2, 11, v135
	buffer_store_short v70, v2, s[44:47], 0 offen
	v_xor_b32_e32 v70, 0x1fffd6, v5
	v_add_u32_e32 v2, 41, v5
	v_add_u32_e32 v70, s35, v70
	v_cndmask_b32_e32 v2, v70, v2, vcc
	v_cvt_pk_bf16_f32 v70, v75, s0
	v_lshl_or_b32 v2, v2, 11, v135
	buffer_store_short v70, v2, s[44:47], 0 offen
	v_xor_b32_e32 v70, 0x1fffd5, v5
	v_add_u32_e32 v2, 42, v5
	v_add_u32_e32 v70, s35, v70
	v_cndmask_b32_e32 v2, v70, v2, vcc
	v_cvt_pk_bf16_f32 v70, v76, s0
	v_lshl_or_b32 v2, v2, 11, v135
	buffer_store_short v70, v2, s[44:47], 0 offen
	v_xor_b32_e32 v70, 0x1fffd4, v5
	v_add_u32_e32 v2, 43, v5
	v_add_u32_e32 v70, s35, v70
	v_cndmask_b32_e32 v2, v70, v2, vcc
	v_cvt_pk_bf16_f32 v70, v77, s0
	v_lshl_or_b32 v2, v2, 11, v135
	buffer_store_short v70, v2, s[44:47], 0 offen
	v_xor_b32_e32 v70, 0x1fffcf, v5
	v_add_u32_e32 v2, 48, v5
	v_add_u32_e32 v70, s35, v70
	v_cndmask_b32_e32 v2, v70, v2, vcc
	v_cvt_pk_bf16_f32 v70, v78, s0
	v_lshl_or_b32 v2, v2, 11, v135
	buffer_store_short v70, v2, s[44:47], 0 offen
	v_xor_b32_e32 v70, 0x1fffce, v5
	v_add_u32_e32 v2, 49, v5
	v_add_u32_e32 v70, s35, v70
	v_cndmask_b32_e32 v2, v70, v2, vcc
	v_cvt_pk_bf16_f32 v70, v79, s0
	v_lshl_or_b32 v2, v2, 11, v135
	buffer_store_short v70, v2, s[44:47], 0 offen
	v_xor_b32_e32 v70, 0x1fffcd, v5
	v_add_u32_e32 v2, 50, v5
	v_add_u32_e32 v70, s35, v70
	v_cndmask_b32_e32 v2, v70, v2, vcc
	v_cvt_pk_bf16_f32 v70, v80, s0
	v_lshl_or_b32 v2, v2, 11, v135
	buffer_store_short v70, v2, s[44:47], 0 offen
	v_xor_b32_e32 v70, 0x1fffcc, v5
	v_add_u32_e32 v2, 51, v5
	v_add_u32_e32 v70, s35, v70
	v_cndmask_b32_e32 v2, v70, v2, vcc
	v_cvt_pk_bf16_f32 v70, v81, s0
	v_lshl_or_b32 v2, v2, 11, v135
	buffer_store_short v70, v2, s[44:47], 0 offen
	v_xor_b32_e32 v70, 0x1fffc7, v5
	v_add_u32_e32 v2, 56, v5
	v_add_u32_e32 v70, s35, v70
	v_cndmask_b32_e32 v2, v70, v2, vcc
	v_cvt_pk_bf16_f32 v70, v82, s0
	v_lshl_or_b32 v2, v2, 11, v135
	buffer_store_short v70, v2, s[44:47], 0 offen
	v_xor_b32_e32 v70, 0x1fffc6, v5
	v_add_u32_e32 v2, 57, v5
	v_add_u32_e32 v70, s35, v70
	v_cndmask_b32_e32 v2, v70, v2, vcc
	v_cvt_pk_bf16_f32 v70, v83, s0
	v_lshl_or_b32 v2, v2, 11, v135
	buffer_store_short v70, v2, s[44:47], 0 offen
	v_xor_b32_e32 v70, 0x1fffc5, v5
	v_add_u32_e32 v2, 58, v5
	v_add_u32_e32 v70, s35, v70
	v_cndmask_b32_e32 v2, v70, v2, vcc
	v_cvt_pk_bf16_f32 v70, v84, s0
	v_lshl_or_b32 v2, v2, 11, v135
	buffer_store_short v70, v2, s[44:47], 0 offen
	v_xor_b32_e32 v70, 0x1fffc4, v5
	v_add_u32_e32 v2, 59, v5
	v_add_u32_e32 v70, s35, v70
	v_cndmask_b32_e32 v2, v70, v2, vcc
	v_cvt_pk_bf16_f32 v70, v85, s0
	v_lshl_or_b32 v2, v2, 11, v135
	buffer_store_short v70, v2, s[44:47], 0 offen
	s_barrier
	v_add_u32_e32 v5, 64, v5
	s_cbranch_scc0 .LBB0_974
	s_mov_b64 s[4:5], 0
